# v14 with MFMA order variant none instead of acc-paired (ordering study)
# speedup vs baseline: 1.0155x; 1.0155x over previous
; #define PG8_STAGE(bufoff, gbase, voff) do { _Pragma("unroll") for (int _i = 0; _i < 2; ++_i) \
;         __builtin_amdgcn_global_load_lds((const unsigned*)((const char*)(gbase) + (voff)[_i]), (LAS unsigned*)(lds + (bufoff) + ldsw + _i * 8192), 16, 0, 0); } while (0)
; #define PG8_LDA(dst, b, h) do { _Pragma("unroll") for (int m = 0; m < 4; ++m) _Pragma("unroll") for (int k = 0; k < 2; ++k) dst[m][k] = *(const LAS bf16x8*)(lds + PG8_SA(b, h) + aoff + m * 2048 + k * 1024); } while (0)
; #define PG8_LDB(dst, b, h) do { _Pragma("unroll") for (int n = 0; n < 2; ++n) _Pragma("unroll") for (int k = 0; k < 2; ++k) dst[n][k] = *(const LAS bf16x8*)(lds + PG8_SB(b, h) + boff + n * 2048 + k * 1024); } while (0)
; #define PG8_MMA(ai, bj, At, Bt) do { __builtin_amdgcn_s_setprio(1); _Pragma("unroll") for (int m = 0; m < 4; ++m) _Pragma("unroll") for (int n = 0; n < 2; ++n) _Pragma("unroll") for (int k = 0; k < 2; ++k) \
;         acc[ai][bj][m][n] = __builtin_amdgcn_mfma_f32_16x16x32_bf16(Bt[n][k], At[m][k], acc[ai][bj][m][n], 0, 0, 0); __builtin_amdgcn_s_setprio(0); } while (0)
; #define PG8_WAIT_V(n) asm volatile("s_waitcnt vmcnt(" #n ")" ::: "memory")
; #define PG8_WAIT_L(n) asm volatile("s_waitcnt lgkmcnt(" #n ")" ::: "memory")
; template <class Epi, class Ptrs>
; __device__ __forceinline__ void gemm_phase(LAS unsigned char* lds, const int K, const StaticOrder& S, const Ptrs& P, const Epi& E) {
;     ...
;         for (int t = 0; t < nt; t += 2) {
;             const bool last = (t == nt - 2);
;             const char* a1 = cA + (size_t)(t + 1) * kstep;
;             const char* a2 = last ? nA : cA + (size_t)(t + 2) * kstep; const char* b2 = last ? nB : cB + (size_t)(t + 2) * kstep;
;             const char* a3 = a2 + kstep; const char* b3 = b2 + kstep;
;             PG8_LDB(B0, 0, 0); PG8_SCHED; PG8_LDA(At, 0, 0); PG8_STAGE(PG8_SA(1, 1), a1 + hstep, voffA);
;             PG8_WAIT_L(8); PG8_BAR; PG8_WAIT_L(0); PG8_MMA(0, 0, At, B0); PG8_BAR; PG8_SCHED;
;             PG8_LDB(B1, 0, 1); PG8_STAGE(PG8_SB(0, 0), b2, voffB);
;             PG8_BAR; PG8_WAIT_L(0); PG8_MMA(0, 1, At, B1); PG8_BAR;
;             PG8_LDA(At, 0, 1); PG8_STAGE(PG8_SA(0, 0), a2, voffA);
;             PG8_BAR; PG8_WAIT_L(0); PG8_MMA(1, 0, At, B0); PG8_BAR; PG8_SCHED;
;             PG8_STAGE(PG8_SB(0, 1), b2 + hstep, voffB);
;             PG8_WAIT_V(6); PG8_BAR; PG8_MMA(1, 1, At, B1); PG8_BAR;
.LBB0_126:
	s_add_u32 s6, s6, 0x40080
	s_addc_u32 s7, s7, 0
	s_add_u32 s20, s78, 0x100
	s_addc_u32 s25, s79, 0
	s_mov_b32 s63, -2
	v_add_u32_e32 v252, 0x18000, v131
	v_add_u32_e32 v253, 0x1c000, v131
	ds_read_b128 v[150:153], v205
	ds_read_b128 v[154:157], v205 offset:1024
	ds_read_b128 v[158:161], v205 offset:2048
	ds_read_b128 v[162:165], v205 offset:3072
	s_add_u32 s69, s6, 0xfffc0080
	s_addc_u32 s71, s7, -1
	s_cmp_eq_u32 s63, 12
	s_cselect_b32 s81, s1, s71
	s_cselect_b32 s80, s0, s69
	s_cselect_b32 s79, s73, s25
	s_cselect_b32 s78, s72, s20
	s_add_i32 m0, s67, 0xc000
	ds_read_b128 v[166:169], v206
	ds_read_b128 v[170:173], v206 offset:1024
	ds_read_b128 v[174:177], v206 offset:2048
	ds_read_b128 v[178:181], v206 offset:3072
	ds_read_b128 v[182:185], v206 offset:4096
	ds_read_b128 v[186:189], v206 offset:5120
	ds_read_b128 v[190:193], v206 offset:6144
	ds_read_b128 v[194:197], v206 offset:7168
	global_load_lds_dwordx4 v142, s[6:7]
	s_add_i32 m0, s67, 0xe000
	s_nop 0
	global_load_lds_dwordx4 v144, s[6:7]
	s_waitcnt lgkmcnt(8)
	s_barrier
	s_waitcnt lgkmcnt(0)
	v_mfma_f32_16x16x32_bf16 v[120:123], v[150:153], v[166:169], 0
	v_mfma_f32_16x16x32_bf16 v[116:119], v[158:161], v[166:169], 0
	v_mfma_f32_16x16x32_bf16 v[104:107], v[150:153], v[174:177], 0
	v_mfma_f32_16x16x32_bf16 v[100:103], v[158:161], v[174:177], 0
	v_mfma_f32_16x16x32_bf16 v[88:91], v[150:153], v[182:185], 0
	v_mfma_f32_16x16x32_bf16 v[84:87], v[158:161], v[182:185], 0
	v_mfma_f32_16x16x32_bf16 v[72:75], v[150:153], v[190:193], 0
	v_mfma_f32_16x16x32_bf16 v[68:71], v[158:161], v[190:193], 0
	v_mfma_f32_16x16x32_bf16 v[120:123], v[154:157], v[170:173], v[120:123]
	v_mfma_f32_16x16x32_bf16 v[116:119], v[162:165], v[170:173], v[116:119]
	v_mfma_f32_16x16x32_bf16 v[104:107], v[154:157], v[178:181], v[104:107]
	v_mfma_f32_16x16x32_bf16 v[100:103], v[162:165], v[178:181], v[100:103]
	v_mfma_f32_16x16x32_bf16 v[88:91], v[154:157], v[186:189], v[88:91]
	v_mfma_f32_16x16x32_bf16 v[84:87], v[162:165], v[186:189], v[84:87]
	v_mfma_f32_16x16x32_bf16 v[72:75], v[154:157], v[194:197], v[72:75]
	v_mfma_f32_16x16x32_bf16 v[68:71], v[162:165], v[194:197], v[68:71]
	s_barrier
	s_add_i32 s69, s91, s65
	s_add_u32 s100, s78, 0x80
	s_addc_u32 s101, s79, 0
	s_mov_b32 m0, s69
	ds_read_b128 v[198:201], v207
	ds_read_b128 v[210:213], v207 offset:1024
	ds_read_b128 v[214:217], v207 offset:2048
	ds_read_b128 v[218:221], v207 offset:3072
	global_load_lds_dwordx4 v134, s[78:79]
	s_add_i32 m0, s69, 0x2000
	s_nop 0
	global_load_lds_dwordx4 v138, s[78:79]
	s_barrier
	s_waitcnt lgkmcnt(0)
	v_mfma_f32_16x16x32_bf16 v[124:127], v[198:201], v[166:169], 0
	v_mfma_f32_16x16x32_bf16 v[112:115], v[214:217], v[166:169], 0
	v_mfma_f32_16x16x32_bf16 v[108:111], v[198:201], v[174:177], 0
	v_mfma_f32_16x16x32_bf16 v[96:99], v[214:217], v[174:177], 0
	v_mfma_f32_16x16x32_bf16 v[92:95], v[198:201], v[182:185], 0
	v_mfma_f32_16x16x32_bf16 v[80:83], v[214:217], v[182:185], 0
	v_mfma_f32_16x16x32_bf16 v[76:79], v[198:201], v[190:193], 0
	v_mfma_f32_16x16x32_bf16 v[64:67], v[214:217], v[190:193], 0
	v_mfma_f32_16x16x32_bf16 v[124:127], v[210:213], v[170:173], v[124:127]
	v_mfma_f32_16x16x32_bf16 v[112:115], v[218:221], v[170:173], v[112:115]
	v_mfma_f32_16x16x32_bf16 v[108:111], v[210:213], v[178:181], v[108:111]
	v_mfma_f32_16x16x32_bf16 v[96:99], v[218:221], v[178:181], v[96:99]
	v_mfma_f32_16x16x32_bf16 v[92:95], v[210:213], v[186:189], v[92:95]
	v_mfma_f32_16x16x32_bf16 v[80:83], v[218:221], v[186:189], v[80:83]
	v_mfma_f32_16x16x32_bf16 v[76:79], v[210:213], v[194:197], v[76:79]
	v_mfma_f32_16x16x32_bf16 v[64:67], v[218:221], v[194:197], v[64:67]
	s_barrier
	s_mov_b32 m0, s67
	ds_read_b128 v[166:169], v206 offset:16384
	ds_read_b128 v[170:173], v206 offset:17408
	ds_read_b128 v[174:177], v206 offset:18432
	ds_read_b128 v[178:181], v206 offset:19456
	ds_read_b128 v[182:185], v206 offset:20480
	ds_read_b128 v[186:189], v206 offset:21504
	ds_read_b128 v[190:193], v206 offset:22528
	ds_read_b128 v[194:197], v206 offset:23552
	global_load_lds_dwordx4 v132, s[80:81]
	s_mov_b32 m0, s75
	s_nop 0
	global_load_lds_dwordx4 v136, s[80:81]
	s_barrier
	s_waitcnt lgkmcnt(0)
	v_mfma_f32_16x16x32_bf16 v[56:59], v[150:153], v[166:169], 0
	v_mfma_f32_16x16x32_bf16 v[52:55], v[158:161], v[166:169], 0
	v_mfma_f32_16x16x32_bf16 v[40:43], v[150:153], v[174:177], 0
	v_mfma_f32_16x16x32_bf16 v[36:39], v[158:161], v[174:177], 0
	v_mfma_f32_16x16x32_bf16 v[24:27], v[150:153], v[182:185], 0
	v_mfma_f32_16x16x32_bf16 v[20:23], v[158:161], v[182:185], 0
	v_mfma_f32_16x16x32_bf16 v[8:11], v[150:153], v[190:193], 0
	v_mfma_f32_16x16x32_bf16 v[4:7], v[158:161], v[190:193], 0
	v_mfma_f32_16x16x32_bf16 v[56:59], v[154:157], v[170:173], v[56:59]
	v_mfma_f32_16x16x32_bf16 v[52:55], v[162:165], v[170:173], v[52:55]
	v_mfma_f32_16x16x32_bf16 v[40:43], v[154:157], v[178:181], v[40:43]
	v_mfma_f32_16x16x32_bf16 v[36:39], v[162:165], v[178:181], v[36:39]
	v_mfma_f32_16x16x32_bf16 v[24:27], v[154:157], v[186:189], v[24:27]
	v_mfma_f32_16x16x32_bf16 v[20:23], v[162:165], v[186:189], v[20:23]
	v_mfma_f32_16x16x32_bf16 v[8:11], v[154:157], v[194:197], v[8:11]
	v_mfma_f32_16x16x32_bf16 v[4:7], v[162:165], v[194:197], v[4:7]
	s_barrier
	s_add_u32 s82, s78, 0x40000
	s_addc_u32 s83, s79, 0
	s_add_i32 s69, s92, s65
	s_mov_b32 m0, s69
	s_nop 0
	global_load_lds_dwordx4 v134, s[82:83]
	s_add_i32 m0, s69, 0x2000
	s_nop 0
	global_load_lds_dwordx4 v138, s[82:83]
	s_waitcnt vmcnt(6)
	s_barrier
; #define PG8_STAGE(bufoff, gbase, voff) do { _Pragma("unroll") for (int _i = 0; _i < 2; ++_i) \
;         __builtin_amdgcn_global_load_lds((const unsigned*)((const char*)(gbase) + (voff)[_i]), (LAS unsigned*)(lds + (bufoff) + ldsw + _i * 8192), 16, 0, 0); } while (0)
; #define PG8_LDA(dst, b, h) do { _Pragma("unroll") for (int m = 0; m < 4; ++m) _Pragma("unroll") for (int k = 0; k < 2; ++k) dst[m][k] = *(const LAS bf16x8*)(lds + PG8_SA(b, h) + aoff + m * 2048 + k * 1024); } while (0)
; #define PG8_LDB(dst, b, h) do { _Pragma("unroll") for (int n = 0; n < 2; ++n) _Pragma("unroll") for (int k = 0; k < 2; ++k) dst[n][k] = *(const LAS bf16x8*)(lds + PG8_SB(b, h) + boff + n * 2048 + k * 1024); } while (0)
; #define PG8_MMA(ai, bj, At, Bt) do { __builtin_amdgcn_s_setprio(1); _Pragma("unroll") for (int m = 0; m < 4; ++m) _Pragma("unroll") for (int n = 0; n < 2; ++n) _Pragma("unroll") for (int k = 0; k < 2; ++k) \
;         acc[ai][bj][m][n] = __builtin_amdgcn_mfma_f32_16x16x32_bf16(Bt[n][k], At[m][k], acc[ai][bj][m][n], 0, 0, 0); __builtin_amdgcn_s_setprio(0); } while (0)
; #define PG8_WAIT_V(n) asm volatile("s_waitcnt vmcnt(" #n ")" ::: "memory")
; #define PG8_WAIT_L(n) asm volatile("s_waitcnt lgkmcnt(" #n ")" ::: "memory")
; #define PG8_BAR __builtin_amdgcn_s_barrier()
; #define PG8_SCHED __builtin_amdgcn_sched_barrier(0)
; template <class Epi, class Ptrs>
; __device__ __forceinline__ void gemm_phase(LAS unsigned char* lds, const int K, const StaticOrder& S, const Ptrs& P, const Epi& E) {
;     ...
;             PG8_WAIT_V(6); PG8_BAR; PG8_MMA(1, 1, At, B1); PG8_BAR;
;             PG8_LDB(B0, 1, 0); PG8_SCHED; PG8_LDA(At, 1, 0); PG8_STAGE(PG8_SA(0, 1), a2 + hstep, voffA);
;             PG8_WAIT_L(8); PG8_BAR; PG8_WAIT_L(0); PG8_MMA(0, 0, At, B0); PG8_BAR; PG8_SCHED;
;             PG8_LDB(B1, 1, 1); PG8_STAGE(PG8_SB(1, 0), b3, voffB);
;             PG8_BAR; PG8_WAIT_L(0); PG8_MMA(0, 1, At, B1); PG8_BAR;
;             PG8_LDA(At, 1, 1); PG8_STAGE(PG8_SA(1, 0), a3, voffA);
;             PG8_BAR; PG8_WAIT_L(0); PG8_MMA(1, 0, At, B0); PG8_BAR; PG8_SCHED;
	v_mfma_f32_16x16x32_bf16 v[60:63], v[198:201], v[166:169], 0
	v_mfma_f32_16x16x32_bf16 v[48:51], v[214:217], v[166:169], 0
	v_mfma_f32_16x16x32_bf16 v[44:47], v[198:201], v[174:177], 0
	v_mfma_f32_16x16x32_bf16 v[32:35], v[214:217], v[174:177], 0
	v_mfma_f32_16x16x32_bf16 v[28:31], v[198:201], v[182:185], 0
	v_mfma_f32_16x16x32_bf16 v[16:19], v[214:217], v[182:185], 0
	v_mfma_f32_16x16x32_bf16 v[12:15], v[198:201], v[190:193], 0
	v_mfma_f32_16x16x32_bf16 v[0:3], v[214:217], v[190:193], 0
	v_mfma_f32_16x16x32_bf16 v[60:63], v[210:213], v[170:173], v[60:63]
	v_mfma_f32_16x16x32_bf16 v[48:51], v[218:221], v[170:173], v[48:51]
	v_mfma_f32_16x16x32_bf16 v[44:47], v[210:213], v[178:181], v[44:47]
	v_mfma_f32_16x16x32_bf16 v[32:35], v[218:221], v[178:181], v[32:35]
	v_mfma_f32_16x16x32_bf16 v[28:31], v[210:213], v[186:189], v[28:31]
	v_mfma_f32_16x16x32_bf16 v[16:19], v[218:221], v[186:189], v[16:19]
	v_mfma_f32_16x16x32_bf16 v[12:15], v[210:213], v[194:197], v[12:15]
	v_mfma_f32_16x16x32_bf16 v[0:3], v[218:221], v[194:197], v[0:3]
	s_barrier
	s_add_i32 s69, 0, 0x18000
	ds_read_b128 v[150:153], v252
	ds_read_b128 v[154:157], v252 offset:1024
	ds_read_b128 v[158:161], v252 offset:2048
	ds_read_b128 v[162:165], v252 offset:3072
	s_add_u32 s80, s80, 0x40000
	s_addc_u32 s81, s81, 0
	s_mov_b32 m0, s77
	ds_read_b128 v[166:169], v206 offset:32768
	ds_read_b128 v[170:173], v206 offset:33792
	ds_read_b128 v[174:177], v206 offset:34816
	ds_read_b128 v[178:181], v206 offset:35840
	ds_read_b128 v[182:185], v206 offset:36864
	ds_read_b128 v[186:189], v206 offset:37888
	ds_read_b128 v[190:193], v206 offset:38912
	ds_read_b128 v[194:197], v206 offset:39936
	global_load_lds_dwordx4 v132, s[80:81]
	s_mov_b32 m0, s85
	s_nop 0
	global_load_lds_dwordx4 v136, s[80:81]
	s_waitcnt lgkmcnt(8)
	s_barrier
	s_waitcnt lgkmcnt(0)
	v_mfma_f32_16x16x32_bf16 v[120:123], v[150:153], v[166:169], v[120:123]
	v_mfma_f32_16x16x32_bf16 v[116:119], v[158:161], v[166:169], v[116:119]
	v_mfma_f32_16x16x32_bf16 v[104:107], v[150:153], v[174:177], v[104:107]
	v_mfma_f32_16x16x32_bf16 v[100:103], v[158:161], v[174:177], v[100:103]
	v_mfma_f32_16x16x32_bf16 v[88:91], v[150:153], v[182:185], v[88:91]
	v_mfma_f32_16x16x32_bf16 v[84:87], v[158:161], v[182:185], v[84:87]
	v_mfma_f32_16x16x32_bf16 v[72:75], v[150:153], v[190:193], v[72:75]
	v_mfma_f32_16x16x32_bf16 v[68:71], v[158:161], v[190:193], v[68:71]
	v_mfma_f32_16x16x32_bf16 v[120:123], v[154:157], v[170:173], v[120:123]
	v_mfma_f32_16x16x32_bf16 v[116:119], v[162:165], v[170:173], v[116:119]
	v_mfma_f32_16x16x32_bf16 v[104:107], v[154:157], v[178:181], v[104:107]
	v_mfma_f32_16x16x32_bf16 v[100:103], v[162:165], v[178:181], v[100:103]
	v_mfma_f32_16x16x32_bf16 v[88:91], v[154:157], v[186:189], v[88:91]
	v_mfma_f32_16x16x32_bf16 v[84:87], v[162:165], v[186:189], v[84:87]
	v_mfma_f32_16x16x32_bf16 v[72:75], v[154:157], v[194:197], v[72:75]
	v_mfma_f32_16x16x32_bf16 v[68:71], v[162:165], v[194:197], v[68:71]
	s_barrier
	s_add_i32 s71, 0, 0x1c000
	s_add_i32 s69, s69, s65
	s_mov_b32 m0, s69
	ds_read_b128 v[198:201], v253
	ds_read_b128 v[210:213], v253 offset:1024
	ds_read_b128 v[214:217], v253 offset:2048
	ds_read_b128 v[218:221], v253 offset:3072
	global_load_lds_dwordx4 v134, s[100:101]
	s_add_i32 m0, s69, 0x2000
	s_nop 0
	global_load_lds_dwordx4 v138, s[100:101]
	s_barrier
	s_waitcnt lgkmcnt(0)
	v_mfma_f32_16x16x32_bf16 v[124:127], v[198:201], v[166:169], v[124:127]
	v_mfma_f32_16x16x32_bf16 v[112:115], v[214:217], v[166:169], v[112:115]
	v_mfma_f32_16x16x32_bf16 v[108:111], v[198:201], v[174:177], v[108:111]
	v_mfma_f32_16x16x32_bf16 v[96:99], v[214:217], v[174:177], v[96:99]
	v_mfma_f32_16x16x32_bf16 v[92:95], v[198:201], v[182:185], v[92:95]
	v_mfma_f32_16x16x32_bf16 v[80:83], v[214:217], v[182:185], v[80:83]
	v_mfma_f32_16x16x32_bf16 v[76:79], v[198:201], v[190:193], v[76:79]
	v_mfma_f32_16x16x32_bf16 v[64:67], v[214:217], v[190:193], v[64:67]
	v_mfma_f32_16x16x32_bf16 v[124:127], v[210:213], v[170:173], v[124:127]
	v_mfma_f32_16x16x32_bf16 v[112:115], v[218:221], v[170:173], v[112:115]
	v_mfma_f32_16x16x32_bf16 v[108:111], v[210:213], v[178:181], v[108:111]
	v_mfma_f32_16x16x32_bf16 v[96:99], v[218:221], v[178:181], v[96:99]
	v_mfma_f32_16x16x32_bf16 v[92:95], v[210:213], v[186:189], v[92:95]
	v_mfma_f32_16x16x32_bf16 v[80:83], v[218:221], v[186:189], v[80:83]
	v_mfma_f32_16x16x32_bf16 v[76:79], v[210:213], v[194:197], v[76:79]
	v_mfma_f32_16x16x32_bf16 v[64:67], v[218:221], v[194:197], v[64:67]
	s_barrier
	s_mov_b32 m0, s89
	s_add_u32 s100, s80, 0xfffc0080
	s_addc_u32 s101, s81, -1
	ds_read_b128 v[166:169], v206 offset:49152
	ds_read_b128 v[170:173], v206 offset:50176
	ds_read_b128 v[174:177], v206 offset:51200
	ds_read_b128 v[178:181], v206 offset:52224
	ds_read_b128 v[182:185], v206 offset:53248
	ds_read_b128 v[186:189], v206 offset:54272
	ds_read_b128 v[190:193], v206 offset:55296
	ds_read_b128 v[194:197], v206 offset:56320
	global_load_lds_dwordx4 v132, s[100:101]
	s_mov_b32 m0, s90
	s_nop 0
	global_load_lds_dwordx4 v136, s[100:101]
	s_barrier
	s_waitcnt lgkmcnt(0)
	v_mfma_f32_16x16x32_bf16 v[56:59], v[150:153], v[166:169], v[56:59]
	v_mfma_f32_16x16x32_bf16 v[52:55], v[158:161], v[166:169], v[52:55]
	v_mfma_f32_16x16x32_bf16 v[40:43], v[150:153], v[174:177], v[40:43]
	v_mfma_f32_16x16x32_bf16 v[36:39], v[158:161], v[174:177], v[36:39]
	v_mfma_f32_16x16x32_bf16 v[24:27], v[150:153], v[182:185], v[24:27]
	v_mfma_f32_16x16x32_bf16 v[20:23], v[158:161], v[182:185], v[20:23]
	v_mfma_f32_16x16x32_bf16 v[8:11], v[150:153], v[190:193], v[8:11]
	v_mfma_f32_16x16x32_bf16 v[4:7], v[158:161], v[190:193], v[4:7]
	v_mfma_f32_16x16x32_bf16 v[56:59], v[154:157], v[170:173], v[56:59]
	v_mfma_f32_16x16x32_bf16 v[52:55], v[162:165], v[170:173], v[52:55]
	v_mfma_f32_16x16x32_bf16 v[40:43], v[154:157], v[178:181], v[40:43]
	v_mfma_f32_16x16x32_bf16 v[36:39], v[162:165], v[178:181], v[36:39]
	v_mfma_f32_16x16x32_bf16 v[24:27], v[154:157], v[186:189], v[24:27]
	v_mfma_f32_16x16x32_bf16 v[20:23], v[162:165], v[186:189], v[20:23]
	v_mfma_f32_16x16x32_bf16 v[8:11], v[154:157], v[194:197], v[8:11]
	v_mfma_f32_16x16x32_bf16 v[4:7], v[162:165], v[194:197], v[4:7]
	s_barrier
; #define PG8_STAGE(bufoff, gbase, voff) do { _Pragma("unroll") for (int _i = 0; _i < 2; ++_i) \
;         __builtin_amdgcn_global_load_lds((const unsigned*)((const char*)(gbase) + (voff)[_i]), (LAS unsigned*)(lds + (bufoff) + ldsw + _i * 8192), 16, 0, 0); } while (0)
; #define PG8_LDA(dst, b, h) do { _Pragma("unroll") for (int m = 0; m < 4; ++m) _Pragma("unroll") for (int k = 0; k < 2; ++k) dst[m][k] = *(const LAS bf16x8*)(lds + PG8_SA(b, h) + aoff + m * 2048 + k * 1024); } while (0)
; #define PG8_LDB(dst, b, h) do { _Pragma("unroll") for (int n = 0; n < 2; ++n) _Pragma("unroll") for (int k = 0; k < 2; ++k) dst[n][k] = *(const LAS bf16x8*)(lds + PG8_SB(b, h) + boff + n * 2048 + k * 1024); } while (0)
; #define PG8_WAIT_V(n) asm volatile("s_waitcnt vmcnt(" #n ")" ::: "memory")
; #define PG8_WAIT_L(n) asm volatile("s_waitcnt lgkmcnt(" #n ")" ::: "memory")
; #define PG8_BAR __builtin_amdgcn_s_barrier()
; #define PG8_SCHED __builtin_amdgcn_sched_barrier(0)
; template <class Epi, class Ptrs>
; __device__ __forceinline__ void gemm_phase(LAS unsigned char* lds, const int K, const StaticOrder& S, const Ptrs& P, const Epi& E) {
;     ...
;             PG8_LDB(B0, 0, 0); PG8_SCHED; PG8_LDA(At, 0, 0); PG8_STAGE(PG8_SA(1, 1), a1 + hstep, voffA);
;             PG8_WAIT_L(8); PG8_BAR; PG8_WAIT_L(0); PG8_MMA(0, 0, At, B0); PG8_BAR; PG8_SCHED;
;             PG8_LDB(B1, 0, 1); PG8_STAGE(PG8_SB(0, 0), b2, voffB);
;             PG8_BAR; PG8_WAIT_L(0); PG8_MMA(0, 1, At, B1); PG8_BAR;
;             PG8_LDA(At, 0, 1); PG8_STAGE(PG8_SA(0, 0), a2, voffA);
;             PG8_BAR; PG8_WAIT_L(0); PG8_MMA(1, 0, At, B0); PG8_BAR; PG8_SCHED;
;             PG8_STAGE(PG8_SB(0, 1), b2 + hstep, voffB);
;             PG8_WAIT_V(6); PG8_BAR; PG8_MMA(1, 1, At, B1); PG8_BAR;
;             PG8_LDB(B0, 1, 0); PG8_SCHED; PG8_LDA(At, 1, 0); PG8_STAGE(PG8_SA(0, 1), a2 + hstep, voffA);
;             PG8_WAIT_L(8); PG8_BAR; PG8_WAIT_L(0); PG8_MMA(0, 0, At, B0); PG8_BAR; PG8_SCHED;
;             PG8_LDB(B1, 1, 1); PG8_STAGE(PG8_SB(1, 0), b3, voffB);
;             PG8_BAR; PG8_WAIT_L(0); PG8_MMA(0, 1, At, B1); PG8_BAR;
;             PG8_LDA(At, 1, 1); PG8_STAGE(PG8_SA(1, 0), a3, voffA);
;             PG8_BAR; PG8_WAIT_L(0); PG8_MMA(1, 0, At, B0); PG8_BAR; PG8_SCHED;
;             PG8_STAGE(PG8_SB(1, 1), b3 + hstep, voffB);
;             PG8_WAIT_V(6); PG8_BAR; PG8_MMA(1, 1, At, B1); PG8_BAR;
	s_add_u32 s78, s78, 0x40080
	s_addc_u32 s79, s79, 0
	s_add_i32 s69, s71, s65
	s_mov_b32 m0, s69
	s_nop 0
	global_load_lds_dwordx4 v134, s[78:79]
	s_add_i32 m0, s69, 0x2000
	s_nop 0
	global_load_lds_dwordx4 v138, s[78:79]
	s_waitcnt vmcnt(6)
	s_barrier
	v_mfma_f32_16x16x32_bf16 v[60:63], v[198:201], v[166:169], v[60:63]
	v_mfma_f32_16x16x32_bf16 v[48:51], v[214:217], v[166:169], v[48:51]
	v_mfma_f32_16x16x32_bf16 v[44:47], v[198:201], v[174:177], v[44:47]
	v_mfma_f32_16x16x32_bf16 v[32:35], v[214:217], v[174:177], v[32:35]
	v_mfma_f32_16x16x32_bf16 v[28:31], v[198:201], v[182:185], v[28:31]
	v_mfma_f32_16x16x32_bf16 v[16:19], v[214:217], v[182:185], v[16:19]
	v_mfma_f32_16x16x32_bf16 v[12:15], v[198:201], v[190:193], v[12:15]
	v_mfma_f32_16x16x32_bf16 v[0:3], v[214:217], v[190:193], v[0:3]
	v_mfma_f32_16x16x32_bf16 v[60:63], v[210:213], v[170:173], v[60:63]
	v_mfma_f32_16x16x32_bf16 v[48:51], v[218:221], v[170:173], v[48:51]
	v_mfma_f32_16x16x32_bf16 v[44:47], v[210:213], v[178:181], v[44:47]
	v_mfma_f32_16x16x32_bf16 v[32:35], v[218:221], v[178:181], v[32:35]
	v_mfma_f32_16x16x32_bf16 v[28:31], v[210:213], v[186:189], v[28:31]
	v_mfma_f32_16x16x32_bf16 v[16:19], v[218:221], v[186:189], v[16:19]
	v_mfma_f32_16x16x32_bf16 v[12:15], v[210:213], v[194:197], v[12:15]
	v_mfma_f32_16x16x32_bf16 v[0:3], v[218:221], v[194:197], v[0:3]
	s_barrier
	s_add_i32 s63, s63, 2
	s_add_u32 s6, s6, 0x100
	s_addc_u32 s7, s7, 0
	s_add_u32 s20, s20, 0x100
	s_addc_u32 s25, s25, 0
	s_cmp_gt_u32 s63, 13
.LBB0_127:
	ds_read_b128 v[150:153], v205
	ds_read_b128 v[154:157], v205 offset:1024
	ds_read_b128 v[158:161], v205 offset:2048
	ds_read_b128 v[162:165], v205 offset:3072
	s_add_u32 s69, s6, 0xfffc0080
	s_addc_u32 s71, s7, -1
	s_cmp_eq_u32 s63, 12
	s_cselect_b32 s81, s1, s71
	s_cselect_b32 s80, s0, s69
	s_cselect_b32 s79, s73, s25
	s_cselect_b32 s78, s72, s20
	s_add_i32 m0, s67, 0xc000
	ds_read_b128 v[166:169], v206
	ds_read_b128 v[170:173], v206 offset:1024
	ds_read_b128 v[174:177], v206 offset:2048
	ds_read_b128 v[178:181], v206 offset:3072
	ds_read_b128 v[182:185], v206 offset:4096
	ds_read_b128 v[186:189], v206 offset:5120
	ds_read_b128 v[190:193], v206 offset:6144
	ds_read_b128 v[194:197], v206 offset:7168
	global_load_lds_dwordx4 v142, s[6:7]
	s_add_i32 m0, s67, 0xe000
	s_nop 0
	global_load_lds_dwordx4 v144, s[6:7]
	s_waitcnt lgkmcnt(8)
	s_barrier
	s_waitcnt lgkmcnt(0)
	v_mfma_f32_16x16x32_bf16 v[120:123], v[150:153], v[166:169], v[120:123]
	v_mfma_f32_16x16x32_bf16 v[116:119], v[158:161], v[166:169], v[116:119]
	v_mfma_f32_16x16x32_bf16 v[104:107], v[150:153], v[174:177], v[104:107]
	v_mfma_f32_16x16x32_bf16 v[100:103], v[158:161], v[174:177], v[100:103]
	v_mfma_f32_16x16x32_bf16 v[88:91], v[150:153], v[182:185], v[88:91]
	v_mfma_f32_16x16x32_bf16 v[84:87], v[158:161], v[182:185], v[84:87]
	v_mfma_f32_16x16x32_bf16 v[72:75], v[150:153], v[190:193], v[72:75]
	v_mfma_f32_16x16x32_bf16 v[68:71], v[158:161], v[190:193], v[68:71]
	v_mfma_f32_16x16x32_bf16 v[120:123], v[154:157], v[170:173], v[120:123]
	v_mfma_f32_16x16x32_bf16 v[116:119], v[162:165], v[170:173], v[116:119]
	v_mfma_f32_16x16x32_bf16 v[104:107], v[154:157], v[178:181], v[104:107]
	v_mfma_f32_16x16x32_bf16 v[100:103], v[162:165], v[178:181], v[100:103]
	v_mfma_f32_16x16x32_bf16 v[88:91], v[154:157], v[186:189], v[88:91]
	v_mfma_f32_16x16x32_bf16 v[84:87], v[162:165], v[186:189], v[84:87]
	v_mfma_f32_16x16x32_bf16 v[72:75], v[154:157], v[194:197], v[72:75]
	v_mfma_f32_16x16x32_bf16 v[68:71], v[162:165], v[194:197], v[68:71]
	s_barrier
	s_add_i32 s69, s91, s65
	s_add_u32 s100, s78, 0x80
	s_addc_u32 s101, s79, 0
	s_mov_b32 m0, s69
	ds_read_b128 v[198:201], v207
	ds_read_b128 v[210:213], v207 offset:1024
	ds_read_b128 v[214:217], v207 offset:2048
	ds_read_b128 v[218:221], v207 offset:3072
	global_load_lds_dwordx4 v134, s[78:79]
	s_add_i32 m0, s69, 0x2000
	s_nop 0
	global_load_lds_dwordx4 v138, s[78:79]
	s_barrier
	s_waitcnt lgkmcnt(0)
	v_mfma_f32_16x16x32_bf16 v[124:127], v[198:201], v[166:169], v[124:127]
	v_mfma_f32_16x16x32_bf16 v[112:115], v[214:217], v[166:169], v[112:115]
	v_mfma_f32_16x16x32_bf16 v[108:111], v[198:201], v[174:177], v[108:111]
	v_mfma_f32_16x16x32_bf16 v[96:99], v[214:217], v[174:177], v[96:99]
	v_mfma_f32_16x16x32_bf16 v[92:95], v[198:201], v[182:185], v[92:95]
	v_mfma_f32_16x16x32_bf16 v[80:83], v[214:217], v[182:185], v[80:83]
	v_mfma_f32_16x16x32_bf16 v[76:79], v[198:201], v[190:193], v[76:79]
	v_mfma_f32_16x16x32_bf16 v[64:67], v[214:217], v[190:193], v[64:67]
	v_mfma_f32_16x16x32_bf16 v[124:127], v[210:213], v[170:173], v[124:127]
	v_mfma_f32_16x16x32_bf16 v[112:115], v[218:221], v[170:173], v[112:115]
	v_mfma_f32_16x16x32_bf16 v[108:111], v[210:213], v[178:181], v[108:111]
	v_mfma_f32_16x16x32_bf16 v[96:99], v[218:221], v[178:181], v[96:99]
	v_mfma_f32_16x16x32_bf16 v[92:95], v[210:213], v[186:189], v[92:95]
	v_mfma_f32_16x16x32_bf16 v[80:83], v[218:221], v[186:189], v[80:83]
	v_mfma_f32_16x16x32_bf16 v[76:79], v[210:213], v[194:197], v[76:79]
	v_mfma_f32_16x16x32_bf16 v[64:67], v[218:221], v[194:197], v[64:67]
	s_barrier
	s_mov_b32 m0, s67
	ds_read_b128 v[166:169], v206 offset:16384
	ds_read_b128 v[170:173], v206 offset:17408
	ds_read_b128 v[174:177], v206 offset:18432
	ds_read_b128 v[178:181], v206 offset:19456
	ds_read_b128 v[182:185], v206 offset:20480
	ds_read_b128 v[186:189], v206 offset:21504
	ds_read_b128 v[190:193], v206 offset:22528
	ds_read_b128 v[194:197], v206 offset:23552
	global_load_lds_dwordx4 v132, s[80:81]
	s_mov_b32 m0, s75
	s_nop 0
	global_load_lds_dwordx4 v136, s[80:81]
	s_barrier
; #define PG8_STAGE(bufoff, gbase, voff) do { _Pragma("unroll") for (int _i = 0; _i < 2; ++_i) \
;         __builtin_amdgcn_global_load_lds((const unsigned*)((const char*)(gbase) + (voff)[_i]), (LAS unsigned*)(lds + (bufoff) + ldsw + _i * 8192), 16, 0, 0); } while (0)
; #define PG8_LDA(dst, b, h) do { _Pragma("unroll") for (int m = 0; m < 4; ++m) _Pragma("unroll") for (int k = 0; k < 2; ++k) dst[m][k] = *(const LAS bf16x8*)(lds + PG8_SA(b, h) + aoff + m * 2048 + k * 1024); } while (0)
; #define PG8_LDB(dst, b, h) do { _Pragma("unroll") for (int n = 0; n < 2; ++n) _Pragma("unroll") for (int k = 0; k < 2; ++k) dst[n][k] = *(const LAS bf16x8*)(lds + PG8_SB(b, h) + boff + n * 2048 + k * 1024); } while (0)
; #define PG8_MMA(ai, bj, At, Bt) do { __builtin_amdgcn_s_setprio(1); _Pragma("unroll") for (int m = 0; m < 4; ++m) _Pragma("unroll") for (int n = 0; n < 2; ++n) _Pragma("unroll") for (int k = 0; k < 2; ++k) \
;         acc[ai][bj][m][n] = __builtin_amdgcn_mfma_f32_16x16x32_bf16(Bt[n][k], At[m][k], acc[ai][bj][m][n], 0, 0, 0); __builtin_amdgcn_s_setprio(0); } while (0)
; #define PG8_WAIT_V(n) asm volatile("s_waitcnt vmcnt(" #n ")" ::: "memory")
; #define PG8_WAIT_L(n) asm volatile("s_waitcnt lgkmcnt(" #n ")" ::: "memory")
; #define PG8_BAR __builtin_amdgcn_s_barrier()
; #define PG8_SCHED __builtin_amdgcn_sched_barrier(0)
; template <class Epi, class Ptrs>
; __device__ __forceinline__ void gemm_phase(LAS unsigned char* lds, const int K, const StaticOrder& S, const Ptrs& P, const Epi& E) {
;     ...
;             PG8_BAR; PG8_WAIT_L(0); PG8_MMA(1, 0, At, B0); PG8_BAR; PG8_SCHED;
;             PG8_STAGE(PG8_SB(0, 1), b2 + hstep, voffB);
;             PG8_WAIT_V(6); PG8_BAR; PG8_MMA(1, 1, At, B1); PG8_BAR;
;             PG8_LDB(B0, 1, 0); PG8_SCHED; PG8_LDA(At, 1, 0); PG8_STAGE(PG8_SA(0, 1), a2 + hstep, voffA);
;             PG8_WAIT_L(8); PG8_BAR; PG8_WAIT_L(0); PG8_MMA(0, 0, At, B0); PG8_BAR; PG8_SCHED;
;             PG8_LDB(B1, 1, 1); PG8_STAGE(PG8_SB(1, 0), b3, voffB);
;             PG8_BAR; PG8_WAIT_L(0); PG8_MMA(0, 1, At, B1); PG8_BAR;
	s_waitcnt lgkmcnt(0)
	v_mfma_f32_16x16x32_bf16 v[56:59], v[150:153], v[166:169], v[56:59]
	v_mfma_f32_16x16x32_bf16 v[52:55], v[158:161], v[166:169], v[52:55]
	v_mfma_f32_16x16x32_bf16 v[40:43], v[150:153], v[174:177], v[40:43]
	v_mfma_f32_16x16x32_bf16 v[36:39], v[158:161], v[174:177], v[36:39]
	v_mfma_f32_16x16x32_bf16 v[24:27], v[150:153], v[182:185], v[24:27]
	v_mfma_f32_16x16x32_bf16 v[20:23], v[158:161], v[182:185], v[20:23]
	v_mfma_f32_16x16x32_bf16 v[8:11], v[150:153], v[190:193], v[8:11]
	v_mfma_f32_16x16x32_bf16 v[4:7], v[158:161], v[190:193], v[4:7]
	v_mfma_f32_16x16x32_bf16 v[56:59], v[154:157], v[170:173], v[56:59]
	v_mfma_f32_16x16x32_bf16 v[52:55], v[162:165], v[170:173], v[52:55]
	v_mfma_f32_16x16x32_bf16 v[40:43], v[154:157], v[178:181], v[40:43]
	v_mfma_f32_16x16x32_bf16 v[36:39], v[162:165], v[178:181], v[36:39]
	v_mfma_f32_16x16x32_bf16 v[24:27], v[154:157], v[186:189], v[24:27]
	v_mfma_f32_16x16x32_bf16 v[20:23], v[162:165], v[186:189], v[20:23]
	v_mfma_f32_16x16x32_bf16 v[8:11], v[154:157], v[194:197], v[8:11]
	v_mfma_f32_16x16x32_bf16 v[4:7], v[162:165], v[194:197], v[4:7]
	s_barrier
	s_add_u32 s82, s78, 0x40000
	s_addc_u32 s83, s79, 0
	s_add_i32 s69, s92, s65
	s_mov_b32 m0, s69
	s_nop 0
	global_load_lds_dwordx4 v134, s[82:83]
	s_add_i32 m0, s69, 0x2000
	s_nop 0
	global_load_lds_dwordx4 v138, s[82:83]
	s_waitcnt vmcnt(6)
	s_barrier
	v_mfma_f32_16x16x32_bf16 v[60:63], v[198:201], v[166:169], v[60:63]
	v_mfma_f32_16x16x32_bf16 v[48:51], v[214:217], v[166:169], v[48:51]
	v_mfma_f32_16x16x32_bf16 v[44:47], v[198:201], v[174:177], v[44:47]
	v_mfma_f32_16x16x32_bf16 v[32:35], v[214:217], v[174:177], v[32:35]
	v_mfma_f32_16x16x32_bf16 v[28:31], v[198:201], v[182:185], v[28:31]
	v_mfma_f32_16x16x32_bf16 v[16:19], v[214:217], v[182:185], v[16:19]
	v_mfma_f32_16x16x32_bf16 v[12:15], v[198:201], v[190:193], v[12:15]
	v_mfma_f32_16x16x32_bf16 v[0:3], v[214:217], v[190:193], v[0:3]
	v_mfma_f32_16x16x32_bf16 v[60:63], v[210:213], v[170:173], v[60:63]
	v_mfma_f32_16x16x32_bf16 v[48:51], v[218:221], v[170:173], v[48:51]
	v_mfma_f32_16x16x32_bf16 v[44:47], v[210:213], v[178:181], v[44:47]
	v_mfma_f32_16x16x32_bf16 v[32:35], v[218:221], v[178:181], v[32:35]
	v_mfma_f32_16x16x32_bf16 v[28:31], v[210:213], v[186:189], v[28:31]
	v_mfma_f32_16x16x32_bf16 v[16:19], v[218:221], v[186:189], v[16:19]
	v_mfma_f32_16x16x32_bf16 v[12:15], v[210:213], v[194:197], v[12:15]
	v_mfma_f32_16x16x32_bf16 v[0:3], v[218:221], v[194:197], v[0:3]
	s_barrier
	s_add_i32 s69, 0, 0x18000
	ds_read_b128 v[150:153], v252
	ds_read_b128 v[154:157], v252 offset:1024
	ds_read_b128 v[158:161], v252 offset:2048
	ds_read_b128 v[162:165], v252 offset:3072
	s_add_u32 s80, s80, 0x40000
	s_addc_u32 s81, s81, 0
	s_mov_b32 m0, s77
	ds_read_b128 v[166:169], v206 offset:32768
	ds_read_b128 v[170:173], v206 offset:33792
	ds_read_b128 v[174:177], v206 offset:34816
	ds_read_b128 v[178:181], v206 offset:35840
	ds_read_b128 v[182:185], v206 offset:36864
	ds_read_b128 v[186:189], v206 offset:37888
	ds_read_b128 v[190:193], v206 offset:38912
	ds_read_b128 v[194:197], v206 offset:39936
	global_load_lds_dwordx4 v132, s[80:81]
	s_mov_b32 m0, s85
	s_nop 0
	global_load_lds_dwordx4 v136, s[80:81]
	s_waitcnt lgkmcnt(8)
	s_barrier
	s_waitcnt lgkmcnt(0)
	v_mfma_f32_16x16x32_bf16 v[120:123], v[150:153], v[166:169], v[120:123]
	v_mfma_f32_16x16x32_bf16 v[116:119], v[158:161], v[166:169], v[116:119]
	v_mfma_f32_16x16x32_bf16 v[104:107], v[150:153], v[174:177], v[104:107]
	v_mfma_f32_16x16x32_bf16 v[100:103], v[158:161], v[174:177], v[100:103]
	v_mfma_f32_16x16x32_bf16 v[88:91], v[150:153], v[182:185], v[88:91]
	v_mfma_f32_16x16x32_bf16 v[84:87], v[158:161], v[182:185], v[84:87]
	v_mfma_f32_16x16x32_bf16 v[72:75], v[150:153], v[190:193], v[72:75]
	v_mfma_f32_16x16x32_bf16 v[68:71], v[158:161], v[190:193], v[68:71]
	v_mfma_f32_16x16x32_bf16 v[120:123], v[154:157], v[170:173], v[120:123]
	v_mfma_f32_16x16x32_bf16 v[116:119], v[162:165], v[170:173], v[116:119]
	v_mfma_f32_16x16x32_bf16 v[104:107], v[154:157], v[178:181], v[104:107]
	v_mfma_f32_16x16x32_bf16 v[100:103], v[162:165], v[178:181], v[100:103]
	v_mfma_f32_16x16x32_bf16 v[88:91], v[154:157], v[186:189], v[88:91]
	v_mfma_f32_16x16x32_bf16 v[84:87], v[162:165], v[186:189], v[84:87]
	v_mfma_f32_16x16x32_bf16 v[72:75], v[154:157], v[194:197], v[72:75]
	v_mfma_f32_16x16x32_bf16 v[68:71], v[162:165], v[194:197], v[68:71]
	s_barrier
	s_add_i32 s71, 0, 0x1c000
	s_add_i32 s69, s69, s65
	s_mov_b32 m0, s69
	ds_read_b128 v[198:201], v253
	ds_read_b128 v[210:213], v253 offset:1024
	ds_read_b128 v[214:217], v253 offset:2048
	ds_read_b128 v[218:221], v253 offset:3072
	global_load_lds_dwordx4 v134, s[100:101]
	s_add_i32 m0, s69, 0x2000
	s_nop 0
	global_load_lds_dwordx4 v138, s[100:101]
	s_barrier
; #define PG8_WAIT_V(n) asm volatile("s_waitcnt vmcnt(" #n ")" ::: "memory")
; template <class Epi, class Ptrs>
; __device__ __forceinline__ void gemm_phase(LAS unsigned char* lds, const int K, const StaticOrder& S, const Ptrs& P, const Epi& E) {
;     ...
;             PG8_BAR; PG8_WAIT_L(0); PG8_MMA(0, 1, At, B1); PG8_BAR;
;             PG8_LDA(At, 1, 1); PG8_STAGE(PG8_SA(1, 0), a3, voffA);
;             PG8_BAR; PG8_WAIT_L(0); PG8_MMA(1, 0, At, B0); PG8_BAR; PG8_SCHED;
;             PG8_STAGE(PG8_SB(1, 1), b3 + hstep, voffB);
;             PG8_WAIT_V(6); PG8_BAR; PG8_MMA(1, 1, At, B1); PG8_BAR;
;     __device__ __forceinline__ void operator()(const f32x4 (&acc)[2][2][4][2], const Unit& u, int ui, int wr, int wc, int fr, int fq) const {
;         const int pn = u.pn;
;         if (pn < 8) {
;             bf16_t* base = (bf16_t*)(ws + WS_U) + (size_t)(u.pm * 256 + wr * 64 + fr) * DM + pn * 128 + wc * 32 + 8 * fq;
; #pragma unroll
;             for (int ai = 0; ai < 2; ++ai)
; #pragma unroll
;                 for (int m = 0; m < 4; ++m) {
;                     const f32x4 g0 = g1_4(acc[ai][0][m][0], acc[ai][1][m][0]), g1 = g1_4(acc[ai][0][m][1], acc[ai][1][m][1]);
;                     *(u32x4*)(base + (size_t)(ai * 128 + m * 16) * DM) = pack8(g0, g1); }
;             return; }
;         if (pn >= 17 && pn < 21) {
;             bf16_t* base = (bf16_t*)(dout + DO_GVT) + (size_t)((pn - 17) * 256 + wr * 64 + fr) * MTOK + u.pm * 256 + wc * 32 + 8 * fq;
;             float* pp = (float*)(ws + WS_PART) + (size_t)(u.pm * 256 + wc * 32 + 8 * fq) * 8 + (pn - 17) * 2 + wr;
; #pragma unroll
;             for (int bj = 0; bj < 2; ++bj) { f32x4 sq0 = {0.f, 0.f, 0.f, 0.f}, sq1 = {0.f, 0.f, 0.f, 0.f};
; #pragma unroll
;                 for (int ai = 0; ai < 2; ++ai)
; #pragma unroll
;                     for (int m = 0; m < 4; ++m) { const f32x4 g0 = gelu4(acc[ai][bj][m][0]), g1 = gelu4(acc[ai][bj][m][1]);
;                         sq0 += g0 * g0; sq1 += g1 * g1;
;                         *(u32x4*)(base + (size_t)(ai * 128 + m * 16) * MTOK + bj * 128) = pack8(g0, g1); }
; #pragma unroll
;                 for (int j = 0; j < 4; ++j) { const float t0 = row16_sum(sq0[j]), t1 = row16_sum(sq1[j]); if (fr == 0) { pp[(size_t)(bj * 128 + j) * 8] = t0; pp[(size_t)(bj * 128 + 4 + j) * 8] = t1; } } }
;             return; }
;         bf16_t* base; size_t ld; int row0, col0, act;
	s_waitcnt lgkmcnt(0)
	v_mfma_f32_16x16x32_bf16 v[124:127], v[198:201], v[166:169], v[124:127]
	v_mfma_f32_16x16x32_bf16 v[112:115], v[214:217], v[166:169], v[112:115]
	v_mfma_f32_16x16x32_bf16 v[108:111], v[198:201], v[174:177], v[108:111]
	v_mfma_f32_16x16x32_bf16 v[96:99], v[214:217], v[174:177], v[96:99]
	v_mfma_f32_16x16x32_bf16 v[92:95], v[198:201], v[182:185], v[92:95]
	v_mfma_f32_16x16x32_bf16 v[80:83], v[214:217], v[182:185], v[80:83]
	v_mfma_f32_16x16x32_bf16 v[76:79], v[198:201], v[190:193], v[76:79]
	v_mfma_f32_16x16x32_bf16 v[64:67], v[214:217], v[190:193], v[64:67]
	v_mfma_f32_16x16x32_bf16 v[124:127], v[210:213], v[170:173], v[124:127]
	v_mfma_f32_16x16x32_bf16 v[112:115], v[218:221], v[170:173], v[112:115]
	v_mfma_f32_16x16x32_bf16 v[108:111], v[210:213], v[178:181], v[108:111]
	v_mfma_f32_16x16x32_bf16 v[96:99], v[218:221], v[178:181], v[96:99]
	v_mfma_f32_16x16x32_bf16 v[92:95], v[210:213], v[186:189], v[92:95]
	v_mfma_f32_16x16x32_bf16 v[80:83], v[218:221], v[186:189], v[80:83]
	v_mfma_f32_16x16x32_bf16 v[76:79], v[210:213], v[194:197], v[76:79]
	v_mfma_f32_16x16x32_bf16 v[64:67], v[218:221], v[194:197], v[64:67]
	s_barrier
	s_mov_b32 m0, s89
	s_add_u32 s100, s80, 0xfffc0080
	s_addc_u32 s101, s81, -1
	ds_read_b128 v[166:169], v206 offset:49152
	ds_read_b128 v[170:173], v206 offset:50176
	ds_read_b128 v[174:177], v206 offset:51200
	ds_read_b128 v[178:181], v206 offset:52224
	ds_read_b128 v[182:185], v206 offset:53248
	ds_read_b128 v[186:189], v206 offset:54272
	ds_read_b128 v[190:193], v206 offset:55296
	ds_read_b128 v[194:197], v206 offset:56320
	global_load_lds_dwordx4 v132, s[100:101]
	s_mov_b32 m0, s90
	s_nop 0
	global_load_lds_dwordx4 v136, s[100:101]
	s_barrier
	s_waitcnt lgkmcnt(0)
	v_mfma_f32_16x16x32_bf16 v[56:59], v[150:153], v[166:169], v[56:59]
	v_mfma_f32_16x16x32_bf16 v[52:55], v[158:161], v[166:169], v[52:55]
	v_mfma_f32_16x16x32_bf16 v[40:43], v[150:153], v[174:177], v[40:43]
	v_mfma_f32_16x16x32_bf16 v[36:39], v[158:161], v[174:177], v[36:39]
	v_mfma_f32_16x16x32_bf16 v[24:27], v[150:153], v[182:185], v[24:27]
	v_mfma_f32_16x16x32_bf16 v[20:23], v[158:161], v[182:185], v[20:23]
	v_mfma_f32_16x16x32_bf16 v[8:11], v[150:153], v[190:193], v[8:11]
	v_mfma_f32_16x16x32_bf16 v[4:7], v[158:161], v[190:193], v[4:7]
	v_mfma_f32_16x16x32_bf16 v[56:59], v[154:157], v[170:173], v[56:59]
	v_mfma_f32_16x16x32_bf16 v[52:55], v[162:165], v[170:173], v[52:55]
	v_mfma_f32_16x16x32_bf16 v[40:43], v[154:157], v[178:181], v[40:43]
	v_mfma_f32_16x16x32_bf16 v[36:39], v[162:165], v[178:181], v[36:39]
	v_mfma_f32_16x16x32_bf16 v[24:27], v[154:157], v[186:189], v[24:27]
	v_mfma_f32_16x16x32_bf16 v[20:23], v[162:165], v[186:189], v[20:23]
	v_mfma_f32_16x16x32_bf16 v[8:11], v[154:157], v[194:197], v[8:11]
	v_mfma_f32_16x16x32_bf16 v[4:7], v[162:165], v[194:197], v[4:7]
	s_barrier
	s_add_u32 s78, s78, 0x40080
	s_addc_u32 s79, s79, 0
	s_add_i32 s69, s71, s65
	s_mov_b32 m0, s69
	s_nop 0
	global_load_lds_dwordx4 v134, s[78:79]
	s_add_i32 m0, s69, 0x2000
	s_nop 0
	global_load_lds_dwordx4 v138, s[78:79]
	s_waitcnt vmcnt(6)
	s_barrier
	v_mfma_f32_16x16x32_bf16 v[60:63], v[198:201], v[166:169], v[60:63]
	v_mfma_f32_16x16x32_bf16 v[48:51], v[214:217], v[166:169], v[48:51]
	v_mfma_f32_16x16x32_bf16 v[44:47], v[198:201], v[174:177], v[44:47]
	v_mfma_f32_16x16x32_bf16 v[32:35], v[214:217], v[174:177], v[32:35]
	v_mfma_f32_16x16x32_bf16 v[28:31], v[198:201], v[182:185], v[28:31]
	v_mfma_f32_16x16x32_bf16 v[16:19], v[214:217], v[182:185], v[16:19]
	v_mfma_f32_16x16x32_bf16 v[12:15], v[198:201], v[190:193], v[12:15]
	v_mfma_f32_16x16x32_bf16 v[0:3], v[214:217], v[190:193], v[0:3]
	v_mfma_f32_16x16x32_bf16 v[60:63], v[210:213], v[170:173], v[60:63]
	v_mfma_f32_16x16x32_bf16 v[48:51], v[218:221], v[170:173], v[48:51]
	v_mfma_f32_16x16x32_bf16 v[44:47], v[210:213], v[178:181], v[44:47]
	v_mfma_f32_16x16x32_bf16 v[32:35], v[218:221], v[178:181], v[32:35]
	v_mfma_f32_16x16x32_bf16 v[28:31], v[210:213], v[186:189], v[28:31]
	v_mfma_f32_16x16x32_bf16 v[16:19], v[218:221], v[186:189], v[16:19]
	v_mfma_f32_16x16x32_bf16 v[12:15], v[210:213], v[194:197], v[12:15]
	v_mfma_f32_16x16x32_bf16 v[0:3], v[218:221], v[194:197], v[0:3]
	s_barrier
	s_add_i32 s63, s63, 2
	s_add_u32 s6, s6, 0x100
	s_addc_u32 s7, s7, 0
	s_add_u32 s20, s20, 0x100
	s_addc_u32 s25, s25, 0
	s_cmp_gt_u32 s63, 13
	s_cbranch_scc0 .LBB0_127
	s_cmp_gt_i32 s74, 7
	s_mov_b64 s[6:7], -1
	s_cbranch_scc0 .LBB0_188
	s_sub_i32 s25, s74, 17
	s_cmp_gt_u32 s25, 3
	s_cbranch_scc0 .LBB0_170
	s_lshl_b32 s69, s76, 8
	s_cmp_gt_u32 s74, 11
	s_cbranch_scc0 .LBB0_135
	s_cmp_eq_u32 s74, 12
	s_mov_b64 s[6:7], 0
	s_cbranch_scc1 .LBB0_134
	s_cmp_gt_u32 s74, 16
	s_cbranch_scc1 .LBB0_191
	s_lshl_b32 s20, s74, 8
	v_readlane_b32 s80, v254, 2
	s_addk_i32 s20, 0xf300
	s_mov_b64 s[78:79], 0x400
	s_mov_b64 s[82:83], -1
	s_mov_b32 s63, s69
	v_readlane_b32 s81, v254, 3
	s_andn2_b64 vcc, exec, s[6:7]
	s_cbranch_vccz .LBB0_136
	s_branch .LBB0_137

; #define PG8_STAGE(bufoff, gbase, voff) do { _Pragma("unroll") for (int _i = 0; _i < 2; ++_i) \
;         __builtin_amdgcn_global_load_lds((const unsigned*)((const char*)(gbase) + (voff)[_i]), (LAS unsigned*)(lds + (bufoff) + ldsw + _i * 8192), 16, 0, 0); } while (0)
; #define PG8_LDA(dst, b, h) do { _Pragma("unroll") for (int m = 0; m < 4; ++m) _Pragma("unroll") for (int k = 0; k < 2; ++k) dst[m][k] = *(const LAS bf16x8*)(lds + PG8_SA(b, h) + aoff + m * 2048 + k * 1024); } while (0)
; #define PG8_LDB(dst, b, h) do { _Pragma("unroll") for (int n = 0; n < 2; ++n) _Pragma("unroll") for (int k = 0; k < 2; ++k) dst[n][k] = *(const LAS bf16x8*)(lds + PG8_SB(b, h) + boff + n * 2048 + k * 1024); } while (0)
; #define PG8_MMA(ai, bj, At, Bt) do { __builtin_amdgcn_s_setprio(1); _Pragma("unroll") for (int m = 0; m < 4; ++m) _Pragma("unroll") for (int n = 0; n < 2; ++n) _Pragma("unroll") for (int k = 0; k < 2; ++k) \
;         acc[ai][bj][m][n] = __builtin_amdgcn_mfma_f32_16x16x32_bf16(Bt[n][k], At[m][k], acc[ai][bj][m][n], 0, 0, 0); __builtin_amdgcn_s_setprio(0); } while (0)
; #define PG8_WAIT_V(n) asm volatile("s_waitcnt vmcnt(" #n ")" ::: "memory")
; #define PG8_WAIT_L(n) asm volatile("s_waitcnt lgkmcnt(" #n ")" ::: "memory")
; template <class Epi, class Ptrs>
; __device__ __forceinline__ void gemm_phase(LAS unsigned char* lds, const int K, const StaticOrder& S, const Ptrs& P, const Epi& E) {
;     ...
;         for (int t = 0; t < nt; t += 2) {
;             const bool last = (t == nt - 2);
;             const char* a1 = cA + (size_t)(t + 1) * kstep;
;             const char* a2 = last ? nA : cA + (size_t)(t + 2) * kstep; const char* b2 = last ? nB : cB + (size_t)(t + 2) * kstep;
;             const char* a3 = a2 + kstep; const char* b3 = b2 + kstep;
;             PG8_LDB(B0, 0, 0); PG8_SCHED; PG8_LDA(At, 0, 0); PG8_STAGE(PG8_SA(1, 1), a1 + hstep, voffA);
;             PG8_WAIT_L(8); PG8_BAR; PG8_WAIT_L(0); PG8_MMA(0, 0, At, B0); PG8_BAR; PG8_SCHED;
;             PG8_LDB(B1, 0, 1); PG8_STAGE(PG8_SB(0, 0), b2, voffB);
;             PG8_BAR; PG8_WAIT_L(0); PG8_MMA(0, 1, At, B1); PG8_BAR;
;             PG8_LDA(At, 0, 1); PG8_STAGE(PG8_SA(0, 0), a2, voffA);
;             PG8_BAR; PG8_WAIT_L(0); PG8_MMA(1, 0, At, B0); PG8_BAR; PG8_SCHED;
;             PG8_STAGE(PG8_SB(0, 1), b2 + hstep, voffB);
;             PG8_WAIT_V(6); PG8_BAR; PG8_MMA(1, 1, At, B1); PG8_BAR;
.LBB0_352:
	s_add_u32 s38, s44, 0x40080
	s_addc_u32 s39, s45, 0
	s_add_u32 s21, s42, 0x100
	s_addc_u32 s23, s43, 0
	s_mov_b32 s41, -2
	v_add_u32_e32 v252, 0x18000, v205
	v_add_u32_e32 v253, 0x1c000, v205
	ds_read_b128 v[128:131], v207
	ds_read_b128 v[132:135], v207 offset:1024
	ds_read_b128 v[136:139], v207 offset:2048
	ds_read_b128 v[140:143], v207 offset:3072
	s_add_u32 s42, s38, 0xfffc0080
	s_addc_u32 s43, s39, -1
	s_cmp_eq_u32 s41, 12
	s_cselect_b32 s45, s1, s43
	s_cselect_b32 s44, s0, s42
	s_cselect_b32 s43, s25, s23
	s_cselect_b32 s42, s24, s21
	s_add_i32 m0, s54, 0xc000
	ds_read_b128 v[144:147], v209
	ds_read_b128 v[148:151], v209 offset:1024
	ds_read_b128 v[152:155], v209 offset:2048
	ds_read_b128 v[156:159], v209 offset:3072
	ds_read_b128 v[160:163], v209 offset:4096
	ds_read_b128 v[164:167], v209 offset:5120
	ds_read_b128 v[168:171], v209 offset:6144
	ds_read_b128 v[172:175], v209 offset:7168
	global_load_lds_dwordx4 v184, s[38:39]
	s_add_i32 m0, s54, 0xe000
	s_nop 0
	global_load_lds_dwordx4 v186, s[38:39]
	s_waitcnt lgkmcnt(8)
	s_barrier
	s_waitcnt lgkmcnt(0)
	v_mfma_f32_16x16x32_bf16 v[124:127], v[128:131], v[144:147], 0
	v_mfma_f32_16x16x32_bf16 v[120:123], v[136:139], v[144:147], 0
	v_mfma_f32_16x16x32_bf16 v[108:111], v[128:131], v[152:155], 0
	v_mfma_f32_16x16x32_bf16 v[104:107], v[136:139], v[152:155], 0
	v_mfma_f32_16x16x32_bf16 v[92:95], v[128:131], v[160:163], 0
	v_mfma_f32_16x16x32_bf16 v[88:91], v[136:139], v[160:163], 0
	v_mfma_f32_16x16x32_bf16 v[76:79], v[128:131], v[168:171], 0
	v_mfma_f32_16x16x32_bf16 v[72:75], v[136:139], v[168:171], 0
	v_mfma_f32_16x16x32_bf16 v[124:127], v[132:135], v[148:151], v[124:127]
	v_mfma_f32_16x16x32_bf16 v[120:123], v[140:143], v[148:151], v[120:123]
	v_mfma_f32_16x16x32_bf16 v[108:111], v[132:135], v[156:159], v[108:111]
	v_mfma_f32_16x16x32_bf16 v[104:107], v[140:143], v[156:159], v[104:107]
	v_mfma_f32_16x16x32_bf16 v[92:95], v[132:135], v[164:167], v[92:95]
	v_mfma_f32_16x16x32_bf16 v[88:91], v[140:143], v[164:167], v[88:91]
	v_mfma_f32_16x16x32_bf16 v[76:79], v[132:135], v[172:175], v[76:79]
	v_mfma_f32_16x16x32_bf16 v[72:75], v[140:143], v[172:175], v[72:75]
	s_barrier
	s_add_i32 s69, s66, s51
	s_add_u32 s90, s42, 0x80
	s_addc_u32 s91, s43, 0
	s_mov_b32 m0, s69
	ds_read_b128 v[192:195], v210
	ds_read_b128 v[196:199], v210 offset:1024
	ds_read_b128 v[200:203], v210 offset:2048
	ds_read_b128 v[212:215], v210 offset:3072
	global_load_lds_dwordx4 v178, s[42:43]
	s_add_i32 m0, s69, 0x2000
	s_nop 0
	global_load_lds_dwordx4 v182, s[42:43]
	s_barrier
	s_waitcnt lgkmcnt(0)
	v_mfma_f32_16x16x32_bf16 v[116:119], v[192:195], v[144:147], 0
	v_mfma_f32_16x16x32_bf16 v[112:115], v[200:203], v[144:147], 0
	v_mfma_f32_16x16x32_bf16 v[100:103], v[192:195], v[152:155], 0
	v_mfma_f32_16x16x32_bf16 v[96:99], v[200:203], v[152:155], 0
	v_mfma_f32_16x16x32_bf16 v[84:87], v[192:195], v[160:163], 0
	v_mfma_f32_16x16x32_bf16 v[80:83], v[200:203], v[160:163], 0
	v_mfma_f32_16x16x32_bf16 v[68:71], v[192:195], v[168:171], 0
	v_mfma_f32_16x16x32_bf16 v[64:67], v[200:203], v[168:171], 0
	v_mfma_f32_16x16x32_bf16 v[116:119], v[196:199], v[148:151], v[116:119]
	v_mfma_f32_16x16x32_bf16 v[112:115], v[212:215], v[148:151], v[112:115]
	v_mfma_f32_16x16x32_bf16 v[100:103], v[196:199], v[156:159], v[100:103]
	v_mfma_f32_16x16x32_bf16 v[96:99], v[212:215], v[156:159], v[96:99]
	v_mfma_f32_16x16x32_bf16 v[84:87], v[196:199], v[164:167], v[84:87]
	v_mfma_f32_16x16x32_bf16 v[80:83], v[212:215], v[164:167], v[80:83]
	v_mfma_f32_16x16x32_bf16 v[68:71], v[196:199], v[172:175], v[68:71]
	v_mfma_f32_16x16x32_bf16 v[64:67], v[212:215], v[172:175], v[64:67]
	s_barrier
	s_mov_b32 m0, s54
	s_add_u32 s92, s44, 0x80
	s_addc_u32 s93, s45, 0
	ds_read_b128 v[144:147], v209 offset:16384
	ds_read_b128 v[148:151], v209 offset:17408
	ds_read_b128 v[152:155], v209 offset:18432
	ds_read_b128 v[156:159], v209 offset:19456
	ds_read_b128 v[160:163], v209 offset:20480
	ds_read_b128 v[164:167], v209 offset:21504
	ds_read_b128 v[168:171], v209 offset:22528
	ds_read_b128 v[172:175], v209 offset:23552
	global_load_lds_dwordx4 v176, s[44:45]
	s_mov_b32 m0, s55
	s_nop 0
	global_load_lds_dwordx4 v180, s[44:45]
	s_barrier
	s_waitcnt lgkmcnt(0)
	v_mfma_f32_16x16x32_bf16 v[60:63], v[128:131], v[144:147], 0
	v_mfma_f32_16x16x32_bf16 v[56:59], v[136:139], v[144:147], 0
	v_mfma_f32_16x16x32_bf16 v[44:47], v[128:131], v[152:155], 0
	v_mfma_f32_16x16x32_bf16 v[40:43], v[136:139], v[152:155], 0
	v_mfma_f32_16x16x32_bf16 v[28:31], v[128:131], v[160:163], 0
	v_mfma_f32_16x16x32_bf16 v[24:27], v[136:139], v[160:163], 0
	v_mfma_f32_16x16x32_bf16 v[12:15], v[128:131], v[168:171], 0
	v_mfma_f32_16x16x32_bf16 v[8:11], v[136:139], v[168:171], 0
	v_mfma_f32_16x16x32_bf16 v[60:63], v[132:135], v[148:151], v[60:63]
	v_mfma_f32_16x16x32_bf16 v[56:59], v[140:143], v[148:151], v[56:59]
	v_mfma_f32_16x16x32_bf16 v[44:47], v[132:135], v[156:159], v[44:47]
	v_mfma_f32_16x16x32_bf16 v[40:43], v[140:143], v[156:159], v[40:43]
	v_mfma_f32_16x16x32_bf16 v[28:31], v[132:135], v[164:167], v[28:31]
	v_mfma_f32_16x16x32_bf16 v[24:27], v[140:143], v[164:167], v[24:27]
	v_mfma_f32_16x16x32_bf16 v[12:15], v[132:135], v[172:175], v[12:15]
	v_mfma_f32_16x16x32_bf16 v[8:11], v[140:143], v[172:175], v[8:11]
	s_barrier
	s_add_u32 s70, s42, 0x40000
	s_addc_u32 s71, s43, 0
	s_add_i32 s69, s67, s51
	s_mov_b32 m0, s69
	s_nop 0
	global_load_lds_dwordx4 v178, s[70:71]
	s_add_i32 m0, s69, 0x2000
	s_nop 0
	global_load_lds_dwordx4 v182, s[70:71]
	s_waitcnt vmcnt(6)
	s_barrier
; #define PG8_STAGE(bufoff, gbase, voff) do { _Pragma("unroll") for (int _i = 0; _i < 2; ++_i) \
;         __builtin_amdgcn_global_load_lds((const unsigned*)((const char*)(gbase) + (voff)[_i]), (LAS unsigned*)(lds + (bufoff) + ldsw + _i * 8192), 16, 0, 0); } while (0)
; #define PG8_LDA(dst, b, h) do { _Pragma("unroll") for (int m = 0; m < 4; ++m) _Pragma("unroll") for (int k = 0; k < 2; ++k) dst[m][k] = *(const LAS bf16x8*)(lds + PG8_SA(b, h) + aoff + m * 2048 + k * 1024); } while (0)
; #define PG8_LDB(dst, b, h) do { _Pragma("unroll") for (int n = 0; n < 2; ++n) _Pragma("unroll") for (int k = 0; k < 2; ++k) dst[n][k] = *(const LAS bf16x8*)(lds + PG8_SB(b, h) + boff + n * 2048 + k * 1024); } while (0)
; #define PG8_MMA(ai, bj, At, Bt) do { __builtin_amdgcn_s_setprio(1); _Pragma("unroll") for (int m = 0; m < 4; ++m) _Pragma("unroll") for (int n = 0; n < 2; ++n) _Pragma("unroll") for (int k = 0; k < 2; ++k) \
;         acc[ai][bj][m][n] = __builtin_amdgcn_mfma_f32_16x16x32_bf16(Bt[n][k], At[m][k], acc[ai][bj][m][n], 0, 0, 0); __builtin_amdgcn_s_setprio(0); } while (0)
; #define PG8_WAIT_V(n) asm volatile("s_waitcnt vmcnt(" #n ")" ::: "memory")
; #define PG8_WAIT_L(n) asm volatile("s_waitcnt lgkmcnt(" #n ")" ::: "memory")
; #define PG8_BAR __builtin_amdgcn_s_barrier()
; #define PG8_SCHED __builtin_amdgcn_sched_barrier(0)
; template <class Epi, class Ptrs>
; __device__ __forceinline__ void gemm_phase(LAS unsigned char* lds, const int K, const StaticOrder& S, const Ptrs& P, const Epi& E) {
;     ...
;             PG8_WAIT_V(6); PG8_BAR; PG8_MMA(1, 1, At, B1); PG8_BAR;
;             PG8_LDB(B0, 1, 0); PG8_SCHED; PG8_LDA(At, 1, 0); PG8_STAGE(PG8_SA(0, 1), a2 + hstep, voffA);
;             PG8_WAIT_L(8); PG8_BAR; PG8_WAIT_L(0); PG8_MMA(0, 0, At, B0); PG8_BAR; PG8_SCHED;
;             PG8_LDB(B1, 1, 1); PG8_STAGE(PG8_SB(1, 0), b3, voffB);
;             PG8_BAR; PG8_WAIT_L(0); PG8_MMA(0, 1, At, B1); PG8_BAR;
;             PG8_LDA(At, 1, 1); PG8_STAGE(PG8_SA(1, 0), a3, voffA);
;             PG8_BAR; PG8_WAIT_L(0); PG8_MMA(1, 0, At, B0); PG8_BAR; PG8_SCHED;
	v_mfma_f32_16x16x32_bf16 v[52:55], v[192:195], v[144:147], 0
	v_mfma_f32_16x16x32_bf16 v[48:51], v[200:203], v[144:147], 0
	v_mfma_f32_16x16x32_bf16 v[36:39], v[192:195], v[152:155], 0
	v_mfma_f32_16x16x32_bf16 v[32:35], v[200:203], v[152:155], 0
	v_mfma_f32_16x16x32_bf16 v[20:23], v[192:195], v[160:163], 0
	v_mfma_f32_16x16x32_bf16 v[16:19], v[200:203], v[160:163], 0
	v_mfma_f32_16x16x32_bf16 v[4:7], v[192:195], v[168:171], 0
	v_mfma_f32_16x16x32_bf16 v[0:3], v[200:203], v[168:171], 0
	v_mfma_f32_16x16x32_bf16 v[52:55], v[196:199], v[148:151], v[52:55]
	v_mfma_f32_16x16x32_bf16 v[48:51], v[212:215], v[148:151], v[48:51]
	v_mfma_f32_16x16x32_bf16 v[36:39], v[196:199], v[156:159], v[36:39]
	v_mfma_f32_16x16x32_bf16 v[32:35], v[212:215], v[156:159], v[32:35]
	v_mfma_f32_16x16x32_bf16 v[20:23], v[196:199], v[164:167], v[20:23]
	v_mfma_f32_16x16x32_bf16 v[16:19], v[212:215], v[164:167], v[16:19]
	v_mfma_f32_16x16x32_bf16 v[4:7], v[196:199], v[172:175], v[4:7]
	v_mfma_f32_16x16x32_bf16 v[0:3], v[212:215], v[172:175], v[0:3]
	s_barrier
	s_add_i32 s69, 0, 0x18000
	ds_read_b128 v[128:131], v252
	ds_read_b128 v[132:135], v252 offset:1024
	ds_read_b128 v[136:139], v252 offset:2048
	ds_read_b128 v[140:143], v252 offset:3072
	s_add_u32 s44, s44, 0x40000
	s_addc_u32 s45, s45, 0
	s_mov_b32 m0, s56
	ds_read_b128 v[144:147], v209 offset:32768
	ds_read_b128 v[148:151], v209 offset:33792
	ds_read_b128 v[152:155], v209 offset:34816
	ds_read_b128 v[156:159], v209 offset:35840
	ds_read_b128 v[160:163], v209 offset:36864
	ds_read_b128 v[164:167], v209 offset:37888
	ds_read_b128 v[168:171], v209 offset:38912
	ds_read_b128 v[172:175], v209 offset:39936
	global_load_lds_dwordx4 v176, s[44:45]
	s_mov_b32 m0, s57
	s_nop 0
	global_load_lds_dwordx4 v180, s[44:45]
	s_waitcnt lgkmcnt(8)
	s_barrier
	s_waitcnt lgkmcnt(0)
	v_mfma_f32_16x16x32_bf16 v[124:127], v[128:131], v[144:147], v[124:127]
	v_mfma_f32_16x16x32_bf16 v[120:123], v[136:139], v[144:147], v[120:123]
	v_mfma_f32_16x16x32_bf16 v[108:111], v[128:131], v[152:155], v[108:111]
	v_mfma_f32_16x16x32_bf16 v[104:107], v[136:139], v[152:155], v[104:107]
	v_mfma_f32_16x16x32_bf16 v[92:95], v[128:131], v[160:163], v[92:95]
	v_mfma_f32_16x16x32_bf16 v[88:91], v[136:139], v[160:163], v[88:91]
	v_mfma_f32_16x16x32_bf16 v[76:79], v[128:131], v[168:171], v[76:79]
	v_mfma_f32_16x16x32_bf16 v[72:75], v[136:139], v[168:171], v[72:75]
	v_mfma_f32_16x16x32_bf16 v[124:127], v[132:135], v[148:151], v[124:127]
	v_mfma_f32_16x16x32_bf16 v[120:123], v[140:143], v[148:151], v[120:123]
	v_mfma_f32_16x16x32_bf16 v[108:111], v[132:135], v[156:159], v[108:111]
	v_mfma_f32_16x16x32_bf16 v[104:107], v[140:143], v[156:159], v[104:107]
	v_mfma_f32_16x16x32_bf16 v[92:95], v[132:135], v[164:167], v[92:95]
	v_mfma_f32_16x16x32_bf16 v[88:91], v[140:143], v[164:167], v[88:91]
	v_mfma_f32_16x16x32_bf16 v[76:79], v[132:135], v[172:175], v[76:79]
	v_mfma_f32_16x16x32_bf16 v[72:75], v[140:143], v[172:175], v[72:75]
	s_barrier
	s_add_i32 s44, 0, 0x1c000
	s_add_i32 s45, s69, s51
	s_mov_b32 m0, s45
	ds_read_b128 v[192:195], v253
	ds_read_b128 v[196:199], v253 offset:1024
	ds_read_b128 v[200:203], v253 offset:2048
	ds_read_b128 v[212:215], v253 offset:3072
	global_load_lds_dwordx4 v178, s[90:91]
	s_add_i32 m0, s45, 0x2000
	s_nop 0
	global_load_lds_dwordx4 v182, s[90:91]
	s_barrier
	s_waitcnt lgkmcnt(0)
	v_mfma_f32_16x16x32_bf16 v[116:119], v[192:195], v[144:147], v[116:119]
	v_mfma_f32_16x16x32_bf16 v[112:115], v[200:203], v[144:147], v[112:115]
	v_mfma_f32_16x16x32_bf16 v[100:103], v[192:195], v[152:155], v[100:103]
	v_mfma_f32_16x16x32_bf16 v[96:99], v[200:203], v[152:155], v[96:99]
	v_mfma_f32_16x16x32_bf16 v[84:87], v[192:195], v[160:163], v[84:87]
	v_mfma_f32_16x16x32_bf16 v[80:83], v[200:203], v[160:163], v[80:83]
	v_mfma_f32_16x16x32_bf16 v[68:71], v[192:195], v[168:171], v[68:71]
	v_mfma_f32_16x16x32_bf16 v[64:67], v[200:203], v[168:171], v[64:67]
	v_mfma_f32_16x16x32_bf16 v[116:119], v[196:199], v[148:151], v[116:119]
	v_mfma_f32_16x16x32_bf16 v[112:115], v[212:215], v[148:151], v[112:115]
	v_mfma_f32_16x16x32_bf16 v[100:103], v[196:199], v[156:159], v[100:103]
	v_mfma_f32_16x16x32_bf16 v[96:99], v[212:215], v[156:159], v[96:99]
	v_mfma_f32_16x16x32_bf16 v[84:87], v[196:199], v[164:167], v[84:87]
	v_mfma_f32_16x16x32_bf16 v[80:83], v[212:215], v[164:167], v[80:83]
	v_mfma_f32_16x16x32_bf16 v[68:71], v[196:199], v[172:175], v[68:71]
	v_mfma_f32_16x16x32_bf16 v[64:67], v[212:215], v[172:175], v[64:67]
	s_barrier
	s_mov_b32 m0, s63
	ds_read_b128 v[144:147], v209 offset:49152
	ds_read_b128 v[148:151], v209 offset:50176
	ds_read_b128 v[152:155], v209 offset:51200
	ds_read_b128 v[156:159], v209 offset:52224
	ds_read_b128 v[160:163], v209 offset:53248
	ds_read_b128 v[164:167], v209 offset:54272
	ds_read_b128 v[168:171], v209 offset:55296
	ds_read_b128 v[172:175], v209 offset:56320
	global_load_lds_dwordx4 v176, s[92:93]
	s_mov_b32 m0, s64
	s_nop 0
	global_load_lds_dwordx4 v180, s[92:93]
	s_barrier
	s_waitcnt lgkmcnt(0)
	v_mfma_f32_16x16x32_bf16 v[60:63], v[128:131], v[144:147], v[60:63]
	v_mfma_f32_16x16x32_bf16 v[56:59], v[136:139], v[144:147], v[56:59]
	v_mfma_f32_16x16x32_bf16 v[44:47], v[128:131], v[152:155], v[44:47]
	v_mfma_f32_16x16x32_bf16 v[40:43], v[136:139], v[152:155], v[40:43]
	v_mfma_f32_16x16x32_bf16 v[28:31], v[128:131], v[160:163], v[28:31]
	v_mfma_f32_16x16x32_bf16 v[24:27], v[136:139], v[160:163], v[24:27]
	v_mfma_f32_16x16x32_bf16 v[12:15], v[128:131], v[168:171], v[12:15]
	v_mfma_f32_16x16x32_bf16 v[8:11], v[136:139], v[168:171], v[8:11]
	v_mfma_f32_16x16x32_bf16 v[60:63], v[132:135], v[148:151], v[60:63]
	v_mfma_f32_16x16x32_bf16 v[56:59], v[140:143], v[148:151], v[56:59]
	v_mfma_f32_16x16x32_bf16 v[44:47], v[132:135], v[156:159], v[44:47]
	v_mfma_f32_16x16x32_bf16 v[40:43], v[140:143], v[156:159], v[40:43]
	v_mfma_f32_16x16x32_bf16 v[28:31], v[132:135], v[164:167], v[28:31]
	v_mfma_f32_16x16x32_bf16 v[24:27], v[140:143], v[164:167], v[24:27]
	v_mfma_f32_16x16x32_bf16 v[12:15], v[132:135], v[172:175], v[12:15]
	v_mfma_f32_16x16x32_bf16 v[8:11], v[140:143], v[172:175], v[8:11]
	s_barrier
; #define PG8_STAGE(bufoff, gbase, voff) do { _Pragma("unroll") for (int _i = 0; _i < 2; ++_i) \
;         __builtin_amdgcn_global_load_lds((const unsigned*)((const char*)(gbase) + (voff)[_i]), (LAS unsigned*)(lds + (bufoff) + ldsw + _i * 8192), 16, 0, 0); } while (0)
; #define PG8_LDA(dst, b, h) do { _Pragma("unroll") for (int m = 0; m < 4; ++m) _Pragma("unroll") for (int k = 0; k < 2; ++k) dst[m][k] = *(const LAS bf16x8*)(lds + PG8_SA(b, h) + aoff + m * 2048 + k * 1024); } while (0)
; #define PG8_LDB(dst, b, h) do { _Pragma("unroll") for (int n = 0; n < 2; ++n) _Pragma("unroll") for (int k = 0; k < 2; ++k) dst[n][k] = *(const LAS bf16x8*)(lds + PG8_SB(b, h) + boff + n * 2048 + k * 1024); } while (0)
; #define PG8_WAIT_V(n) asm volatile("s_waitcnt vmcnt(" #n ")" ::: "memory")
; #define PG8_WAIT_L(n) asm volatile("s_waitcnt lgkmcnt(" #n ")" ::: "memory")
; #define PG8_BAR __builtin_amdgcn_s_barrier()
; #define PG8_SCHED __builtin_amdgcn_sched_barrier(0)
; template <class Epi, class Ptrs>
; __device__ __forceinline__ void gemm_phase(LAS unsigned char* lds, const int K, const StaticOrder& S, const Ptrs& P, const Epi& E) {
;     ...
;             PG8_LDB(B0, 0, 0); PG8_SCHED; PG8_LDA(At, 0, 0); PG8_STAGE(PG8_SA(1, 1), a1 + hstep, voffA);
;             PG8_WAIT_L(8); PG8_BAR; PG8_WAIT_L(0); PG8_MMA(0, 0, At, B0); PG8_BAR; PG8_SCHED;
;             PG8_LDB(B1, 0, 1); PG8_STAGE(PG8_SB(0, 0), b2, voffB);
;             PG8_BAR; PG8_WAIT_L(0); PG8_MMA(0, 1, At, B1); PG8_BAR;
;             PG8_LDA(At, 0, 1); PG8_STAGE(PG8_SA(0, 0), a2, voffA);
;             PG8_BAR; PG8_WAIT_L(0); PG8_MMA(1, 0, At, B0); PG8_BAR; PG8_SCHED;
;             PG8_STAGE(PG8_SB(0, 1), b2 + hstep, voffB);
;             PG8_WAIT_V(6); PG8_BAR; PG8_MMA(1, 1, At, B1); PG8_BAR;
;             PG8_LDB(B0, 1, 0); PG8_SCHED; PG8_LDA(At, 1, 0); PG8_STAGE(PG8_SA(0, 1), a2 + hstep, voffA);
;             PG8_WAIT_L(8); PG8_BAR; PG8_WAIT_L(0); PG8_MMA(0, 0, At, B0); PG8_BAR; PG8_SCHED;
;             PG8_LDB(B1, 1, 1); PG8_STAGE(PG8_SB(1, 0), b3, voffB);
;             PG8_BAR; PG8_WAIT_L(0); PG8_MMA(0, 1, At, B1); PG8_BAR;
;             PG8_LDA(At, 1, 1); PG8_STAGE(PG8_SA(1, 0), a3, voffA);
;             PG8_BAR; PG8_WAIT_L(0); PG8_MMA(1, 0, At, B0); PG8_BAR; PG8_SCHED;
;             PG8_STAGE(PG8_SB(1, 1), b3 + hstep, voffB);
;             PG8_WAIT_V(6); PG8_BAR; PG8_MMA(1, 1, At, B1); PG8_BAR;
	s_add_u32 s42, s42, 0x40080
	s_addc_u32 s43, s43, 0
	s_add_i32 s44, s44, s51
	s_mov_b32 m0, s44
	s_nop 0
	global_load_lds_dwordx4 v178, s[42:43]
	s_add_i32 m0, s44, 0x2000
	s_nop 0
	global_load_lds_dwordx4 v182, s[42:43]
	s_waitcnt vmcnt(6)
	s_barrier
	v_mfma_f32_16x16x32_bf16 v[52:55], v[192:195], v[144:147], v[52:55]
	v_mfma_f32_16x16x32_bf16 v[48:51], v[200:203], v[144:147], v[48:51]
	v_mfma_f32_16x16x32_bf16 v[36:39], v[192:195], v[152:155], v[36:39]
	v_mfma_f32_16x16x32_bf16 v[32:35], v[200:203], v[152:155], v[32:35]
	v_mfma_f32_16x16x32_bf16 v[20:23], v[192:195], v[160:163], v[20:23]
	v_mfma_f32_16x16x32_bf16 v[16:19], v[200:203], v[160:163], v[16:19]
	v_mfma_f32_16x16x32_bf16 v[4:7], v[192:195], v[168:171], v[4:7]
	v_mfma_f32_16x16x32_bf16 v[0:3], v[200:203], v[168:171], v[0:3]
	v_mfma_f32_16x16x32_bf16 v[52:55], v[196:199], v[148:151], v[52:55]
	v_mfma_f32_16x16x32_bf16 v[48:51], v[212:215], v[148:151], v[48:51]
	v_mfma_f32_16x16x32_bf16 v[36:39], v[196:199], v[156:159], v[36:39]
	v_mfma_f32_16x16x32_bf16 v[32:35], v[212:215], v[156:159], v[32:35]
	v_mfma_f32_16x16x32_bf16 v[20:23], v[196:199], v[164:167], v[20:23]
	v_mfma_f32_16x16x32_bf16 v[16:19], v[212:215], v[164:167], v[16:19]
	v_mfma_f32_16x16x32_bf16 v[4:7], v[196:199], v[172:175], v[4:7]
	v_mfma_f32_16x16x32_bf16 v[0:3], v[212:215], v[172:175], v[0:3]
	s_barrier
	s_add_i32 s41, s41, 2
	s_add_u32 s38, s38, 0x100
	s_addc_u32 s39, s39, 0
	s_add_u32 s21, s21, 0x100
	s_addc_u32 s23, s23, 0
	s_cmp_gt_u32 s41, 13
.LBB0_353:
	ds_read_b128 v[128:131], v207
	ds_read_b128 v[132:135], v207 offset:1024
	ds_read_b128 v[136:139], v207 offset:2048
	ds_read_b128 v[140:143], v207 offset:3072
	s_add_u32 s42, s38, 0xfffc0080
	s_addc_u32 s43, s39, -1
	s_cmp_eq_u32 s41, 12
	s_cselect_b32 s45, s1, s43
	s_cselect_b32 s44, s0, s42
	s_cselect_b32 s43, s25, s23
	s_cselect_b32 s42, s24, s21
	s_add_i32 m0, s54, 0xc000
	ds_read_b128 v[144:147], v209
	ds_read_b128 v[148:151], v209 offset:1024
	ds_read_b128 v[152:155], v209 offset:2048
	ds_read_b128 v[156:159], v209 offset:3072
	ds_read_b128 v[160:163], v209 offset:4096
	ds_read_b128 v[164:167], v209 offset:5120
	ds_read_b128 v[168:171], v209 offset:6144
	ds_read_b128 v[172:175], v209 offset:7168
	global_load_lds_dwordx4 v184, s[38:39]
	s_add_i32 m0, s54, 0xe000
	s_nop 0
	global_load_lds_dwordx4 v186, s[38:39]
	s_waitcnt lgkmcnt(8)
	s_barrier
	s_waitcnt lgkmcnt(0)
	v_mfma_f32_16x16x32_bf16 v[124:127], v[128:131], v[144:147], v[124:127]
	v_mfma_f32_16x16x32_bf16 v[120:123], v[136:139], v[144:147], v[120:123]
	v_mfma_f32_16x16x32_bf16 v[108:111], v[128:131], v[152:155], v[108:111]
	v_mfma_f32_16x16x32_bf16 v[104:107], v[136:139], v[152:155], v[104:107]
	v_mfma_f32_16x16x32_bf16 v[92:95], v[128:131], v[160:163], v[92:95]
	v_mfma_f32_16x16x32_bf16 v[88:91], v[136:139], v[160:163], v[88:91]
	v_mfma_f32_16x16x32_bf16 v[76:79], v[128:131], v[168:171], v[76:79]
	v_mfma_f32_16x16x32_bf16 v[72:75], v[136:139], v[168:171], v[72:75]
	v_mfma_f32_16x16x32_bf16 v[124:127], v[132:135], v[148:151], v[124:127]
	v_mfma_f32_16x16x32_bf16 v[120:123], v[140:143], v[148:151], v[120:123]
	v_mfma_f32_16x16x32_bf16 v[108:111], v[132:135], v[156:159], v[108:111]
	v_mfma_f32_16x16x32_bf16 v[104:107], v[140:143], v[156:159], v[104:107]
	v_mfma_f32_16x16x32_bf16 v[92:95], v[132:135], v[164:167], v[92:95]
	v_mfma_f32_16x16x32_bf16 v[88:91], v[140:143], v[164:167], v[88:91]
	v_mfma_f32_16x16x32_bf16 v[76:79], v[132:135], v[172:175], v[76:79]
	v_mfma_f32_16x16x32_bf16 v[72:75], v[140:143], v[172:175], v[72:75]
	s_barrier
	s_add_i32 s69, s66, s51
	s_add_u32 s90, s42, 0x80
	s_addc_u32 s91, s43, 0
	s_mov_b32 m0, s69
	ds_read_b128 v[192:195], v210
	ds_read_b128 v[196:199], v210 offset:1024
	ds_read_b128 v[200:203], v210 offset:2048
	ds_read_b128 v[212:215], v210 offset:3072
	global_load_lds_dwordx4 v178, s[42:43]
	s_add_i32 m0, s69, 0x2000
	s_nop 0
	global_load_lds_dwordx4 v182, s[42:43]
	s_barrier
	s_waitcnt lgkmcnt(0)
	v_mfma_f32_16x16x32_bf16 v[116:119], v[192:195], v[144:147], v[116:119]
	v_mfma_f32_16x16x32_bf16 v[112:115], v[200:203], v[144:147], v[112:115]
	v_mfma_f32_16x16x32_bf16 v[100:103], v[192:195], v[152:155], v[100:103]
	v_mfma_f32_16x16x32_bf16 v[96:99], v[200:203], v[152:155], v[96:99]
	v_mfma_f32_16x16x32_bf16 v[84:87], v[192:195], v[160:163], v[84:87]
	v_mfma_f32_16x16x32_bf16 v[80:83], v[200:203], v[160:163], v[80:83]
	v_mfma_f32_16x16x32_bf16 v[68:71], v[192:195], v[168:171], v[68:71]
	v_mfma_f32_16x16x32_bf16 v[64:67], v[200:203], v[168:171], v[64:67]
	v_mfma_f32_16x16x32_bf16 v[116:119], v[196:199], v[148:151], v[116:119]
	v_mfma_f32_16x16x32_bf16 v[112:115], v[212:215], v[148:151], v[112:115]
	v_mfma_f32_16x16x32_bf16 v[100:103], v[196:199], v[156:159], v[100:103]
	v_mfma_f32_16x16x32_bf16 v[96:99], v[212:215], v[156:159], v[96:99]
	v_mfma_f32_16x16x32_bf16 v[84:87], v[196:199], v[164:167], v[84:87]
	v_mfma_f32_16x16x32_bf16 v[80:83], v[212:215], v[164:167], v[80:83]
	v_mfma_f32_16x16x32_bf16 v[68:71], v[196:199], v[172:175], v[68:71]
	v_mfma_f32_16x16x32_bf16 v[64:67], v[212:215], v[172:175], v[64:67]
	s_barrier
	s_mov_b32 m0, s54
	s_add_u32 s92, s44, 0x80
	s_addc_u32 s93, s45, 0
	ds_read_b128 v[144:147], v209 offset:16384
	ds_read_b128 v[148:151], v209 offset:17408
	ds_read_b128 v[152:155], v209 offset:18432
	ds_read_b128 v[156:159], v209 offset:19456
	ds_read_b128 v[160:163], v209 offset:20480
	ds_read_b128 v[164:167], v209 offset:21504
	ds_read_b128 v[168:171], v209 offset:22528
	ds_read_b128 v[172:175], v209 offset:23552
	global_load_lds_dwordx4 v176, s[44:45]
	s_mov_b32 m0, s55
	s_nop 0
	global_load_lds_dwordx4 v180, s[44:45]
	s_barrier
; #define PG8_STAGE(bufoff, gbase, voff) do { _Pragma("unroll") for (int _i = 0; _i < 2; ++_i) \
;         __builtin_amdgcn_global_load_lds((const unsigned*)((const char*)(gbase) + (voff)[_i]), (LAS unsigned*)(lds + (bufoff) + ldsw + _i * 8192), 16, 0, 0); } while (0)
; #define PG8_LDA(dst, b, h) do { _Pragma("unroll") for (int m = 0; m < 4; ++m) _Pragma("unroll") for (int k = 0; k < 2; ++k) dst[m][k] = *(const LAS bf16x8*)(lds + PG8_SA(b, h) + aoff + m * 2048 + k * 1024); } while (0)
; #define PG8_LDB(dst, b, h) do { _Pragma("unroll") for (int n = 0; n < 2; ++n) _Pragma("unroll") for (int k = 0; k < 2; ++k) dst[n][k] = *(const LAS bf16x8*)(lds + PG8_SB(b, h) + boff + n * 2048 + k * 1024); } while (0)
; #define PG8_MMA(ai, bj, At, Bt) do { __builtin_amdgcn_s_setprio(1); _Pragma("unroll") for (int m = 0; m < 4; ++m) _Pragma("unroll") for (int n = 0; n < 2; ++n) _Pragma("unroll") for (int k = 0; k < 2; ++k) \
;         acc[ai][bj][m][n] = __builtin_amdgcn_mfma_f32_16x16x32_bf16(Bt[n][k], At[m][k], acc[ai][bj][m][n], 0, 0, 0); __builtin_amdgcn_s_setprio(0); } while (0)
; #define PG8_WAIT_V(n) asm volatile("s_waitcnt vmcnt(" #n ")" ::: "memory")
; #define PG8_WAIT_L(n) asm volatile("s_waitcnt lgkmcnt(" #n ")" ::: "memory")
; #define PG8_BAR __builtin_amdgcn_s_barrier()
; #define PG8_SCHED __builtin_amdgcn_sched_barrier(0)
; template <class Epi, class Ptrs>
; __device__ __forceinline__ void gemm_phase(LAS unsigned char* lds, const int K, const StaticOrder& S, const Ptrs& P, const Epi& E) {
;     ...
;             PG8_BAR; PG8_WAIT_L(0); PG8_MMA(1, 0, At, B0); PG8_BAR; PG8_SCHED;
;             PG8_STAGE(PG8_SB(0, 1), b2 + hstep, voffB);
;             PG8_WAIT_V(6); PG8_BAR; PG8_MMA(1, 1, At, B1); PG8_BAR;
;             PG8_LDB(B0, 1, 0); PG8_SCHED; PG8_LDA(At, 1, 0); PG8_STAGE(PG8_SA(0, 1), a2 + hstep, voffA);
;             PG8_WAIT_L(8); PG8_BAR; PG8_WAIT_L(0); PG8_MMA(0, 0, At, B0); PG8_BAR; PG8_SCHED;
;             PG8_LDB(B1, 1, 1); PG8_STAGE(PG8_SB(1, 0), b3, voffB);
;             PG8_BAR; PG8_WAIT_L(0); PG8_MMA(0, 1, At, B1); PG8_BAR;
	s_waitcnt lgkmcnt(0)
	v_mfma_f32_16x16x32_bf16 v[60:63], v[128:131], v[144:147], v[60:63]
	v_mfma_f32_16x16x32_bf16 v[56:59], v[136:139], v[144:147], v[56:59]
	v_mfma_f32_16x16x32_bf16 v[44:47], v[128:131], v[152:155], v[44:47]
	v_mfma_f32_16x16x32_bf16 v[40:43], v[136:139], v[152:155], v[40:43]
	v_mfma_f32_16x16x32_bf16 v[28:31], v[128:131], v[160:163], v[28:31]
	v_mfma_f32_16x16x32_bf16 v[24:27], v[136:139], v[160:163], v[24:27]
	v_mfma_f32_16x16x32_bf16 v[12:15], v[128:131], v[168:171], v[12:15]
	v_mfma_f32_16x16x32_bf16 v[8:11], v[136:139], v[168:171], v[8:11]
	v_mfma_f32_16x16x32_bf16 v[60:63], v[132:135], v[148:151], v[60:63]
	v_mfma_f32_16x16x32_bf16 v[56:59], v[140:143], v[148:151], v[56:59]
	v_mfma_f32_16x16x32_bf16 v[44:47], v[132:135], v[156:159], v[44:47]
	v_mfma_f32_16x16x32_bf16 v[40:43], v[140:143], v[156:159], v[40:43]
	v_mfma_f32_16x16x32_bf16 v[28:31], v[132:135], v[164:167], v[28:31]
	v_mfma_f32_16x16x32_bf16 v[24:27], v[140:143], v[164:167], v[24:27]
	v_mfma_f32_16x16x32_bf16 v[12:15], v[132:135], v[172:175], v[12:15]
	v_mfma_f32_16x16x32_bf16 v[8:11], v[140:143], v[172:175], v[8:11]
	s_barrier
	s_add_u32 s70, s42, 0x40000
	s_addc_u32 s71, s43, 0
	s_add_i32 s69, s67, s51
	s_mov_b32 m0, s69
	s_nop 0
	global_load_lds_dwordx4 v178, s[70:71]
	s_add_i32 m0, s69, 0x2000
	s_nop 0
	global_load_lds_dwordx4 v182, s[70:71]
	s_waitcnt vmcnt(6)
	s_barrier
	v_mfma_f32_16x16x32_bf16 v[52:55], v[192:195], v[144:147], v[52:55]
	v_mfma_f32_16x16x32_bf16 v[48:51], v[200:203], v[144:147], v[48:51]
	v_mfma_f32_16x16x32_bf16 v[36:39], v[192:195], v[152:155], v[36:39]
	v_mfma_f32_16x16x32_bf16 v[32:35], v[200:203], v[152:155], v[32:35]
	v_mfma_f32_16x16x32_bf16 v[20:23], v[192:195], v[160:163], v[20:23]
	v_mfma_f32_16x16x32_bf16 v[16:19], v[200:203], v[160:163], v[16:19]
	v_mfma_f32_16x16x32_bf16 v[4:7], v[192:195], v[168:171], v[4:7]
	v_mfma_f32_16x16x32_bf16 v[0:3], v[200:203], v[168:171], v[0:3]
	v_mfma_f32_16x16x32_bf16 v[52:55], v[196:199], v[148:151], v[52:55]
	v_mfma_f32_16x16x32_bf16 v[48:51], v[212:215], v[148:151], v[48:51]
	v_mfma_f32_16x16x32_bf16 v[36:39], v[196:199], v[156:159], v[36:39]
	v_mfma_f32_16x16x32_bf16 v[32:35], v[212:215], v[156:159], v[32:35]
	v_mfma_f32_16x16x32_bf16 v[20:23], v[196:199], v[164:167], v[20:23]
	v_mfma_f32_16x16x32_bf16 v[16:19], v[212:215], v[164:167], v[16:19]
	v_mfma_f32_16x16x32_bf16 v[4:7], v[196:199], v[172:175], v[4:7]
	v_mfma_f32_16x16x32_bf16 v[0:3], v[212:215], v[172:175], v[0:3]
	s_barrier
	s_add_i32 s69, 0, 0x18000
	ds_read_b128 v[128:131], v252
	ds_read_b128 v[132:135], v252 offset:1024
	ds_read_b128 v[136:139], v252 offset:2048
	ds_read_b128 v[140:143], v252 offset:3072
	s_add_u32 s44, s44, 0x40000
	s_addc_u32 s45, s45, 0
	s_mov_b32 m0, s56
	ds_read_b128 v[144:147], v209 offset:32768
	ds_read_b128 v[148:151], v209 offset:33792
	ds_read_b128 v[152:155], v209 offset:34816
	ds_read_b128 v[156:159], v209 offset:35840
	ds_read_b128 v[160:163], v209 offset:36864
	ds_read_b128 v[164:167], v209 offset:37888
	ds_read_b128 v[168:171], v209 offset:38912
	ds_read_b128 v[172:175], v209 offset:39936
	global_load_lds_dwordx4 v176, s[44:45]
	s_mov_b32 m0, s57
	s_nop 0
	global_load_lds_dwordx4 v180, s[44:45]
	s_waitcnt lgkmcnt(8)
	s_barrier
	s_waitcnt lgkmcnt(0)
	v_mfma_f32_16x16x32_bf16 v[124:127], v[128:131], v[144:147], v[124:127]
	v_mfma_f32_16x16x32_bf16 v[120:123], v[136:139], v[144:147], v[120:123]
	v_mfma_f32_16x16x32_bf16 v[108:111], v[128:131], v[152:155], v[108:111]
	v_mfma_f32_16x16x32_bf16 v[104:107], v[136:139], v[152:155], v[104:107]
	v_mfma_f32_16x16x32_bf16 v[92:95], v[128:131], v[160:163], v[92:95]
	v_mfma_f32_16x16x32_bf16 v[88:91], v[136:139], v[160:163], v[88:91]
	v_mfma_f32_16x16x32_bf16 v[76:79], v[128:131], v[168:171], v[76:79]
	v_mfma_f32_16x16x32_bf16 v[72:75], v[136:139], v[168:171], v[72:75]
	v_mfma_f32_16x16x32_bf16 v[124:127], v[132:135], v[148:151], v[124:127]
	v_mfma_f32_16x16x32_bf16 v[120:123], v[140:143], v[148:151], v[120:123]
	v_mfma_f32_16x16x32_bf16 v[108:111], v[132:135], v[156:159], v[108:111]
	v_mfma_f32_16x16x32_bf16 v[104:107], v[140:143], v[156:159], v[104:107]
	v_mfma_f32_16x16x32_bf16 v[92:95], v[132:135], v[164:167], v[92:95]
	v_mfma_f32_16x16x32_bf16 v[88:91], v[140:143], v[164:167], v[88:91]
	v_mfma_f32_16x16x32_bf16 v[76:79], v[132:135], v[172:175], v[76:79]
	v_mfma_f32_16x16x32_bf16 v[72:75], v[140:143], v[172:175], v[72:75]
	s_barrier
	s_add_i32 s44, 0, 0x1c000
	s_add_i32 s45, s69, s51
	s_mov_b32 m0, s45
	ds_read_b128 v[192:195], v253
	ds_read_b128 v[196:199], v253 offset:1024
	ds_read_b128 v[200:203], v253 offset:2048
	ds_read_b128 v[212:215], v253 offset:3072
	global_load_lds_dwordx4 v178, s[90:91]
	s_add_i32 m0, s45, 0x2000
	s_nop 0
	global_load_lds_dwordx4 v182, s[90:91]
	s_barrier
	s_waitcnt lgkmcnt(0)
	v_mfma_f32_16x16x32_bf16 v[116:119], v[192:195], v[144:147], v[116:119]
	v_mfma_f32_16x16x32_bf16 v[112:115], v[200:203], v[144:147], v[112:115]
	v_mfma_f32_16x16x32_bf16 v[100:103], v[192:195], v[152:155], v[100:103]
	v_mfma_f32_16x16x32_bf16 v[96:99], v[200:203], v[152:155], v[96:99]
	v_mfma_f32_16x16x32_bf16 v[84:87], v[192:195], v[160:163], v[84:87]
	v_mfma_f32_16x16x32_bf16 v[80:83], v[200:203], v[160:163], v[80:83]
	v_mfma_f32_16x16x32_bf16 v[68:71], v[192:195], v[168:171], v[68:71]
	v_mfma_f32_16x16x32_bf16 v[64:67], v[200:203], v[168:171], v[64:67]
	v_mfma_f32_16x16x32_bf16 v[116:119], v[196:199], v[148:151], v[116:119]
	v_mfma_f32_16x16x32_bf16 v[112:115], v[212:215], v[148:151], v[112:115]
	v_mfma_f32_16x16x32_bf16 v[100:103], v[196:199], v[156:159], v[100:103]
	v_mfma_f32_16x16x32_bf16 v[96:99], v[212:215], v[156:159], v[96:99]
	v_mfma_f32_16x16x32_bf16 v[84:87], v[196:199], v[164:167], v[84:87]
	v_mfma_f32_16x16x32_bf16 v[80:83], v[212:215], v[164:167], v[80:83]
	v_mfma_f32_16x16x32_bf16 v[68:71], v[196:199], v[172:175], v[68:71]
	v_mfma_f32_16x16x32_bf16 v[64:67], v[212:215], v[172:175], v[64:67]
	s_barrier
; #define PG8_STAGE(bufoff, gbase, voff) do { _Pragma("unroll") for (int _i = 0; _i < 2; ++_i) \
;         __builtin_amdgcn_global_load_lds((const unsigned*)((const char*)(gbase) + (voff)[_i]), (LAS unsigned*)(lds + (bufoff) + ldsw + _i * 8192), 16, 0, 0); } while (0)
; #define PG8_LDA(dst, b, h) do { _Pragma("unroll") for (int m = 0; m < 4; ++m) _Pragma("unroll") for (int k = 0; k < 2; ++k) dst[m][k] = *(const LAS bf16x8*)(lds + PG8_SA(b, h) + aoff + m * 2048 + k * 1024); } while (0)
; #define PG8_MMA(ai, bj, At, Bt) do { __builtin_amdgcn_s_setprio(1); _Pragma("unroll") for (int m = 0; m < 4; ++m) _Pragma("unroll") for (int n = 0; n < 2; ++n) _Pragma("unroll") for (int k = 0; k < 2; ++k) \
;         acc[ai][bj][m][n] = __builtin_amdgcn_mfma_f32_16x16x32_bf16(Bt[n][k], At[m][k], acc[ai][bj][m][n], 0, 0, 0); __builtin_amdgcn_s_setprio(0); } while (0)
; #define PG8_WAIT_V(n) asm volatile("s_waitcnt vmcnt(" #n ")" ::: "memory")
; #define PG8_WAIT_L(n) asm volatile("s_waitcnt lgkmcnt(" #n ")" ::: "memory")
; #define PG8_BAR __builtin_amdgcn_s_barrier()
; #define PG8_SCHED __builtin_amdgcn_sched_barrier(0)
; template <class Epi, class Ptrs>
; __device__ __forceinline__ void gemm_phase(LAS unsigned char* lds, const int K, const StaticOrder& S, const Ptrs& P, const Epi& E) {
;     ...
;             PG8_LDA(At, 1, 1); PG8_STAGE(PG8_SA(1, 0), a3, voffA);
;             PG8_BAR; PG8_WAIT_L(0); PG8_MMA(1, 0, At, B0); PG8_BAR; PG8_SCHED;
;             PG8_STAGE(PG8_SB(1, 1), b3 + hstep, voffB);
;             PG8_WAIT_V(6); PG8_BAR; PG8_MMA(1, 1, At, B1); PG8_BAR;
	s_mov_b32 m0, s63
	ds_read_b128 v[144:147], v209 offset:49152
	ds_read_b128 v[148:151], v209 offset:50176
	ds_read_b128 v[152:155], v209 offset:51200
	ds_read_b128 v[156:159], v209 offset:52224
	ds_read_b128 v[160:163], v209 offset:53248
	ds_read_b128 v[164:167], v209 offset:54272
	ds_read_b128 v[168:171], v209 offset:55296
	ds_read_b128 v[172:175], v209 offset:56320
	global_load_lds_dwordx4 v176, s[92:93]
	s_mov_b32 m0, s64
	s_nop 0
	global_load_lds_dwordx4 v180, s[92:93]
	s_barrier
	s_waitcnt lgkmcnt(0)
	v_mfma_f32_16x16x32_bf16 v[60:63], v[128:131], v[144:147], v[60:63]
	v_mfma_f32_16x16x32_bf16 v[56:59], v[136:139], v[144:147], v[56:59]
	v_mfma_f32_16x16x32_bf16 v[44:47], v[128:131], v[152:155], v[44:47]
	v_mfma_f32_16x16x32_bf16 v[40:43], v[136:139], v[152:155], v[40:43]
	v_mfma_f32_16x16x32_bf16 v[28:31], v[128:131], v[160:163], v[28:31]
	v_mfma_f32_16x16x32_bf16 v[24:27], v[136:139], v[160:163], v[24:27]
	v_mfma_f32_16x16x32_bf16 v[12:15], v[128:131], v[168:171], v[12:15]
	v_mfma_f32_16x16x32_bf16 v[8:11], v[136:139], v[168:171], v[8:11]
	v_mfma_f32_16x16x32_bf16 v[60:63], v[132:135], v[148:151], v[60:63]
	v_mfma_f32_16x16x32_bf16 v[56:59], v[140:143], v[148:151], v[56:59]
	v_mfma_f32_16x16x32_bf16 v[44:47], v[132:135], v[156:159], v[44:47]
	v_mfma_f32_16x16x32_bf16 v[40:43], v[140:143], v[156:159], v[40:43]
	v_mfma_f32_16x16x32_bf16 v[28:31], v[132:135], v[164:167], v[28:31]
	v_mfma_f32_16x16x32_bf16 v[24:27], v[140:143], v[164:167], v[24:27]
	v_mfma_f32_16x16x32_bf16 v[12:15], v[132:135], v[172:175], v[12:15]
	v_mfma_f32_16x16x32_bf16 v[8:11], v[140:143], v[172:175], v[8:11]
	s_barrier
	s_add_u32 s42, s42, 0x40080
	s_addc_u32 s43, s43, 0
	s_add_i32 s44, s44, s51
	s_mov_b32 m0, s44
	s_nop 0
	global_load_lds_dwordx4 v178, s[42:43]
	s_add_i32 m0, s44, 0x2000
	s_nop 0
	global_load_lds_dwordx4 v182, s[42:43]
	s_waitcnt vmcnt(6)
	s_barrier
	v_mfma_f32_16x16x32_bf16 v[52:55], v[192:195], v[144:147], v[52:55]
	v_mfma_f32_16x16x32_bf16 v[48:51], v[200:203], v[144:147], v[48:51]
	v_mfma_f32_16x16x32_bf16 v[36:39], v[192:195], v[152:155], v[36:39]
	v_mfma_f32_16x16x32_bf16 v[32:35], v[200:203], v[152:155], v[32:35]
	v_mfma_f32_16x16x32_bf16 v[20:23], v[192:195], v[160:163], v[20:23]
	v_mfma_f32_16x16x32_bf16 v[16:19], v[200:203], v[160:163], v[16:19]
	v_mfma_f32_16x16x32_bf16 v[4:7], v[192:195], v[168:171], v[4:7]
	v_mfma_f32_16x16x32_bf16 v[0:3], v[200:203], v[168:171], v[0:3]
	v_mfma_f32_16x16x32_bf16 v[52:55], v[196:199], v[148:151], v[52:55]
	v_mfma_f32_16x16x32_bf16 v[48:51], v[212:215], v[148:151], v[48:51]
	v_mfma_f32_16x16x32_bf16 v[36:39], v[196:199], v[156:159], v[36:39]
	v_mfma_f32_16x16x32_bf16 v[32:35], v[212:215], v[156:159], v[32:35]
	v_mfma_f32_16x16x32_bf16 v[20:23], v[196:199], v[164:167], v[20:23]
	v_mfma_f32_16x16x32_bf16 v[16:19], v[212:215], v[164:167], v[16:19]
	v_mfma_f32_16x16x32_bf16 v[4:7], v[196:199], v[172:175], v[4:7]
	v_mfma_f32_16x16x32_bf16 v[0:3], v[212:215], v[172:175], v[0:3]
	s_barrier
	s_add_i32 s41, s41, 2
	s_add_u32 s38, s38, 0x100
	s_addc_u32 s39, s39, 0
	s_add_u32 s21, s21, 0x100
	s_addc_u32 s23, s23, 0
	s_cmp_gt_u32 s41, 13
	s_cbranch_scc0 .LBB0_353
; __device__ __forceinline__ unsigned cvt_pk_bf16(float lo, float hi) { unsigned r; asm volatile("v_cvt_pk_bf16_f32 %0, %1, %2" : "=v"(r) : "v"(lo), "v"(hi)); return r; }
; __device__ __forceinline__ float x16_sum(float x) { auto s = __builtin_amdgcn_permlane16_swap(__float_as_uint(x), __float_as_uint(x), false, false); return __uint_as_float(s[0]) + __uint_as_float(s[1]); }
; __device__ __forceinline__ float x32_sum(float x) { auto s = __builtin_amdgcn_permlane32_swap(__float_as_uint(x), __float_as_uint(x), false, false); return __uint_as_float(s[0]) + __uint_as_float(s[1]); }
;     __device__ __forceinline__ void operator()(const f32x4 (&acc)[2][2][4][2], const Unit& u, int ui, int wr, int wc, int fr, int fq) const {
;         const int row0 = u.pm * 256 + wr * 64 + fr, col0 = u.pn * 256 + wc * 32 + 8 * fq;
;         const float* xb0 = (u.pm * 256 < MP) ? xp : xs - (size_t)MP * DM;
; #pragma unroll
;         for (int ai = 0; ai < 2; ++ai) {
;             f32x4 xv[4][2][2];
; #pragma unroll
;             for (int m = 0; m < 4; ++m)
; #pragma unroll
;                 for (int bj = 0; bj < 2; ++bj) { const float* p = xb0 + (size_t)(row0 + ai * 128 + m * 16) * DM + col0 + bj * 128; xv[m][bj][0] = *(const f32x4*)p; xv[m][bj][1] = *(const f32x4*)(p + 4); }
; #pragma unroll
;             for (int m = 0; m < 4; ++m) { const int row = row0 + ai * 128 + m * 16; const size_t off = (size_t)row * DM + col0; float ss = 0.f;
; #pragma unroll
;                 for (int bj = 0; bj < 2; ++bj) {
;                     const f32x4 v0 = acc[ai][bj][m][0] + xv[m][bj][0], v1 = acc[ai][bj][m][1] + xv[m][bj][1];
;                     u32x4 w; w.x = cvt_pk_bf16(v0[0], v0[1]); w.y = cvt_pk_bf16(v0[2], v0[3]); w.z = cvt_pk_bf16(v1[0], v1[1]); w.w = cvt_pk_bf16(v1[2], v1[3]);
;                     *(u32x4*)(xb + off + bj * 128) = w;
;                     ss += (v0[0] * v0[0] + v0[1] * v0[1]) + (v0[2] * v0[2] + v0[3] * v0[3]) + (v1[0] * v1[0] + v1[1] * v1[1]) + (v1[2] * v1[2] + v1[3] * v1[3]); }
;                 ss = x32_sum(x16_sum(ss));
;                 if (fq == 0) part[(size_t)row * 16 + u.pn * 4 + wc] = ss; }
	s_cmpk_lt_i32 s40, 0x80
	v_lshl_add_u32 v194, s40, 8, v204
	v_lshl_or_b32 v192, s12, 8, v206
	s_cselect_b32 s21, s37, s61
	s_cselect_b32 s23, s36, s60
	v_mov_b32_e32 v128, s23
	v_mov_b32_e32 v129, s21
	v_ashrrev_i32_e32 v193, 31, v192
	v_ashrrev_i32_e32 v195, 31, v194
	v_lshl_add_u64 v[196:197], v[192:193], 2, v[128:129]
	v_lshlrev_b64 v[128:129], 12, v[194:195]
	v_or_b32_e32 v202, 16, v194
	v_or_b32_e32 v200, 32, v194
	v_or_b32_e32 v198, 48, v194
	v_lshl_add_u64 v[128:129], v[196:197], 0, v[128:129]
	v_ashrrev_i32_e32 v203, 31, v202
	v_ashrrev_i32_e32 v201, 31, v200
	v_ashrrev_i32_e32 v199, 31, v198
	global_load_dwordx4 v[212:215], v[128:129], off
	global_load_dwordx4 v[216:219], v[128:129], off offset:16
	global_load_dwordx4 v[220:223], v[128:129], off offset:512
	global_load_dwordx4 v[224:227], v[128:129], off offset:528
	v_lshlrev_b64 v[128:129], 12, v[202:203]
	v_lshlrev_b64 v[130:131], 12, v[200:201]
	v_lshlrev_b64 v[132:133], 12, v[198:199]
	v_lshl_add_u64 v[128:129], v[196:197], 0, v[128:129]
	v_lshl_add_u64 v[130:131], v[196:197], 0, v[130:131]
	v_lshl_add_u64 v[132:133], v[196:197], 0, v[132:133]
	global_load_dwordx4 v[168:171], v[128:129], off offset:16
	global_load_dwordx4 v[172:175], v[128:129], off
	global_load_dwordx4 v[160:163], v[128:129], off offset:528
	global_load_dwordx4 v[164:167], v[128:129], off offset:512
	global_load_dwordx4 v[152:155], v[130:131], off offset:16
	global_load_dwordx4 v[156:159], v[130:131], off
	global_load_dwordx4 v[144:147], v[130:131], off offset:528
	global_load_dwordx4 v[148:151], v[130:131], off offset:512
	global_load_dwordx4 v[136:139], v[132:133], off offset:16
	global_load_dwordx4 v[140:143], v[132:133], off
	s_nop 0
	global_load_dwordx4 v[128:131], v[132:133], off offset:528
	s_nop 0
	global_load_dwordx4 v[132:135], v[132:133], off offset:512
	v_lshlrev_b64 v[228:229], 11, v[194:195]
	v_lshl_add_u64 v[228:229], s[14:15], 0, v[228:229]
	v_lshl_add_u64 v[228:229], v[192:193], 1, v[228:229]
	s_lshl_b32 s38, s12, 2
	s_ashr_i32 s39, s38, 31
	s_waitcnt vmcnt(0)
	v_pk_add_f32 v[126:127], v[126:127], v[214:215]
	v_pk_add_f32 v[124:125], v[124:125], v[212:213]
	v_pk_add_f32 v[118:119], v[118:119], v[222:223]
	v_pk_add_f32 v[116:117], v[116:117], v[220:221]
	v_pk_add_f32 v[120:121], v[120:121], v[216:217]
	v_pk_add_f32 v[214:215], v[112:113], v[224:225]
	v_cvt_pk_bf16_f32 v112, v124, v125
	v_cvt_pk_bf16_f32 v113, v126, v127
	v_mul_f32_e32 v125, v125, v125
	v_mul_f32_e32 v127, v127, v127
	v_mul_f32_e32 v211, v117, v117
	v_mul_f32_e32 v216, v119, v119
	v_pk_add_f32 v[122:123], v[122:123], v[218:219]
	v_pk_add_f32 v[212:213], v[114:115], v[226:227]
	v_cvt_pk_bf16_f32 v114, v120, v121
	v_cvt_pk_bf16_f32 v115, v122, v123
	v_mul_f32_e32 v121, v121, v121
	v_mul_f32_e32 v217, v215, v215
	global_store_dwordx4 v[228:229], v[112:115], off
	v_fmac_f32_e32 v125, v124, v124
	v_fmac_f32_e32 v127, v126, v126
	v_cvt_pk_bf16_f32 v112, v116, v117
	v_fmac_f32_e32 v211, v116, v116
	v_fmac_f32_e32 v216, v118, v118
	v_mul_f32_e32 v123, v123, v123
	v_mul_f32_e32 v218, v213, v213
	v_fmac_f32_e32 v121, v120, v120
	v_cvt_pk_bf16_f32 v113, v118, v119
	v_cvt_pk_bf16_f32 v114, v214, v215
	v_cvt_pk_bf16_f32 v115, v212, v213
	v_fmac_f32_e32 v217, v214, v214
	v_add_f32_e32 v116, v125, v127
	global_store_dwordx4 v[228:229], v[112:115], off offset:256
	v_fmac_f32_e32 v123, v122, v122
	v_fmac_f32_e32 v218, v212, v212
	v_add_f32_e32 v112, v211, v216
	v_add_f32_e32 v113, v116, v121
	v_add_f32_e32 v112, v112, v217
	v_add_f32_e32 v113, v123, v113
	v_add_f32_e32 v112, v218, v112
	v_add_f32_e32 v112, v113, v112
	v_mov_b32_e32 v113, v112
	s_nop 1
	v_permlane16_swap_b32_e32 v112, v113
	v_add_f32_e32 v112, v112, v113
	v_mov_b32_e32 v113, v112
	s_nop 1
	v_permlane32_swap_b32_e32 v112, v113
	s_and_saveexec_b64 s[40:41], s[6:7]
	s_cbranch_execz .LBB0_356
	v_lshlrev_b64 v[114:115], 6, v[194:195]
	v_lshl_add_u64 v[114:115], s[16:17], 0, v[114:115]
	v_lshl_add_u64 v[114:115], s[38:39], 2, v[114:115]
	s_lshl_b32 s12, s62, 2
	v_lshl_add_u64 v[114:115], v[114:115], 0, s[12:13]
	v_add_f32_e32 v112, v112, v113
	global_store_dword v[114:115], v112, off

; #define PG8_STAGE(bufoff, gbase, voff) do { _Pragma("unroll") for (int _i = 0; _i < 2; ++_i) \
;         __builtin_amdgcn_global_load_lds((const unsigned*)((const char*)(gbase) + (voff)[_i]), (LAS unsigned*)(lds + (bufoff) + ldsw + _i * 8192), 16, 0, 0); } while (0)
; #define PG8_LDA(dst, b, h) do { _Pragma("unroll") for (int m = 0; m < 4; ++m) _Pragma("unroll") for (int k = 0; k < 2; ++k) dst[m][k] = *(const LAS bf16x8*)(lds + PG8_SA(b, h) + aoff + m * 2048 + k * 1024); } while (0)
; #define PG8_LDB(dst, b, h) do { _Pragma("unroll") for (int n = 0; n < 2; ++n) _Pragma("unroll") for (int k = 0; k < 2; ++k) dst[n][k] = *(const LAS bf16x8*)(lds + PG8_SB(b, h) + boff + n * 2048 + k * 1024); } while (0)
; #define PG8_MMA(ai, bj, At, Bt) do { __builtin_amdgcn_s_setprio(1); _Pragma("unroll") for (int m = 0; m < 4; ++m) _Pragma("unroll") for (int n = 0; n < 2; ++n) _Pragma("unroll") for (int k = 0; k < 2; ++k) \
;         acc[ai][bj][m][n] = __builtin_amdgcn_mfma_f32_16x16x32_bf16(Bt[n][k], At[m][k], acc[ai][bj][m][n], 0, 0, 0); __builtin_amdgcn_s_setprio(0); } while (0)
; #define PG8_WAIT_V(n) asm volatile("s_waitcnt vmcnt(" #n ")" ::: "memory")
; #define PG8_WAIT_L(n) asm volatile("s_waitcnt lgkmcnt(" #n ")" ::: "memory")
; template <class Epi, class Ptrs>
; __device__ __forceinline__ void gemm_phase(LAS unsigned char* lds, const int K, const StaticOrder& S, const Ptrs& P, const Epi& E) {
;     ...
;         for (int t = 0; t < nt; t += 2) {
;             const bool last = (t == nt - 2);
;             const char* a1 = cA + (size_t)(t + 1) * kstep;
;             const char* a2 = last ? nA : cA + (size_t)(t + 2) * kstep; const char* b2 = last ? nB : cB + (size_t)(t + 2) * kstep;
;             const char* a3 = a2 + kstep; const char* b3 = b2 + kstep;
;             PG8_LDB(B0, 0, 0); PG8_SCHED; PG8_LDA(At, 0, 0); PG8_STAGE(PG8_SA(1, 1), a1 + hstep, voffA);
;             PG8_WAIT_L(8); PG8_BAR; PG8_WAIT_L(0); PG8_MMA(0, 0, At, B0); PG8_BAR; PG8_SCHED;
;             PG8_LDB(B1, 0, 1); PG8_STAGE(PG8_SB(0, 0), b2, voffB);
;             PG8_BAR; PG8_WAIT_L(0); PG8_MMA(0, 1, At, B1); PG8_BAR;
;             PG8_LDA(At, 0, 1); PG8_STAGE(PG8_SA(0, 0), a2, voffA);
;             PG8_BAR; PG8_WAIT_L(0); PG8_MMA(1, 0, At, B0); PG8_BAR; PG8_SCHED;
;             PG8_STAGE(PG8_SB(0, 1), b2 + hstep, voffB);
;             PG8_WAIT_V(6); PG8_BAR; PG8_MMA(1, 1, At, B1); PG8_BAR;
.LBB0_432:
	s_add_u32 s40, s40, 0x40080
	s_addc_u32 s41, s41, 0
	s_add_u32 s23, s42, 0x100
	s_addc_u32 s25, s43, 0
	s_mov_b32 s70, -2
	v_add_u32_e32 v252, 0x18000, v147
	v_add_u32_e32 v253, 0x1c000, v147
	ds_read_b128 v[152:155], v149
	ds_read_b128 v[156:159], v149 offset:1024
	ds_read_b128 v[160:163], v149 offset:2048
	ds_read_b128 v[164:167], v149 offset:3072
	s_add_u32 s42, s40, 0xfffc0080
	s_addc_u32 s43, s41, -1
	s_cmp_eq_u32 s70, 12
	s_cselect_b32 s45, s1, s43
	s_cselect_b32 s44, s0, s42
	s_cselect_b32 s43, s37, s25
	s_cselect_b32 s42, s36, s23
	s_add_i32 m0, s39, 0xc000
	ds_read_b128 v[168:171], v150
	ds_read_b128 v[172:175], v150 offset:1024
	ds_read_b128 v[176:179], v150 offset:2048
	ds_read_b128 v[180:183], v150 offset:3072
	ds_read_b128 v[184:187], v150 offset:4096
	ds_read_b128 v[188:191], v150 offset:5120
	ds_read_b128 v[192:195], v150 offset:6144
	ds_read_b128 v[196:199], v150 offset:7168
	global_load_lds_dwordx4 v136, s[40:41]
	s_add_i32 m0, s39, 0xe000
	s_nop 0
	global_load_lds_dwordx4 v138, s[40:41]
	s_waitcnt lgkmcnt(8)
	s_barrier
	s_waitcnt lgkmcnt(0)
	v_mfma_f32_16x16x32_bf16 v[124:127], v[152:155], v[168:171], 0
	v_mfma_f32_16x16x32_bf16 v[120:123], v[160:163], v[168:171], 0
	v_mfma_f32_16x16x32_bf16 v[108:111], v[152:155], v[176:179], 0
	v_mfma_f32_16x16x32_bf16 v[104:107], v[160:163], v[176:179], 0
	v_mfma_f32_16x16x32_bf16 v[92:95], v[152:155], v[184:187], 0
	v_mfma_f32_16x16x32_bf16 v[88:91], v[160:163], v[184:187], 0
	v_mfma_f32_16x16x32_bf16 v[76:79], v[152:155], v[192:195], 0
	v_mfma_f32_16x16x32_bf16 v[72:75], v[160:163], v[192:195], 0
	v_mfma_f32_16x16x32_bf16 v[124:127], v[156:159], v[172:175], v[124:127]
	v_mfma_f32_16x16x32_bf16 v[120:123], v[164:167], v[172:175], v[120:123]
	v_mfma_f32_16x16x32_bf16 v[108:111], v[156:159], v[180:183], v[108:111]
	v_mfma_f32_16x16x32_bf16 v[104:107], v[164:167], v[180:183], v[104:107]
	v_mfma_f32_16x16x32_bf16 v[92:95], v[156:159], v[188:191], v[92:95]
	v_mfma_f32_16x16x32_bf16 v[88:91], v[164:167], v[188:191], v[88:91]
	v_mfma_f32_16x16x32_bf16 v[76:79], v[156:159], v[196:199], v[76:79]
	v_mfma_f32_16x16x32_bf16 v[72:75], v[164:167], v[196:199], v[72:75]
	s_barrier
	s_add_i32 s71, s63, s51
	s_add_u32 s76, s42, 0x80
	s_addc_u32 s77, s43, 0
	s_mov_b32 m0, s71
	ds_read_b128 v[200:203], v151
	ds_read_b128 v[204:207], v151 offset:1024
	ds_read_b128 v[210:213], v151 offset:2048
	ds_read_b128 v[214:217], v151 offset:3072
	global_load_lds_dwordx4 v130, s[42:43]
	s_add_i32 m0, s71, 0x2000
	s_nop 0
	global_load_lds_dwordx4 v134, s[42:43]
	s_barrier
	s_waitcnt lgkmcnt(0)
	v_mfma_f32_16x16x32_bf16 v[116:119], v[200:203], v[168:171], 0
	v_mfma_f32_16x16x32_bf16 v[112:115], v[210:213], v[168:171], 0
	v_mfma_f32_16x16x32_bf16 v[100:103], v[200:203], v[176:179], 0
	v_mfma_f32_16x16x32_bf16 v[96:99], v[210:213], v[176:179], 0
	v_mfma_f32_16x16x32_bf16 v[84:87], v[200:203], v[184:187], 0
	v_mfma_f32_16x16x32_bf16 v[80:83], v[210:213], v[184:187], 0
	v_mfma_f32_16x16x32_bf16 v[68:71], v[200:203], v[192:195], 0
	v_mfma_f32_16x16x32_bf16 v[64:67], v[210:213], v[192:195], 0
	v_mfma_f32_16x16x32_bf16 v[116:119], v[204:207], v[172:175], v[116:119]
	v_mfma_f32_16x16x32_bf16 v[112:115], v[214:217], v[172:175], v[112:115]
	v_mfma_f32_16x16x32_bf16 v[100:103], v[204:207], v[180:183], v[100:103]
	v_mfma_f32_16x16x32_bf16 v[96:99], v[214:217], v[180:183], v[96:99]
	v_mfma_f32_16x16x32_bf16 v[84:87], v[204:207], v[188:191], v[84:87]
	v_mfma_f32_16x16x32_bf16 v[80:83], v[214:217], v[188:191], v[80:83]
	v_mfma_f32_16x16x32_bf16 v[68:71], v[204:207], v[196:199], v[68:71]
	v_mfma_f32_16x16x32_bf16 v[64:67], v[214:217], v[196:199], v[64:67]
	s_barrier
	s_mov_b32 m0, s39
	s_add_u32 s78, s44, 0x80
	s_addc_u32 s79, s45, 0
	ds_read_b128 v[168:171], v150 offset:16384
	ds_read_b128 v[172:175], v150 offset:17408
	ds_read_b128 v[176:179], v150 offset:18432
	ds_read_b128 v[180:183], v150 offset:19456
	ds_read_b128 v[184:187], v150 offset:20480
	ds_read_b128 v[188:191], v150 offset:21504
	ds_read_b128 v[192:195], v150 offset:22528
	ds_read_b128 v[196:199], v150 offset:23552
	global_load_lds_dwordx4 v128, s[44:45]
	s_mov_b32 m0, s56
	s_nop 0
	global_load_lds_dwordx4 v132, s[44:45]
	s_barrier
	s_waitcnt lgkmcnt(0)
	v_mfma_f32_16x16x32_bf16 v[60:63], v[152:155], v[168:171], 0
	v_mfma_f32_16x16x32_bf16 v[56:59], v[160:163], v[168:171], 0
	v_mfma_f32_16x16x32_bf16 v[44:47], v[152:155], v[176:179], 0
	v_mfma_f32_16x16x32_bf16 v[40:43], v[160:163], v[176:179], 0
	v_mfma_f32_16x16x32_bf16 v[28:31], v[152:155], v[184:187], 0
	v_mfma_f32_16x16x32_bf16 v[24:27], v[160:163], v[184:187], 0
	v_mfma_f32_16x16x32_bf16 v[12:15], v[152:155], v[192:195], 0
	v_mfma_f32_16x16x32_bf16 v[8:11], v[160:163], v[192:195], 0
	v_mfma_f32_16x16x32_bf16 v[60:63], v[156:159], v[172:175], v[60:63]
	v_mfma_f32_16x16x32_bf16 v[56:59], v[164:167], v[172:175], v[56:59]
	v_mfma_f32_16x16x32_bf16 v[44:47], v[156:159], v[180:183], v[44:47]
	v_mfma_f32_16x16x32_bf16 v[40:43], v[164:167], v[180:183], v[40:43]
	v_mfma_f32_16x16x32_bf16 v[28:31], v[156:159], v[188:191], v[28:31]
	v_mfma_f32_16x16x32_bf16 v[24:27], v[164:167], v[188:191], v[24:27]
	v_mfma_f32_16x16x32_bf16 v[12:15], v[156:159], v[196:199], v[12:15]
	v_mfma_f32_16x16x32_bf16 v[8:11], v[164:167], v[196:199], v[8:11]
	s_barrier
	s_add_u32 s72, s42, 0x40000
	s_addc_u32 s73, s43, 0
	s_add_i32 s71, s64, s51
	s_mov_b32 m0, s71
	s_nop 0
	global_load_lds_dwordx4 v130, s[72:73]
	s_add_i32 m0, s71, 0x2000
	s_nop 0
	global_load_lds_dwordx4 v134, s[72:73]
	s_waitcnt vmcnt(6)
	s_barrier
; #define PG8_STAGE(bufoff, gbase, voff) do { _Pragma("unroll") for (int _i = 0; _i < 2; ++_i) \
;         __builtin_amdgcn_global_load_lds((const unsigned*)((const char*)(gbase) + (voff)[_i]), (LAS unsigned*)(lds + (bufoff) + ldsw + _i * 8192), 16, 0, 0); } while (0)
; #define PG8_LDA(dst, b, h) do { _Pragma("unroll") for (int m = 0; m < 4; ++m) _Pragma("unroll") for (int k = 0; k < 2; ++k) dst[m][k] = *(const LAS bf16x8*)(lds + PG8_SA(b, h) + aoff + m * 2048 + k * 1024); } while (0)
; #define PG8_LDB(dst, b, h) do { _Pragma("unroll") for (int n = 0; n < 2; ++n) _Pragma("unroll") for (int k = 0; k < 2; ++k) dst[n][k] = *(const LAS bf16x8*)(lds + PG8_SB(b, h) + boff + n * 2048 + k * 1024); } while (0)
; #define PG8_MMA(ai, bj, At, Bt) do { __builtin_amdgcn_s_setprio(1); _Pragma("unroll") for (int m = 0; m < 4; ++m) _Pragma("unroll") for (int n = 0; n < 2; ++n) _Pragma("unroll") for (int k = 0; k < 2; ++k) \
;         acc[ai][bj][m][n] = __builtin_amdgcn_mfma_f32_16x16x32_bf16(Bt[n][k], At[m][k], acc[ai][bj][m][n], 0, 0, 0); __builtin_amdgcn_s_setprio(0); } while (0)
; #define PG8_WAIT_V(n) asm volatile("s_waitcnt vmcnt(" #n ")" ::: "memory")
; #define PG8_WAIT_L(n) asm volatile("s_waitcnt lgkmcnt(" #n ")" ::: "memory")
; #define PG8_BAR __builtin_amdgcn_s_barrier()
; #define PG8_SCHED __builtin_amdgcn_sched_barrier(0)
; template <class Epi, class Ptrs>
; __device__ __forceinline__ void gemm_phase(LAS unsigned char* lds, const int K, const StaticOrder& S, const Ptrs& P, const Epi& E) {
;     ...
;             PG8_WAIT_V(6); PG8_BAR; PG8_MMA(1, 1, At, B1); PG8_BAR;
;             PG8_LDB(B0, 1, 0); PG8_SCHED; PG8_LDA(At, 1, 0); PG8_STAGE(PG8_SA(0, 1), a2 + hstep, voffA);
;             PG8_WAIT_L(8); PG8_BAR; PG8_WAIT_L(0); PG8_MMA(0, 0, At, B0); PG8_BAR; PG8_SCHED;
;             PG8_LDB(B1, 1, 1); PG8_STAGE(PG8_SB(1, 0), b3, voffB);
;             PG8_BAR; PG8_WAIT_L(0); PG8_MMA(0, 1, At, B1); PG8_BAR;
;             PG8_LDA(At, 1, 1); PG8_STAGE(PG8_SA(1, 0), a3, voffA);
;             PG8_BAR; PG8_WAIT_L(0); PG8_MMA(1, 0, At, B0); PG8_BAR; PG8_SCHED;
	v_mfma_f32_16x16x32_bf16 v[52:55], v[200:203], v[168:171], 0
	v_mfma_f32_16x16x32_bf16 v[48:51], v[210:213], v[168:171], 0
	v_mfma_f32_16x16x32_bf16 v[36:39], v[200:203], v[176:179], 0
	v_mfma_f32_16x16x32_bf16 v[32:35], v[210:213], v[176:179], 0
	v_mfma_f32_16x16x32_bf16 v[20:23], v[200:203], v[184:187], 0
	v_mfma_f32_16x16x32_bf16 v[16:19], v[210:213], v[184:187], 0
	v_mfma_f32_16x16x32_bf16 v[4:7], v[200:203], v[192:195], 0
	v_mfma_f32_16x16x32_bf16 v[0:3], v[210:213], v[192:195], 0
	v_mfma_f32_16x16x32_bf16 v[52:55], v[204:207], v[172:175], v[52:55]
	v_mfma_f32_16x16x32_bf16 v[48:51], v[214:217], v[172:175], v[48:51]
	v_mfma_f32_16x16x32_bf16 v[36:39], v[204:207], v[180:183], v[36:39]
	v_mfma_f32_16x16x32_bf16 v[32:35], v[214:217], v[180:183], v[32:35]
	v_mfma_f32_16x16x32_bf16 v[20:23], v[204:207], v[188:191], v[20:23]
	v_mfma_f32_16x16x32_bf16 v[16:19], v[214:217], v[188:191], v[16:19]
	v_mfma_f32_16x16x32_bf16 v[4:7], v[204:207], v[196:199], v[4:7]
	v_mfma_f32_16x16x32_bf16 v[0:3], v[214:217], v[196:199], v[0:3]
	s_barrier
	s_add_i32 s71, 0, 0x18000
	ds_read_b128 v[152:155], v252
	ds_read_b128 v[156:159], v252 offset:1024
	ds_read_b128 v[160:163], v252 offset:2048
	ds_read_b128 v[164:167], v252 offset:3072
	s_add_u32 s44, s44, 0x40000
	s_addc_u32 s45, s45, 0
	s_mov_b32 m0, s57
	ds_read_b128 v[168:171], v150 offset:32768
	ds_read_b128 v[172:175], v150 offset:33792
	ds_read_b128 v[176:179], v150 offset:34816
	ds_read_b128 v[180:183], v150 offset:35840
	ds_read_b128 v[184:187], v150 offset:36864
	ds_read_b128 v[188:191], v150 offset:37888
	ds_read_b128 v[192:195], v150 offset:38912
	ds_read_b128 v[196:199], v150 offset:39936
	global_load_lds_dwordx4 v128, s[44:45]
	s_mov_b32 m0, s58
	s_nop 0
	global_load_lds_dwordx4 v132, s[44:45]
	s_waitcnt lgkmcnt(8)
	s_barrier
	s_waitcnt lgkmcnt(0)
	v_mfma_f32_16x16x32_bf16 v[124:127], v[152:155], v[168:171], v[124:127]
	v_mfma_f32_16x16x32_bf16 v[120:123], v[160:163], v[168:171], v[120:123]
	v_mfma_f32_16x16x32_bf16 v[108:111], v[152:155], v[176:179], v[108:111]
	v_mfma_f32_16x16x32_bf16 v[104:107], v[160:163], v[176:179], v[104:107]
	v_mfma_f32_16x16x32_bf16 v[92:95], v[152:155], v[184:187], v[92:95]
	v_mfma_f32_16x16x32_bf16 v[88:91], v[160:163], v[184:187], v[88:91]
	v_mfma_f32_16x16x32_bf16 v[76:79], v[152:155], v[192:195], v[76:79]
	v_mfma_f32_16x16x32_bf16 v[72:75], v[160:163], v[192:195], v[72:75]
	v_mfma_f32_16x16x32_bf16 v[124:127], v[156:159], v[172:175], v[124:127]
	v_mfma_f32_16x16x32_bf16 v[120:123], v[164:167], v[172:175], v[120:123]
	v_mfma_f32_16x16x32_bf16 v[108:111], v[156:159], v[180:183], v[108:111]
	v_mfma_f32_16x16x32_bf16 v[104:107], v[164:167], v[180:183], v[104:107]
	v_mfma_f32_16x16x32_bf16 v[92:95], v[156:159], v[188:191], v[92:95]
	v_mfma_f32_16x16x32_bf16 v[88:91], v[164:167], v[188:191], v[88:91]
	v_mfma_f32_16x16x32_bf16 v[76:79], v[156:159], v[196:199], v[76:79]
	v_mfma_f32_16x16x32_bf16 v[72:75], v[164:167], v[196:199], v[72:75]
	s_barrier
	s_add_i32 s44, 0, 0x1c000
	s_add_i32 s45, s71, s51
	s_mov_b32 m0, s45
	ds_read_b128 v[200:203], v253
	ds_read_b128 v[204:207], v253 offset:1024
	ds_read_b128 v[210:213], v253 offset:2048
	ds_read_b128 v[214:217], v253 offset:3072
	global_load_lds_dwordx4 v130, s[76:77]
	s_add_i32 m0, s45, 0x2000
	s_nop 0
	global_load_lds_dwordx4 v134, s[76:77]
	s_barrier
	s_waitcnt lgkmcnt(0)
	v_mfma_f32_16x16x32_bf16 v[116:119], v[200:203], v[168:171], v[116:119]
	v_mfma_f32_16x16x32_bf16 v[112:115], v[210:213], v[168:171], v[112:115]
	v_mfma_f32_16x16x32_bf16 v[100:103], v[200:203], v[176:179], v[100:103]
	v_mfma_f32_16x16x32_bf16 v[96:99], v[210:213], v[176:179], v[96:99]
	v_mfma_f32_16x16x32_bf16 v[84:87], v[200:203], v[184:187], v[84:87]
	v_mfma_f32_16x16x32_bf16 v[80:83], v[210:213], v[184:187], v[80:83]
	v_mfma_f32_16x16x32_bf16 v[68:71], v[200:203], v[192:195], v[68:71]
	v_mfma_f32_16x16x32_bf16 v[64:67], v[210:213], v[192:195], v[64:67]
	v_mfma_f32_16x16x32_bf16 v[116:119], v[204:207], v[172:175], v[116:119]
	v_mfma_f32_16x16x32_bf16 v[112:115], v[214:217], v[172:175], v[112:115]
	v_mfma_f32_16x16x32_bf16 v[100:103], v[204:207], v[180:183], v[100:103]
	v_mfma_f32_16x16x32_bf16 v[96:99], v[214:217], v[180:183], v[96:99]
	v_mfma_f32_16x16x32_bf16 v[84:87], v[204:207], v[188:191], v[84:87]
	v_mfma_f32_16x16x32_bf16 v[80:83], v[214:217], v[188:191], v[80:83]
	v_mfma_f32_16x16x32_bf16 v[68:71], v[204:207], v[196:199], v[68:71]
	v_mfma_f32_16x16x32_bf16 v[64:67], v[214:217], v[196:199], v[64:67]
	s_barrier
	s_mov_b32 m0, s61
	ds_read_b128 v[168:171], v150 offset:49152
	ds_read_b128 v[172:175], v150 offset:50176
	ds_read_b128 v[176:179], v150 offset:51200
	ds_read_b128 v[180:183], v150 offset:52224
	ds_read_b128 v[184:187], v150 offset:53248
	ds_read_b128 v[188:191], v150 offset:54272
	ds_read_b128 v[192:195], v150 offset:55296
	ds_read_b128 v[196:199], v150 offset:56320
	global_load_lds_dwordx4 v128, s[78:79]
	s_mov_b32 m0, s62
	s_nop 0
	global_load_lds_dwordx4 v132, s[78:79]
	s_barrier
	s_waitcnt lgkmcnt(0)
	v_mfma_f32_16x16x32_bf16 v[60:63], v[152:155], v[168:171], v[60:63]
	v_mfma_f32_16x16x32_bf16 v[56:59], v[160:163], v[168:171], v[56:59]
	v_mfma_f32_16x16x32_bf16 v[44:47], v[152:155], v[176:179], v[44:47]
	v_mfma_f32_16x16x32_bf16 v[40:43], v[160:163], v[176:179], v[40:43]
	v_mfma_f32_16x16x32_bf16 v[28:31], v[152:155], v[184:187], v[28:31]
	v_mfma_f32_16x16x32_bf16 v[24:27], v[160:163], v[184:187], v[24:27]
	v_mfma_f32_16x16x32_bf16 v[12:15], v[152:155], v[192:195], v[12:15]
	v_mfma_f32_16x16x32_bf16 v[8:11], v[160:163], v[192:195], v[8:11]
	v_mfma_f32_16x16x32_bf16 v[60:63], v[156:159], v[172:175], v[60:63]
	v_mfma_f32_16x16x32_bf16 v[56:59], v[164:167], v[172:175], v[56:59]
	v_mfma_f32_16x16x32_bf16 v[44:47], v[156:159], v[180:183], v[44:47]
	v_mfma_f32_16x16x32_bf16 v[40:43], v[164:167], v[180:183], v[40:43]
	v_mfma_f32_16x16x32_bf16 v[28:31], v[156:159], v[188:191], v[28:31]
	v_mfma_f32_16x16x32_bf16 v[24:27], v[164:167], v[188:191], v[24:27]
	v_mfma_f32_16x16x32_bf16 v[12:15], v[156:159], v[196:199], v[12:15]
	v_mfma_f32_16x16x32_bf16 v[8:11], v[164:167], v[196:199], v[8:11]
	s_barrier
; #define PG8_STAGE(bufoff, gbase, voff) do { _Pragma("unroll") for (int _i = 0; _i < 2; ++_i) \
;         __builtin_amdgcn_global_load_lds((const unsigned*)((const char*)(gbase) + (voff)[_i]), (LAS unsigned*)(lds + (bufoff) + ldsw + _i * 8192), 16, 0, 0); } while (0)
; #define PG8_LDA(dst, b, h) do { _Pragma("unroll") for (int m = 0; m < 4; ++m) _Pragma("unroll") for (int k = 0; k < 2; ++k) dst[m][k] = *(const LAS bf16x8*)(lds + PG8_SA(b, h) + aoff + m * 2048 + k * 1024); } while (0)
; #define PG8_WAIT_V(n) asm volatile("s_waitcnt vmcnt(" #n ")" ::: "memory")
; #define PG8_BAR __builtin_amdgcn_s_barrier()
; template <class Epi, class Ptrs>
; __device__ __forceinline__ void gemm_phase(LAS unsigned char* lds, const int K, const StaticOrder& S, const Ptrs& P, const Epi& E) {
;     ...
;         for (int t = 0; t < nt; t += 2) {
;             const bool last = (t == nt - 2);
;             const char* a1 = cA + (size_t)(t + 1) * kstep;
;             const char* a2 = last ? nA : cA + (size_t)(t + 2) * kstep; const char* b2 = last ? nB : cB + (size_t)(t + 2) * kstep;
;             const char* a3 = a2 + kstep; const char* b3 = b2 + kstep;
;             PG8_LDB(B0, 0, 0); PG8_SCHED; PG8_LDA(At, 0, 0); PG8_STAGE(PG8_SA(1, 1), a1 + hstep, voffA);
;             PG8_WAIT_L(8); PG8_BAR; PG8_WAIT_L(0); PG8_MMA(0, 0, At, B0); PG8_BAR; PG8_SCHED;
;             PG8_LDB(B1, 0, 1); PG8_STAGE(PG8_SB(0, 0), b2, voffB);
;             PG8_BAR; PG8_WAIT_L(0); PG8_MMA(0, 1, At, B1); PG8_BAR;
;             PG8_LDA(At, 0, 1); PG8_STAGE(PG8_SA(0, 0), a2, voffA);
;             PG8_BAR; PG8_WAIT_L(0); PG8_MMA(1, 0, At, B0); PG8_BAR; PG8_SCHED;
;             PG8_STAGE(PG8_SB(0, 1), b2 + hstep, voffB);
;             PG8_WAIT_V(6); PG8_BAR; PG8_MMA(1, 1, At, B1); PG8_BAR;
;             PG8_LDB(B0, 1, 0); PG8_SCHED; PG8_LDA(At, 1, 0); PG8_STAGE(PG8_SA(0, 1), a2 + hstep, voffA);
;             PG8_WAIT_L(8); PG8_BAR; PG8_WAIT_L(0); PG8_MMA(0, 0, At, B0); PG8_BAR; PG8_SCHED;
;             PG8_LDB(B1, 1, 1); PG8_STAGE(PG8_SB(1, 0), b3, voffB);
;             PG8_BAR; PG8_WAIT_L(0); PG8_MMA(0, 1, At, B1); PG8_BAR;
;             PG8_LDA(At, 1, 1); PG8_STAGE(PG8_SA(1, 0), a3, voffA);
;             PG8_BAR; PG8_WAIT_L(0); PG8_MMA(1, 0, At, B0); PG8_BAR; PG8_SCHED;
;             PG8_STAGE(PG8_SB(1, 1), b3 + hstep, voffB);
;             PG8_WAIT_V(6); PG8_BAR; PG8_MMA(1, 1, At, B1); PG8_BAR;
	s_add_u32 s42, s42, 0x40080
	s_addc_u32 s43, s43, 0
	s_add_i32 s44, s44, s51
	s_mov_b32 m0, s44
	s_nop 0
	global_load_lds_dwordx4 v130, s[42:43]
	s_add_i32 m0, s44, 0x2000
	s_nop 0
	global_load_lds_dwordx4 v134, s[42:43]
	s_waitcnt vmcnt(6)
	s_barrier
	v_mfma_f32_16x16x32_bf16 v[52:55], v[200:203], v[168:171], v[52:55]
	v_mfma_f32_16x16x32_bf16 v[48:51], v[210:213], v[168:171], v[48:51]
	v_mfma_f32_16x16x32_bf16 v[36:39], v[200:203], v[176:179], v[36:39]
	v_mfma_f32_16x16x32_bf16 v[32:35], v[210:213], v[176:179], v[32:35]
	v_mfma_f32_16x16x32_bf16 v[20:23], v[200:203], v[184:187], v[20:23]
	v_mfma_f32_16x16x32_bf16 v[16:19], v[210:213], v[184:187], v[16:19]
	v_mfma_f32_16x16x32_bf16 v[4:7], v[200:203], v[192:195], v[4:7]
	v_mfma_f32_16x16x32_bf16 v[0:3], v[210:213], v[192:195], v[0:3]
	v_mfma_f32_16x16x32_bf16 v[52:55], v[204:207], v[172:175], v[52:55]
	v_mfma_f32_16x16x32_bf16 v[48:51], v[214:217], v[172:175], v[48:51]
	v_mfma_f32_16x16x32_bf16 v[36:39], v[204:207], v[180:183], v[36:39]
	v_mfma_f32_16x16x32_bf16 v[32:35], v[214:217], v[180:183], v[32:35]
	v_mfma_f32_16x16x32_bf16 v[20:23], v[204:207], v[188:191], v[20:23]
	v_mfma_f32_16x16x32_bf16 v[16:19], v[214:217], v[188:191], v[16:19]
	v_mfma_f32_16x16x32_bf16 v[4:7], v[204:207], v[196:199], v[4:7]
	v_mfma_f32_16x16x32_bf16 v[0:3], v[214:217], v[196:199], v[0:3]
	s_barrier
	s_add_i32 s70, s70, 2
	s_add_u32 s40, s40, 0x100
	s_addc_u32 s41, s41, 0
	s_add_u32 s23, s23, 0x100
	s_addc_u32 s25, s25, 0
	s_cmp_gt_u32 s70, 13
.LBB0_433:
	ds_read_b128 v[152:155], v149
	ds_read_b128 v[156:159], v149 offset:1024
	ds_read_b128 v[160:163], v149 offset:2048
	ds_read_b128 v[164:167], v149 offset:3072
	s_add_u32 s42, s40, 0xfffc0080
	s_addc_u32 s43, s41, -1
	s_cmp_eq_u32 s70, 12
	s_cselect_b32 s45, s1, s43
	s_cselect_b32 s44, s0, s42
	s_cselect_b32 s43, s37, s25
	s_cselect_b32 s42, s36, s23
	s_add_i32 m0, s39, 0xc000
	ds_read_b128 v[168:171], v150
	ds_read_b128 v[172:175], v150 offset:1024
	ds_read_b128 v[176:179], v150 offset:2048
	ds_read_b128 v[180:183], v150 offset:3072
	ds_read_b128 v[184:187], v150 offset:4096
	ds_read_b128 v[188:191], v150 offset:5120
	ds_read_b128 v[192:195], v150 offset:6144
	ds_read_b128 v[196:199], v150 offset:7168
	global_load_lds_dwordx4 v136, s[40:41]
	s_add_i32 m0, s39, 0xe000
	s_nop 0
	global_load_lds_dwordx4 v138, s[40:41]
	s_waitcnt lgkmcnt(8)
	s_barrier
	s_waitcnt lgkmcnt(0)
	v_mfma_f32_16x16x32_bf16 v[124:127], v[152:155], v[168:171], v[124:127]
	v_mfma_f32_16x16x32_bf16 v[120:123], v[160:163], v[168:171], v[120:123]
	v_mfma_f32_16x16x32_bf16 v[108:111], v[152:155], v[176:179], v[108:111]
	v_mfma_f32_16x16x32_bf16 v[104:107], v[160:163], v[176:179], v[104:107]
	v_mfma_f32_16x16x32_bf16 v[92:95], v[152:155], v[184:187], v[92:95]
	v_mfma_f32_16x16x32_bf16 v[88:91], v[160:163], v[184:187], v[88:91]
	v_mfma_f32_16x16x32_bf16 v[76:79], v[152:155], v[192:195], v[76:79]
	v_mfma_f32_16x16x32_bf16 v[72:75], v[160:163], v[192:195], v[72:75]
	v_mfma_f32_16x16x32_bf16 v[124:127], v[156:159], v[172:175], v[124:127]
	v_mfma_f32_16x16x32_bf16 v[120:123], v[164:167], v[172:175], v[120:123]
	v_mfma_f32_16x16x32_bf16 v[108:111], v[156:159], v[180:183], v[108:111]
	v_mfma_f32_16x16x32_bf16 v[104:107], v[164:167], v[180:183], v[104:107]
	v_mfma_f32_16x16x32_bf16 v[92:95], v[156:159], v[188:191], v[92:95]
	v_mfma_f32_16x16x32_bf16 v[88:91], v[164:167], v[188:191], v[88:91]
	v_mfma_f32_16x16x32_bf16 v[76:79], v[156:159], v[196:199], v[76:79]
	v_mfma_f32_16x16x32_bf16 v[72:75], v[164:167], v[196:199], v[72:75]
	s_barrier
	s_add_i32 s71, s63, s51
	s_add_u32 s76, s42, 0x80
	s_addc_u32 s77, s43, 0
	s_mov_b32 m0, s71
	ds_read_b128 v[200:203], v151
	ds_read_b128 v[204:207], v151 offset:1024
	ds_read_b128 v[210:213], v151 offset:2048
	ds_read_b128 v[214:217], v151 offset:3072
	global_load_lds_dwordx4 v130, s[42:43]
	s_add_i32 m0, s71, 0x2000
	s_nop 0
	global_load_lds_dwordx4 v134, s[42:43]
	s_barrier
	s_waitcnt lgkmcnt(0)
	v_mfma_f32_16x16x32_bf16 v[116:119], v[200:203], v[168:171], v[116:119]
	v_mfma_f32_16x16x32_bf16 v[112:115], v[210:213], v[168:171], v[112:115]
	v_mfma_f32_16x16x32_bf16 v[100:103], v[200:203], v[176:179], v[100:103]
	v_mfma_f32_16x16x32_bf16 v[96:99], v[210:213], v[176:179], v[96:99]
	v_mfma_f32_16x16x32_bf16 v[84:87], v[200:203], v[184:187], v[84:87]
	v_mfma_f32_16x16x32_bf16 v[80:83], v[210:213], v[184:187], v[80:83]
	v_mfma_f32_16x16x32_bf16 v[68:71], v[200:203], v[192:195], v[68:71]
	v_mfma_f32_16x16x32_bf16 v[64:67], v[210:213], v[192:195], v[64:67]
	v_mfma_f32_16x16x32_bf16 v[116:119], v[204:207], v[172:175], v[116:119]
	v_mfma_f32_16x16x32_bf16 v[112:115], v[214:217], v[172:175], v[112:115]
	v_mfma_f32_16x16x32_bf16 v[100:103], v[204:207], v[180:183], v[100:103]
	v_mfma_f32_16x16x32_bf16 v[96:99], v[214:217], v[180:183], v[96:99]
	v_mfma_f32_16x16x32_bf16 v[84:87], v[204:207], v[188:191], v[84:87]
	v_mfma_f32_16x16x32_bf16 v[80:83], v[214:217], v[188:191], v[80:83]
	v_mfma_f32_16x16x32_bf16 v[68:71], v[204:207], v[196:199], v[68:71]
	v_mfma_f32_16x16x32_bf16 v[64:67], v[214:217], v[196:199], v[64:67]
	s_barrier
	s_mov_b32 m0, s39
	s_add_u32 s78, s44, 0x80
	s_addc_u32 s79, s45, 0
	ds_read_b128 v[168:171], v150 offset:16384
	ds_read_b128 v[172:175], v150 offset:17408
	ds_read_b128 v[176:179], v150 offset:18432
	ds_read_b128 v[180:183], v150 offset:19456
	ds_read_b128 v[184:187], v150 offset:20480
	ds_read_b128 v[188:191], v150 offset:21504
	ds_read_b128 v[192:195], v150 offset:22528
	ds_read_b128 v[196:199], v150 offset:23552
	global_load_lds_dwordx4 v128, s[44:45]
	s_mov_b32 m0, s56
	s_nop 0
	global_load_lds_dwordx4 v132, s[44:45]
	s_barrier
; #define PG8_STAGE(bufoff, gbase, voff) do { _Pragma("unroll") for (int _i = 0; _i < 2; ++_i) \
;         __builtin_amdgcn_global_load_lds((const unsigned*)((const char*)(gbase) + (voff)[_i]), (LAS unsigned*)(lds + (bufoff) + ldsw + _i * 8192), 16, 0, 0); } while (0)
; #define PG8_LDA(dst, b, h) do { _Pragma("unroll") for (int m = 0; m < 4; ++m) _Pragma("unroll") for (int k = 0; k < 2; ++k) dst[m][k] = *(const LAS bf16x8*)(lds + PG8_SA(b, h) + aoff + m * 2048 + k * 1024); } while (0)
; #define PG8_LDB(dst, b, h) do { _Pragma("unroll") for (int n = 0; n < 2; ++n) _Pragma("unroll") for (int k = 0; k < 2; ++k) dst[n][k] = *(const LAS bf16x8*)(lds + PG8_SB(b, h) + boff + n * 2048 + k * 1024); } while (0)
; #define PG8_WAIT_V(n) asm volatile("s_waitcnt vmcnt(" #n ")" ::: "memory")
; #define PG8_WAIT_L(n) asm volatile("s_waitcnt lgkmcnt(" #n ")" ::: "memory")
; #define PG8_BAR __builtin_amdgcn_s_barrier()
; #define PG8_SCHED __builtin_amdgcn_sched_barrier(0)
; template <class Epi, class Ptrs>
; __device__ __forceinline__ void gemm_phase(LAS unsigned char* lds, const int K, const StaticOrder& S, const Ptrs& P, const Epi& E) {
;     ...
;             PG8_LDB(B0, 0, 0); PG8_SCHED; PG8_LDA(At, 0, 0); PG8_STAGE(PG8_SA(1, 1), a1 + hstep, voffA);
;             PG8_WAIT_L(8); PG8_BAR; PG8_WAIT_L(0); PG8_MMA(0, 0, At, B0); PG8_BAR; PG8_SCHED;
;             PG8_LDB(B1, 0, 1); PG8_STAGE(PG8_SB(0, 0), b2, voffB);
;             PG8_BAR; PG8_WAIT_L(0); PG8_MMA(0, 1, At, B1); PG8_BAR;
;             PG8_LDA(At, 0, 1); PG8_STAGE(PG8_SA(0, 0), a2, voffA);
;             PG8_BAR; PG8_WAIT_L(0); PG8_MMA(1, 0, At, B0); PG8_BAR; PG8_SCHED;
;             PG8_STAGE(PG8_SB(0, 1), b2 + hstep, voffB);
;             PG8_WAIT_V(6); PG8_BAR; PG8_MMA(1, 1, At, B1); PG8_BAR;
;             PG8_LDB(B0, 1, 0); PG8_SCHED; PG8_LDA(At, 1, 0); PG8_STAGE(PG8_SA(0, 1), a2 + hstep, voffA);
;             PG8_WAIT_L(8); PG8_BAR; PG8_WAIT_L(0); PG8_MMA(0, 0, At, B0); PG8_BAR; PG8_SCHED;
;             PG8_LDB(B1, 1, 1); PG8_STAGE(PG8_SB(1, 0), b3, voffB);
;             PG8_BAR; PG8_WAIT_L(0); PG8_MMA(0, 1, At, B1); PG8_BAR;
;             PG8_LDA(At, 1, 1); PG8_STAGE(PG8_SA(1, 0), a3, voffA);
;             PG8_BAR; PG8_WAIT_L(0); PG8_MMA(1, 0, At, B0); PG8_BAR; PG8_SCHED;
;             PG8_STAGE(PG8_SB(1, 1), b3 + hstep, voffB);
;             PG8_WAIT_V(6); PG8_BAR; PG8_MMA(1, 1, At, B1); PG8_BAR;
	s_waitcnt lgkmcnt(0)
	v_mfma_f32_16x16x32_bf16 v[60:63], v[152:155], v[168:171], v[60:63]
	v_mfma_f32_16x16x32_bf16 v[56:59], v[160:163], v[168:171], v[56:59]
	v_mfma_f32_16x16x32_bf16 v[44:47], v[152:155], v[176:179], v[44:47]
	v_mfma_f32_16x16x32_bf16 v[40:43], v[160:163], v[176:179], v[40:43]
	v_mfma_f32_16x16x32_bf16 v[28:31], v[152:155], v[184:187], v[28:31]
	v_mfma_f32_16x16x32_bf16 v[24:27], v[160:163], v[184:187], v[24:27]
	v_mfma_f32_16x16x32_bf16 v[12:15], v[152:155], v[192:195], v[12:15]
	v_mfma_f32_16x16x32_bf16 v[8:11], v[160:163], v[192:195], v[8:11]
	v_mfma_f32_16x16x32_bf16 v[60:63], v[156:159], v[172:175], v[60:63]
	v_mfma_f32_16x16x32_bf16 v[56:59], v[164:167], v[172:175], v[56:59]
	v_mfma_f32_16x16x32_bf16 v[44:47], v[156:159], v[180:183], v[44:47]
	v_mfma_f32_16x16x32_bf16 v[40:43], v[164:167], v[180:183], v[40:43]
	v_mfma_f32_16x16x32_bf16 v[28:31], v[156:159], v[188:191], v[28:31]
	v_mfma_f32_16x16x32_bf16 v[24:27], v[164:167], v[188:191], v[24:27]
	v_mfma_f32_16x16x32_bf16 v[12:15], v[156:159], v[196:199], v[12:15]
	v_mfma_f32_16x16x32_bf16 v[8:11], v[164:167], v[196:199], v[8:11]
	s_barrier
	s_add_u32 s72, s42, 0x40000
	s_addc_u32 s73, s43, 0
	s_add_i32 s71, s64, s51
	s_mov_b32 m0, s71
	s_nop 0
	global_load_lds_dwordx4 v130, s[72:73]
	s_add_i32 m0, s71, 0x2000
	s_nop 0
	global_load_lds_dwordx4 v134, s[72:73]
	s_waitcnt vmcnt(6)
	s_barrier
	v_mfma_f32_16x16x32_bf16 v[52:55], v[200:203], v[168:171], v[52:55]
	v_mfma_f32_16x16x32_bf16 v[48:51], v[210:213], v[168:171], v[48:51]
	v_mfma_f32_16x16x32_bf16 v[36:39], v[200:203], v[176:179], v[36:39]
	v_mfma_f32_16x16x32_bf16 v[32:35], v[210:213], v[176:179], v[32:35]
	v_mfma_f32_16x16x32_bf16 v[20:23], v[200:203], v[184:187], v[20:23]
	v_mfma_f32_16x16x32_bf16 v[16:19], v[210:213], v[184:187], v[16:19]
	v_mfma_f32_16x16x32_bf16 v[4:7], v[200:203], v[192:195], v[4:7]
	v_mfma_f32_16x16x32_bf16 v[0:3], v[210:213], v[192:195], v[0:3]
	v_mfma_f32_16x16x32_bf16 v[52:55], v[204:207], v[172:175], v[52:55]
	v_mfma_f32_16x16x32_bf16 v[48:51], v[214:217], v[172:175], v[48:51]
	v_mfma_f32_16x16x32_bf16 v[36:39], v[204:207], v[180:183], v[36:39]
	v_mfma_f32_16x16x32_bf16 v[32:35], v[214:217], v[180:183], v[32:35]
	v_mfma_f32_16x16x32_bf16 v[20:23], v[204:207], v[188:191], v[20:23]
	v_mfma_f32_16x16x32_bf16 v[16:19], v[214:217], v[188:191], v[16:19]
	v_mfma_f32_16x16x32_bf16 v[4:7], v[204:207], v[196:199], v[4:7]
	v_mfma_f32_16x16x32_bf16 v[0:3], v[214:217], v[196:199], v[0:3]
	s_barrier
	s_add_i32 s71, 0, 0x18000
	ds_read_b128 v[152:155], v252
	ds_read_b128 v[156:159], v252 offset:1024
	ds_read_b128 v[160:163], v252 offset:2048
	ds_read_b128 v[164:167], v252 offset:3072
	s_add_u32 s44, s44, 0x40000
	s_addc_u32 s45, s45, 0
	s_mov_b32 m0, s57
	ds_read_b128 v[168:171], v150 offset:32768
	ds_read_b128 v[172:175], v150 offset:33792
	ds_read_b128 v[176:179], v150 offset:34816
	ds_read_b128 v[180:183], v150 offset:35840
	ds_read_b128 v[184:187], v150 offset:36864
	ds_read_b128 v[188:191], v150 offset:37888
	ds_read_b128 v[192:195], v150 offset:38912
	ds_read_b128 v[196:199], v150 offset:39936
	global_load_lds_dwordx4 v128, s[44:45]
	s_mov_b32 m0, s58
	s_nop 0
	global_load_lds_dwordx4 v132, s[44:45]
	s_waitcnt lgkmcnt(8)
	s_barrier
	s_waitcnt lgkmcnt(0)
	v_mfma_f32_16x16x32_bf16 v[124:127], v[152:155], v[168:171], v[124:127]
	v_mfma_f32_16x16x32_bf16 v[120:123], v[160:163], v[168:171], v[120:123]
	v_mfma_f32_16x16x32_bf16 v[108:111], v[152:155], v[176:179], v[108:111]
	v_mfma_f32_16x16x32_bf16 v[104:107], v[160:163], v[176:179], v[104:107]
	v_mfma_f32_16x16x32_bf16 v[92:95], v[152:155], v[184:187], v[92:95]
	v_mfma_f32_16x16x32_bf16 v[88:91], v[160:163], v[184:187], v[88:91]
	v_mfma_f32_16x16x32_bf16 v[76:79], v[152:155], v[192:195], v[76:79]
	v_mfma_f32_16x16x32_bf16 v[72:75], v[160:163], v[192:195], v[72:75]
	v_mfma_f32_16x16x32_bf16 v[124:127], v[156:159], v[172:175], v[124:127]
	v_mfma_f32_16x16x32_bf16 v[120:123], v[164:167], v[172:175], v[120:123]
	v_mfma_f32_16x16x32_bf16 v[108:111], v[156:159], v[180:183], v[108:111]
	v_mfma_f32_16x16x32_bf16 v[104:107], v[164:167], v[180:183], v[104:107]
	v_mfma_f32_16x16x32_bf16 v[92:95], v[156:159], v[188:191], v[92:95]
	v_mfma_f32_16x16x32_bf16 v[88:91], v[164:167], v[188:191], v[88:91]
	v_mfma_f32_16x16x32_bf16 v[76:79], v[156:159], v[196:199], v[76:79]
	v_mfma_f32_16x16x32_bf16 v[72:75], v[164:167], v[196:199], v[72:75]
	s_barrier
	s_add_i32 s44, 0, 0x1c000
	s_add_i32 s45, s71, s51
	s_mov_b32 m0, s45
	ds_read_b128 v[200:203], v253
	ds_read_b128 v[204:207], v253 offset:1024
	ds_read_b128 v[210:213], v253 offset:2048
	ds_read_b128 v[214:217], v253 offset:3072
	global_load_lds_dwordx4 v130, s[76:77]
	s_add_i32 m0, s45, 0x2000
	s_nop 0
	global_load_lds_dwordx4 v134, s[76:77]
	s_barrier
	s_waitcnt lgkmcnt(0)
	v_mfma_f32_16x16x32_bf16 v[116:119], v[200:203], v[168:171], v[116:119]
	v_mfma_f32_16x16x32_bf16 v[112:115], v[210:213], v[168:171], v[112:115]
	v_mfma_f32_16x16x32_bf16 v[100:103], v[200:203], v[176:179], v[100:103]
	v_mfma_f32_16x16x32_bf16 v[96:99], v[210:213], v[176:179], v[96:99]
	v_mfma_f32_16x16x32_bf16 v[84:87], v[200:203], v[184:187], v[84:87]
	v_mfma_f32_16x16x32_bf16 v[80:83], v[210:213], v[184:187], v[80:83]
	v_mfma_f32_16x16x32_bf16 v[68:71], v[200:203], v[192:195], v[68:71]
	v_mfma_f32_16x16x32_bf16 v[64:67], v[210:213], v[192:195], v[64:67]
	v_mfma_f32_16x16x32_bf16 v[116:119], v[204:207], v[172:175], v[116:119]
	v_mfma_f32_16x16x32_bf16 v[112:115], v[214:217], v[172:175], v[112:115]
	v_mfma_f32_16x16x32_bf16 v[100:103], v[204:207], v[180:183], v[100:103]
	v_mfma_f32_16x16x32_bf16 v[96:99], v[214:217], v[180:183], v[96:99]
	v_mfma_f32_16x16x32_bf16 v[84:87], v[204:207], v[188:191], v[84:87]
	v_mfma_f32_16x16x32_bf16 v[80:83], v[214:217], v[188:191], v[80:83]
	v_mfma_f32_16x16x32_bf16 v[68:71], v[204:207], v[196:199], v[68:71]
	v_mfma_f32_16x16x32_bf16 v[64:67], v[214:217], v[196:199], v[64:67]
	s_barrier
; __device__ __forceinline__ unsigned cvt_pk_bf16(float lo, float hi) { unsigned r; asm volatile("v_cvt_pk_bf16_f32 %0, %1, %2" : "=v"(r) : "v"(lo), "v"(hi)); return r; }
; #define PG8_STAGE(bufoff, gbase, voff) do { _Pragma("unroll") for (int _i = 0; _i < 2; ++_i) \
;         __builtin_amdgcn_global_load_lds((const unsigned*)((const char*)(gbase) + (voff)[_i]), (LAS unsigned*)(lds + (bufoff) + ldsw + _i * 8192), 16, 0, 0); } while (0)
; #define PG8_LDA(dst, b, h) do { _Pragma("unroll") for (int m = 0; m < 4; ++m) _Pragma("unroll") for (int k = 0; k < 2; ++k) dst[m][k] = *(const LAS bf16x8*)(lds + PG8_SA(b, h) + aoff + m * 2048 + k * 1024); } while (0)
; #define PG8_WAIT_V(n) asm volatile("s_waitcnt vmcnt(" #n ")" ::: "memory")
; #define PG8_WAIT_L(n) asm volatile("s_waitcnt lgkmcnt(" #n ")" ::: "memory")
; template <class Epi, class Ptrs>
; __device__ __forceinline__ void gemm_phase(LAS unsigned char* lds, const int K, const StaticOrder& S, const Ptrs& P, const Epi& E) {
;     ...
;             PG8_WAIT_L(8); PG8_BAR; PG8_WAIT_L(0); PG8_MMA(0, 0, At, B0); PG8_BAR; PG8_SCHED;
;             PG8_LDB(B1, 1, 1); PG8_STAGE(PG8_SB(1, 0), b3, voffB);
;             PG8_BAR; PG8_WAIT_L(0); PG8_MMA(0, 1, At, B1); PG8_BAR;
;             PG8_LDA(At, 1, 1); PG8_STAGE(PG8_SA(1, 0), a3, voffA);
;             PG8_BAR; PG8_WAIT_L(0); PG8_MMA(1, 0, At, B0); PG8_BAR; PG8_SCHED;
;             PG8_STAGE(PG8_SB(1, 1), b3 + hstep, voffB);
;             PG8_WAIT_V(6); PG8_BAR; PG8_MMA(1, 1, At, B1); PG8_BAR;
;         }
;         E(acc, cur, ui, wr, wc, fr, fq);
;     __device__ __forceinline__ void operator()(const f32x4 (&acc)[2][2][4][2], const Unit& u, int ui, int wr, int wc, int fr, int fq) const {
;     ...
;         for (int ai = 0; ai < 2; ++ai)
; #pragma unroll
;             for (int m = 0; m < 4; ++m) { bf16_t* rowp = hid + (size_t)(row0 + ai * 128 + m * 16) * DFF + col0;
; #pragma unroll
;                 for (int bj = 0; bj < 2; ++bj) { f32x4 v0 = acc[ai][bj][m][0], v1 = acc[ai][bj][m][1];
; #pragma unroll
;                     for (int j = 0; j < 4; ++j) { const float a = fmaxf(v0[j], 0.f), b = fmaxf(v1[j], 0.f); v0[j] = a * a; v1[j] = b * b; }
;                     u32x4 w; w.x = cvt_pk_bf16(v0[0], v0[1]); w.y = cvt_pk_bf16(v0[2], v0[3]); w.z = cvt_pk_bf16(v1[0], v1[1]); w.w = cvt_pk_bf16(v1[2], v1[3]);
;                     *(u32x4*)(rowp + bj * 128) = w; } }
	s_mov_b32 m0, s61
	ds_read_b128 v[168:171], v150 offset:49152
	ds_read_b128 v[172:175], v150 offset:50176
	ds_read_b128 v[176:179], v150 offset:51200
	ds_read_b128 v[180:183], v150 offset:52224
	ds_read_b128 v[184:187], v150 offset:53248
	ds_read_b128 v[188:191], v150 offset:54272
	ds_read_b128 v[192:195], v150 offset:55296
	ds_read_b128 v[196:199], v150 offset:56320
	global_load_lds_dwordx4 v128, s[78:79]
	s_mov_b32 m0, s62
	s_nop 0
	global_load_lds_dwordx4 v132, s[78:79]
	s_barrier
	s_waitcnt lgkmcnt(0)
	v_mfma_f32_16x16x32_bf16 v[60:63], v[152:155], v[168:171], v[60:63]
	v_mfma_f32_16x16x32_bf16 v[56:59], v[160:163], v[168:171], v[56:59]
	v_mfma_f32_16x16x32_bf16 v[44:47], v[152:155], v[176:179], v[44:47]
	v_mfma_f32_16x16x32_bf16 v[40:43], v[160:163], v[176:179], v[40:43]
	v_mfma_f32_16x16x32_bf16 v[28:31], v[152:155], v[184:187], v[28:31]
	v_mfma_f32_16x16x32_bf16 v[24:27], v[160:163], v[184:187], v[24:27]
	v_mfma_f32_16x16x32_bf16 v[12:15], v[152:155], v[192:195], v[12:15]
	v_mfma_f32_16x16x32_bf16 v[8:11], v[160:163], v[192:195], v[8:11]
	v_mfma_f32_16x16x32_bf16 v[60:63], v[156:159], v[172:175], v[60:63]
	v_mfma_f32_16x16x32_bf16 v[56:59], v[164:167], v[172:175], v[56:59]
	v_mfma_f32_16x16x32_bf16 v[44:47], v[156:159], v[180:183], v[44:47]
	v_mfma_f32_16x16x32_bf16 v[40:43], v[164:167], v[180:183], v[40:43]
	v_mfma_f32_16x16x32_bf16 v[28:31], v[156:159], v[188:191], v[28:31]
	v_mfma_f32_16x16x32_bf16 v[24:27], v[164:167], v[188:191], v[24:27]
	v_mfma_f32_16x16x32_bf16 v[12:15], v[156:159], v[196:199], v[12:15]
	v_mfma_f32_16x16x32_bf16 v[8:11], v[164:167], v[196:199], v[8:11]
	s_barrier
	s_add_u32 s42, s42, 0x40080
	s_addc_u32 s43, s43, 0
	s_add_i32 s44, s44, s51
	s_mov_b32 m0, s44
	s_nop 0
	global_load_lds_dwordx4 v130, s[42:43]
	s_add_i32 m0, s44, 0x2000
	s_nop 0
	global_load_lds_dwordx4 v134, s[42:43]
	s_waitcnt vmcnt(6)
	s_barrier
	v_mfma_f32_16x16x32_bf16 v[52:55], v[200:203], v[168:171], v[52:55]
	v_mfma_f32_16x16x32_bf16 v[48:51], v[210:213], v[168:171], v[48:51]
	v_mfma_f32_16x16x32_bf16 v[36:39], v[200:203], v[176:179], v[36:39]
	v_mfma_f32_16x16x32_bf16 v[32:35], v[210:213], v[176:179], v[32:35]
	v_mfma_f32_16x16x32_bf16 v[20:23], v[200:203], v[184:187], v[20:23]
	v_mfma_f32_16x16x32_bf16 v[16:19], v[210:213], v[184:187], v[16:19]
	v_mfma_f32_16x16x32_bf16 v[4:7], v[200:203], v[192:195], v[4:7]
	v_mfma_f32_16x16x32_bf16 v[0:3], v[210:213], v[192:195], v[0:3]
	v_mfma_f32_16x16x32_bf16 v[52:55], v[204:207], v[172:175], v[52:55]
	v_mfma_f32_16x16x32_bf16 v[48:51], v[214:217], v[172:175], v[48:51]
	v_mfma_f32_16x16x32_bf16 v[36:39], v[204:207], v[180:183], v[36:39]
	v_mfma_f32_16x16x32_bf16 v[32:35], v[214:217], v[180:183], v[32:35]
	v_mfma_f32_16x16x32_bf16 v[20:23], v[204:207], v[188:191], v[20:23]
	v_mfma_f32_16x16x32_bf16 v[16:19], v[214:217], v[188:191], v[16:19]
	v_mfma_f32_16x16x32_bf16 v[4:7], v[204:207], v[196:199], v[4:7]
	v_mfma_f32_16x16x32_bf16 v[0:3], v[214:217], v[196:199], v[0:3]
	s_barrier
	s_add_i32 s70, s70, 2
	s_add_u32 s40, s40, 0x100
	s_addc_u32 s41, s41, 0
	s_add_u32 s23, s23, 0x100
	s_addc_u32 s25, s25, 0
	s_cmp_gt_u32 s70, 13
	s_cbranch_scc0 .LBB0_433
	v_lshl_add_u32 v152, s38, 8, v146
	v_max_f32_e32 v120, 0, v120
	v_ashrrev_i32_e32 v153, 31, v152
	v_max_f32_e32 v121, 0, v121
	v_max_f32_e32 v122, 0, v122
	v_lshl_or_b32 v144, s69, 8, v148
	v_lshlrev_b64 v[154:155], 13, v[152:153]
	v_mul_f32_e32 v153, v120, v120
	v_max_f32_e32 v120, 0, v125
	v_ashrrev_i32_e32 v145, 31, v144
	v_max_f32_e32 v124, 0, v124
	v_mul_f32_e32 v125, v121, v121
	v_max_f32_e32 v121, 0, v126
	v_mul_f32_e32 v126, v122, v122
	v_max_f32_e32 v122, 0, v127
	v_max_f32_e32 v123, 0, v123
	v_lshl_add_u64 v[154:155], s[10:11], 0, v[154:155]
	v_lshlrev_b64 v[156:157], 1, v[144:145]
	v_mul_f32_e32 v120, v120, v120
	v_max_f32_e32 v112, 0, v112
	v_lshl_add_u64 v[144:145], v[154:155], 0, v[156:157]
	v_mul_f32_e32 v124, v124, v124
	v_mul_f32_e32 v121, v121, v121
	v_mul_f32_e32 v122, v122, v122
	v_mul_f32_e32 v123, v123, v123
	v_cvt_pk_bf16_f32 v120, v124, v120
	v_max_f32_e32 v113, 0, v113
	v_max_f32_e32 v114, 0, v114
	v_cvt_pk_bf16_f32 v121, v121, v122
	v_cvt_pk_bf16_f32 v122, v153, v125
	v_cvt_pk_bf16_f32 v123, v126, v123
	global_store_dwordx4 v[144:145], v[120:123], off
	s_nop 1
	v_mul_f32_e32 v120, v112, v112
	v_max_f32_e32 v112, 0, v117
	v_max_f32_e32 v116, 0, v116
	v_mul_f32_e32 v117, v113, v113
	v_max_f32_e32 v113, 0, v118
	v_mul_f32_e32 v118, v114, v114
	v_max_f32_e32 v114, 0, v119
	v_max_f32_e32 v115, 0, v115
	v_mul_f32_e32 v112, v112, v112
	v_mul_f32_e32 v116, v116, v116
	v_mul_f32_e32 v113, v113, v113
	v_mul_f32_e32 v114, v114, v114
	v_mul_f32_e32 v115, v115, v115
	v_cvt_pk_bf16_f32 v112, v116, v112
	v_max_f32_e32 v104, 0, v104
	v_cvt_pk_bf16_f32 v113, v113, v114
	v_cvt_pk_bf16_f32 v114, v120, v117
	v_cvt_pk_bf16_f32 v115, v118, v115
	global_store_dwordx4 v[144:145], v[112:115], off offset:256
	s_nop 0
	v_max_f32_e32 v105, 0, v105
	v_or_b32_e32 v112, 16, v152
	v_max_f32_e32 v106, 0, v106
	v_ashrrev_i32_e32 v113, 31, v112
	v_mul_f32_e32 v114, v104, v104
	v_max_f32_e32 v104, 0, v109
	v_lshlrev_b64 v[112:113], 13, v[112:113]
	v_max_f32_e32 v108, 0, v108
	v_mul_f32_e32 v109, v105, v105
	v_max_f32_e32 v105, 0, v110
	v_mul_f32_e32 v110, v106, v106
	v_max_f32_e32 v106, 0, v111
	v_max_f32_e32 v107, 0, v107
	v_lshl_add_u64 v[112:113], s[10:11], 0, v[112:113]
	v_mul_f32_e32 v104, v104, v104
	v_max_f32_e32 v96, 0, v96
	v_lshl_add_u64 v[112:113], v[112:113], 0, v[156:157]
	v_mul_f32_e32 v108, v108, v108
	v_mul_f32_e32 v105, v105, v105
	v_mul_f32_e32 v106, v106, v106
	v_mul_f32_e32 v107, v107, v107
	v_cvt_pk_bf16_f32 v104, v108, v104
; __device__ __forceinline__ unsigned cvt_pk_bf16(float lo, float hi) { unsigned r; asm volatile("v_cvt_pk_bf16_f32 %0, %1, %2" : "=v"(r) : "v"(lo), "v"(hi)); return r; }
;     __device__ __forceinline__ void operator()(const f32x4 (&acc)[2][2][4][2], const Unit& u, int ui, int wr, int wc, int fr, int fq) const {
;     ...
;         for (int ai = 0; ai < 2; ++ai)
; #pragma unroll
;             for (int m = 0; m < 4; ++m) { bf16_t* rowp = hid + (size_t)(row0 + ai * 128 + m * 16) * DFF + col0;
; #pragma unroll
;                 for (int bj = 0; bj < 2; ++bj) { f32x4 v0 = acc[ai][bj][m][0], v1 = acc[ai][bj][m][1];
; #pragma unroll
;                     for (int j = 0; j < 4; ++j) { const float a = fmaxf(v0[j], 0.f), b = fmaxf(v1[j], 0.f); v0[j] = a * a; v1[j] = b * b; }
;                     u32x4 w; w.x = cvt_pk_bf16(v0[0], v0[1]); w.y = cvt_pk_bf16(v0[2], v0[3]); w.z = cvt_pk_bf16(v1[0], v1[1]); w.w = cvt_pk_bf16(v1[2], v1[3]);
;                     *(u32x4*)(rowp + bj * 128) = w; } }
	v_max_f32_e32 v97, 0, v97
	v_max_f32_e32 v98, 0, v98
	v_cvt_pk_bf16_f32 v105, v105, v106
	v_cvt_pk_bf16_f32 v106, v114, v109
	v_cvt_pk_bf16_f32 v107, v110, v107
	global_store_dwordx4 v[112:113], v[104:107], off
	s_nop 1
	v_mul_f32_e32 v104, v96, v96
	v_max_f32_e32 v96, 0, v101
	v_max_f32_e32 v100, 0, v100
	v_mul_f32_e32 v101, v97, v97
	v_max_f32_e32 v97, 0, v102
	v_mul_f32_e32 v102, v98, v98
	v_max_f32_e32 v98, 0, v103
	v_max_f32_e32 v99, 0, v99
	v_mul_f32_e32 v96, v96, v96
	v_mul_f32_e32 v100, v100, v100
	v_mul_f32_e32 v97, v97, v97
	v_mul_f32_e32 v98, v98, v98
	v_mul_f32_e32 v99, v99, v99
	v_cvt_pk_bf16_f32 v96, v100, v96
	v_max_f32_e32 v88, 0, v88
	v_cvt_pk_bf16_f32 v97, v97, v98
	v_cvt_pk_bf16_f32 v98, v104, v101
	v_cvt_pk_bf16_f32 v99, v102, v99
	global_store_dwordx4 v[112:113], v[96:99], off offset:256
	s_nop 0
	v_max_f32_e32 v89, 0, v89
	v_or_b32_e32 v96, 32, v152
	v_max_f32_e32 v90, 0, v90
	v_ashrrev_i32_e32 v97, 31, v96
	v_mul_f32_e32 v98, v88, v88
	v_max_f32_e32 v88, 0, v93
	v_lshlrev_b64 v[96:97], 13, v[96:97]
	v_max_f32_e32 v92, 0, v92
	v_mul_f32_e32 v93, v89, v89
	v_max_f32_e32 v89, 0, v94
	v_mul_f32_e32 v94, v90, v90
	v_max_f32_e32 v90, 0, v95
	v_max_f32_e32 v91, 0, v91
	v_lshl_add_u64 v[96:97], s[10:11], 0, v[96:97]
	v_mul_f32_e32 v88, v88, v88
	v_max_f32_e32 v80, 0, v80
	v_lshl_add_u64 v[96:97], v[96:97], 0, v[156:157]
	v_mul_f32_e32 v92, v92, v92
	v_mul_f32_e32 v89, v89, v89
	v_mul_f32_e32 v90, v90, v90
	v_mul_f32_e32 v91, v91, v91
	v_cvt_pk_bf16_f32 v88, v92, v88
	v_max_f32_e32 v81, 0, v81
	v_max_f32_e32 v82, 0, v82
	v_cvt_pk_bf16_f32 v89, v89, v90
	v_cvt_pk_bf16_f32 v90, v98, v93
	v_cvt_pk_bf16_f32 v91, v94, v91
	global_store_dwordx4 v[96:97], v[88:91], off
	s_nop 1
	v_mul_f32_e32 v88, v80, v80
	v_max_f32_e32 v80, 0, v85
	v_max_f32_e32 v84, 0, v84
	v_mul_f32_e32 v85, v81, v81
	v_max_f32_e32 v81, 0, v86
	v_mul_f32_e32 v86, v82, v82
	v_max_f32_e32 v82, 0, v87
	v_max_f32_e32 v83, 0, v83
	v_mul_f32_e32 v80, v80, v80
	v_mul_f32_e32 v84, v84, v84
	v_mul_f32_e32 v81, v81, v81
	v_mul_f32_e32 v82, v82, v82
	v_mul_f32_e32 v83, v83, v83
	v_cvt_pk_bf16_f32 v80, v84, v80
	v_max_f32_e32 v72, 0, v72
	v_cvt_pk_bf16_f32 v81, v81, v82
	v_cvt_pk_bf16_f32 v82, v88, v85
	v_cvt_pk_bf16_f32 v83, v86, v83
	global_store_dwordx4 v[96:97], v[80:83], off offset:256
	s_nop 0
	v_max_f32_e32 v73, 0, v73
	v_or_b32_e32 v80, 48, v152
	v_max_f32_e32 v74, 0, v74
	v_ashrrev_i32_e32 v81, 31, v80
	v_mul_f32_e32 v82, v72, v72
	v_max_f32_e32 v72, 0, v77
	v_lshlrev_b64 v[80:81], 13, v[80:81]
	v_max_f32_e32 v76, 0, v76
	v_mul_f32_e32 v77, v73, v73
	v_max_f32_e32 v73, 0, v78
	v_mul_f32_e32 v78, v74, v74
	v_max_f32_e32 v74, 0, v79
	v_max_f32_e32 v75, 0, v75
	v_lshl_add_u64 v[80:81], s[10:11], 0, v[80:81]
	v_mul_f32_e32 v72, v72, v72
	v_max_f32_e32 v64, 0, v64
	v_max_f32_e32 v65, 0, v65
	v_max_f32_e32 v66, 0, v66
	v_lshl_add_u64 v[80:81], v[80:81], 0, v[156:157]
	v_mul_f32_e32 v76, v76, v76
	v_mul_f32_e32 v73, v73, v73
	v_mul_f32_e32 v74, v74, v74
	v_mul_f32_e32 v75, v75, v75
	v_cvt_pk_bf16_f32 v72, v76, v72
	v_cvt_pk_bf16_f32 v73, v73, v74
	v_cvt_pk_bf16_f32 v74, v82, v77
	v_cvt_pk_bf16_f32 v75, v78, v75
	global_store_dwordx4 v[80:81], v[72:75], off
	v_max_f32_e32 v68, 0, v68
	v_max_f32_e32 v67, 0, v67
	v_mul_f32_e32 v72, v64, v64
	v_max_f32_e32 v64, 0, v69
	v_mul_f32_e32 v69, v65, v65
	v_max_f32_e32 v65, 0, v70
	v_mul_f32_e32 v70, v66, v66
	v_max_f32_e32 v66, 0, v71
	v_mul_f32_e32 v64, v64, v64
	v_mul_f32_e32 v65, v65, v65
	v_mul_f32_e32 v66, v66, v66
	v_max_f32_e32 v56, 0, v56
	v_mul_f32_e32 v68, v68, v68
	v_mul_f32_e32 v67, v67, v67
	v_cvt_pk_bf16_f32 v64, v68, v64
	v_cvt_pk_bf16_f32 v65, v65, v66
	v_cvt_pk_bf16_f32 v66, v72, v69
	v_max_f32_e32 v57, 0, v57
	v_max_f32_e32 v58, 0, v58
	v_cvt_pk_bf16_f32 v67, v70, v67
	global_store_dwordx4 v[80:81], v[64:67], off offset:256
	s_nop 0
	v_max_f32_e32 v60, 0, v60
	v_mul_f32_e32 v66, v56, v56
	v_max_f32_e32 v56, 0, v61
	v_mul_f32_e32 v61, v57, v57
	v_max_f32_e32 v57, 0, v62
	v_mul_f32_e32 v62, v58, v58
	v_max_f32_e32 v58, 0, v63
	v_mul_f32_e32 v60, v60, v60
	v_mul_f32_e32 v56, v56, v56
	v_max_f32_e32 v59, 0, v59
	v_mul_f32_e32 v57, v57, v57
	v_mul_f32_e32 v58, v58, v58
	v_cvt_pk_bf16_f32 v56, v60, v56
	v_add_co_u32_e32 v60, vcc, s65, v144
	v_max_f32_e32 v48, 0, v48
	v_max_f32_e32 v49, 0, v49
	v_max_f32_e32 v50, 0, v50
	v_mul_f32_e32 v59, v59, v59
	v_cvt_pk_bf16_f32 v57, v57, v58
	v_cvt_pk_bf16_f32 v58, v66, v61
	v_addc_co_u32_e32 v61, vcc, 0, v145, vcc
	v_cvt_pk_bf16_f32 v59, v62, v59
	global_store_dwordx4 v[60:61], v[56:59], off
	v_max_f32_e32 v52, 0, v52
	v_max_f32_e32 v51, 0, v51
	v_mul_f32_e32 v56, v48, v48
	v_max_f32_e32 v48, 0, v53
	v_mul_f32_e32 v53, v49, v49
	v_max_f32_e32 v49, 0, v54
	v_mul_f32_e32 v54, v50, v50
	v_max_f32_e32 v50, 0, v55
; __device__ __forceinline__ unsigned cvt_pk_bf16(float lo, float hi) { unsigned r; asm volatile("v_cvt_pk_bf16_f32 %0, %1, %2" : "=v"(r) : "v"(lo), "v"(hi)); return r; }
; #define PG8_WAIT_V(n) asm volatile("s_waitcnt vmcnt(" #n ")" ::: "memory")
; #define PG8_BAR __builtin_amdgcn_s_barrier()
; template <class Epi, class Ptrs>
; __device__ __forceinline__ void gemm_phase(LAS unsigned char* lds, const int K, const StaticOrder& S, const Ptrs& P, const Epi& E) {
;     ...
;         if (!has_next) break;
; #pragma unroll
;         for (int a = 0; a < 2; ++a)
; #pragma unroll
;             for (int b = 0; b < 2; ++b)
; #pragma unroll
;                 for (int m = 0; m < 4; ++m)
; #pragma unroll
;                     for (int n = 0; n < 2; ++n) acc[a][b][m][n] = (f32x4){0.f, 0.f, 0.f, 0.f};
;         cur = nxt; cA = nA; cB = nB; ++ui;
;     }
;     PG8_WAIT_V(0);
;     if (wr == 0) PG8_BAR;
;     PG8_BAR;
;     __device__ __forceinline__ void operator()(const f32x4 (&acc)[2][2][4][2], const Unit& u, int ui, int wr, int wc, int fr, int fq) const {
;     ...
;         for (int ai = 0; ai < 2; ++ai)
; #pragma unroll
;             for (int m = 0; m < 4; ++m) { bf16_t* rowp = hid + (size_t)(row0 + ai * 128 + m * 16) * DFF + col0;
; #pragma unroll
;                 for (int bj = 0; bj < 2; ++bj) { f32x4 v0 = acc[ai][bj][m][0], v1 = acc[ai][bj][m][1];
; #pragma unroll
;                     for (int j = 0; j < 4; ++j) { const float a = fmaxf(v0[j], 0.f), b = fmaxf(v1[j], 0.f); v0[j] = a * a; v1[j] = b * b; }
;                     u32x4 w; w.x = cvt_pk_bf16(v0[0], v0[1]); w.y = cvt_pk_bf16(v0[2], v0[3]); w.z = cvt_pk_bf16(v1[0], v1[1]); w.w = cvt_pk_bf16(v1[2], v1[3]);
;                     *(u32x4*)(rowp + bj * 128) = w; } }
	v_mul_f32_e32 v48, v48, v48
	v_mul_f32_e32 v49, v49, v49
	v_mul_f32_e32 v50, v50, v50
	v_max_f32_e32 v40, 0, v40
	v_lshl_add_u64 v[64:65], v[144:145], 0, s[14:15]
	v_mul_f32_e32 v52, v52, v52
	v_mul_f32_e32 v51, v51, v51
	v_cvt_pk_bf16_f32 v48, v52, v48
	v_cvt_pk_bf16_f32 v49, v49, v50
	v_cvt_pk_bf16_f32 v50, v56, v53
	v_max_f32_e32 v41, 0, v41
	v_max_f32_e32 v42, 0, v42
	v_cvt_pk_bf16_f32 v51, v54, v51
	global_store_dwordx4 v[64:65], v[48:51], off offset:256
	s_nop 0
	v_max_f32_e32 v44, 0, v44
	v_mul_f32_e32 v50, v40, v40
	v_max_f32_e32 v40, 0, v45
	v_mul_f32_e32 v45, v41, v41
	v_max_f32_e32 v41, 0, v46
	v_mul_f32_e32 v46, v42, v42
	v_max_f32_e32 v42, 0, v47
	v_mul_f32_e32 v44, v44, v44
	v_mul_f32_e32 v40, v40, v40
	v_max_f32_e32 v43, 0, v43
	v_mul_f32_e32 v41, v41, v41
	v_mul_f32_e32 v42, v42, v42
	v_cvt_pk_bf16_f32 v40, v44, v40
	v_add_co_u32_e32 v44, vcc, s66, v144
	v_max_f32_e32 v32, 0, v32
	v_max_f32_e32 v33, 0, v33
	v_max_f32_e32 v34, 0, v34
	v_mul_f32_e32 v43, v43, v43
	v_cvt_pk_bf16_f32 v41, v41, v42
	v_cvt_pk_bf16_f32 v42, v50, v45
	v_addc_co_u32_e32 v45, vcc, 0, v145, vcc
	v_cvt_pk_bf16_f32 v43, v46, v43
	global_store_dwordx4 v[44:45], v[40:43], off
	v_max_f32_e32 v36, 0, v36
	v_max_f32_e32 v35, 0, v35
	v_mul_f32_e32 v40, v32, v32
	v_max_f32_e32 v32, 0, v37
	v_mul_f32_e32 v37, v33, v33
	v_max_f32_e32 v33, 0, v38
	v_mul_f32_e32 v38, v34, v34
	v_max_f32_e32 v34, 0, v39
	v_mul_f32_e32 v32, v32, v32
	v_mul_f32_e32 v33, v33, v33
	v_mul_f32_e32 v34, v34, v34
	v_max_f32_e32 v24, 0, v24
	v_lshl_add_u64 v[48:49], v[144:145], 0, s[16:17]
	v_mul_f32_e32 v36, v36, v36
	v_mul_f32_e32 v35, v35, v35
	v_cvt_pk_bf16_f32 v32, v36, v32
	v_cvt_pk_bf16_f32 v33, v33, v34
	v_cvt_pk_bf16_f32 v34, v40, v37
	v_max_f32_e32 v25, 0, v25
	v_max_f32_e32 v26, 0, v26
	v_cvt_pk_bf16_f32 v35, v38, v35
	global_store_dwordx4 v[48:49], v[32:35], off offset:256
	s_nop 0
	v_max_f32_e32 v28, 0, v28
	v_mul_f32_e32 v34, v24, v24
	v_max_f32_e32 v24, 0, v29
	v_mul_f32_e32 v29, v25, v25
	v_max_f32_e32 v25, 0, v30
	v_mul_f32_e32 v30, v26, v26
	v_max_f32_e32 v26, 0, v31
	v_mul_f32_e32 v28, v28, v28
	v_mul_f32_e32 v24, v24, v24
	v_max_f32_e32 v27, 0, v27
	v_mul_f32_e32 v25, v25, v25
	v_mul_f32_e32 v26, v26, v26
	v_cvt_pk_bf16_f32 v24, v28, v24
	v_add_co_u32_e32 v28, vcc, s67, v144
	v_max_f32_e32 v16, 0, v16
	v_max_f32_e32 v17, 0, v17
	v_max_f32_e32 v18, 0, v18
	v_mul_f32_e32 v27, v27, v27
	v_cvt_pk_bf16_f32 v25, v25, v26
	v_cvt_pk_bf16_f32 v26, v34, v29
	v_addc_co_u32_e32 v29, vcc, 0, v145, vcc
	v_cvt_pk_bf16_f32 v27, v30, v27
	global_store_dwordx4 v[28:29], v[24:27], off
	v_max_f32_e32 v20, 0, v20
	v_max_f32_e32 v19, 0, v19
	v_mul_f32_e32 v24, v16, v16
	v_max_f32_e32 v16, 0, v21
	v_mul_f32_e32 v21, v17, v17
	v_max_f32_e32 v17, 0, v22
	v_mul_f32_e32 v22, v18, v18
	v_max_f32_e32 v18, 0, v23
	v_mul_f32_e32 v16, v16, v16
	v_mul_f32_e32 v17, v17, v17
	v_mul_f32_e32 v18, v18, v18
	v_max_f32_e32 v8, 0, v8
	v_lshl_add_u64 v[32:33], v[144:145], 0, s[18:19]
	v_mul_f32_e32 v20, v20, v20
	v_mul_f32_e32 v19, v19, v19
	v_cvt_pk_bf16_f32 v16, v20, v16
	v_cvt_pk_bf16_f32 v17, v17, v18
	v_cvt_pk_bf16_f32 v18, v24, v21
	v_max_f32_e32 v9, 0, v9
	v_max_f32_e32 v10, 0, v10
	v_cvt_pk_bf16_f32 v19, v22, v19
	global_store_dwordx4 v[32:33], v[16:19], off offset:256
	s_nop 0
	v_max_f32_e32 v12, 0, v12
	v_mul_f32_e32 v18, v8, v8
	v_max_f32_e32 v8, 0, v13
	v_mul_f32_e32 v13, v9, v9
	v_max_f32_e32 v9, 0, v14
	v_mul_f32_e32 v14, v10, v10
	v_max_f32_e32 v10, 0, v15
	v_mul_f32_e32 v12, v12, v12
	v_mul_f32_e32 v8, v8, v8
	v_max_f32_e32 v11, 0, v11
	v_mul_f32_e32 v9, v9, v9
	v_mul_f32_e32 v10, v10, v10
	v_cvt_pk_bf16_f32 v8, v12, v8
	v_add_co_u32_e32 v12, vcc, s68, v144
	v_max_f32_e32 v0, 0, v0
	v_max_f32_e32 v1, 0, v1
	v_max_f32_e32 v2, 0, v2
	v_mul_f32_e32 v11, v11, v11
	v_cvt_pk_bf16_f32 v9, v9, v10
	v_cvt_pk_bf16_f32 v10, v18, v13
	v_addc_co_u32_e32 v13, vcc, 0, v145, vcc
	v_cvt_pk_bf16_f32 v11, v14, v11
	global_store_dwordx4 v[12:13], v[8:11], off
	v_max_f32_e32 v3, 0, v3
	v_max_f32_e32 v4, 0, v4
	v_mul_f32_e32 v8, v0, v0
	v_max_f32_e32 v0, 0, v5
	v_mul_f32_e32 v5, v1, v1
	v_max_f32_e32 v1, 0, v6
	v_mul_f32_e32 v6, v2, v2
	v_max_f32_e32 v2, 0, v7
	v_lshl_add_u64 v[16:17], v[144:145], 0, s[20:21]
	v_mul_f32_e32 v0, v0, v0
	v_mul_f32_e32 v1, v1, v1
	v_mul_f32_e32 v2, v2, v2
	v_mul_f32_e32 v3, v3, v3
	s_and_b64 vcc, exec, s[4:5]
	s_mov_b32 s69, s22
	s_mov_b32 s38, s24
	s_mov_b64 s[40:41], s[0:1]
	s_mov_b64 s[42:43], s[36:37]
	v_mul_f32_e32 v4, v4, v4
	v_cvt_pk_bf16_f32 v0, v4, v0
	v_cvt_pk_bf16_f32 v1, v1, v2
	v_cvt_pk_bf16_f32 v2, v8, v5
	v_cvt_pk_bf16_f32 v3, v6, v3
	global_store_dwordx4 v[16:17], v[0:3], off offset:256
	s_cbranch_vccz .LBB0_428
	s_waitcnt vmcnt(0)
	s_setprio 0
	s_cmpk_gt_u32 s46, 0xff
	s_cbranch_scc1 .LBB0_437
	s_barrier

; #define PG8_STAGE(bufoff, gbase, voff) do { _Pragma("unroll") for (int _i = 0; _i < 2; ++_i) \
;         __builtin_amdgcn_global_load_lds((const unsigned*)((const char*)(gbase) + (voff)[_i]), (LAS unsigned*)(lds + (bufoff) + ldsw + _i * 8192), 16, 0, 0); } while (0)
; #define PG8_LDA(dst, b, h) do { _Pragma("unroll") for (int m = 0; m < 4; ++m) _Pragma("unroll") for (int k = 0; k < 2; ++k) dst[m][k] = *(const LAS bf16x8*)(lds + PG8_SA(b, h) + aoff + m * 2048 + k * 1024); } while (0)
; #define PG8_WAIT_V(n) asm volatile("s_waitcnt vmcnt(" #n ")" ::: "memory")
; #define PG8_BAR __builtin_amdgcn_s_barrier()
; template <class Epi, class Ptrs>
; __device__ __forceinline__ void gemm_phase(LAS unsigned char* lds, const int K, const StaticOrder& S, const Ptrs& P, const Epi& E) {
;     ...
;         for (int t = 0; t < nt; t += 2) {
;             const bool last = (t == nt - 2);
;             const char* a1 = cA + (size_t)(t + 1) * kstep;
;             const char* a2 = last ? nA : cA + (size_t)(t + 2) * kstep; const char* b2 = last ? nB : cB + (size_t)(t + 2) * kstep;
;             const char* a3 = a2 + kstep; const char* b3 = b2 + kstep;
;             PG8_LDB(B0, 0, 0); PG8_SCHED; PG8_LDA(At, 0, 0); PG8_STAGE(PG8_SA(1, 1), a1 + hstep, voffA);
;             PG8_WAIT_L(8); PG8_BAR; PG8_WAIT_L(0); PG8_MMA(0, 0, At, B0); PG8_BAR; PG8_SCHED;
;             PG8_LDB(B1, 0, 1); PG8_STAGE(PG8_SB(0, 0), b2, voffB);
;             PG8_BAR; PG8_WAIT_L(0); PG8_MMA(0, 1, At, B1); PG8_BAR;
;             PG8_LDA(At, 0, 1); PG8_STAGE(PG8_SA(0, 0), a2, voffA);
;             PG8_BAR; PG8_WAIT_L(0); PG8_MMA(1, 0, At, B0); PG8_BAR; PG8_SCHED;
;             PG8_STAGE(PG8_SB(0, 1), b2 + hstep, voffB);
;             PG8_WAIT_V(6); PG8_BAR; PG8_MMA(1, 1, At, B1); PG8_BAR;
;             PG8_LDB(B0, 1, 0); PG8_SCHED; PG8_LDA(At, 1, 0); PG8_STAGE(PG8_SA(0, 1), a2 + hstep, voffA);
;             PG8_WAIT_L(8); PG8_BAR; PG8_WAIT_L(0); PG8_MMA(0, 0, At, B0); PG8_BAR; PG8_SCHED;
;             PG8_LDB(B1, 1, 1); PG8_STAGE(PG8_SB(1, 0), b3, voffB);
;             PG8_BAR; PG8_WAIT_L(0); PG8_MMA(0, 1, At, B1); PG8_BAR;
;             PG8_LDA(At, 1, 1); PG8_STAGE(PG8_SA(1, 0), a3, voffA);
;             PG8_BAR; PG8_WAIT_L(0); PG8_MMA(1, 0, At, B0); PG8_BAR; PG8_SCHED;
;             PG8_STAGE(PG8_SB(1, 1), b3 + hstep, voffB);
;             PG8_WAIT_V(6); PG8_BAR; PG8_MMA(1, 1, At, B1); PG8_BAR;
.LBB0_521:
	s_add_u32 s20, s20, 0x100080
	s_addc_u32 s21, s21, 0
	s_add_u32 s11, s22, 0x100
	s_addc_u32 s13, s23, 0
	s_mov_b32 s46, -2
	v_add_u32_e32 v252, 0x18000, v187
	v_add_u32_e32 v253, 0x1c000, v187
	ds_read_b128 v[128:131], v193
	ds_read_b128 v[132:135], v193 offset:1024
	ds_read_b128 v[136:139], v193 offset:2048
	ds_read_b128 v[140:143], v193 offset:3072
	s_add_u32 s22, s20, 0xfff00080
	s_addc_u32 s23, s21, -1
	s_cmp_eq_u32 s46, 60
	s_cselect_b32 s25, s5, s23
	s_cselect_b32 s24, s4, s22
	s_cselect_b32 s23, s15, s13
	s_cselect_b32 s22, s14, s11
	s_add_i32 m0, s17, 0xc000
	ds_read_b128 v[144:147], v194
	ds_read_b128 v[148:151], v194 offset:1024
	ds_read_b128 v[152:155], v194 offset:2048
	ds_read_b128 v[156:159], v194 offset:3072
	ds_read_b128 v[176:179], v194 offset:4096
	ds_read_b128 v[180:183], v194 offset:5120
	ds_read_b128 v[196:199], v194 offset:6144
	ds_read_b128 v[200:203], v194 offset:7168
	global_load_lds_dwordx4 v168, s[20:21]
	s_add_i32 m0, s17, 0xe000
	s_nop 0
	global_load_lds_dwordx4 v170, s[20:21]
	s_waitcnt lgkmcnt(8)
	s_barrier
	s_waitcnt lgkmcnt(0)
	v_mfma_f32_16x16x32_bf16 v[124:127], v[128:131], v[144:147], 0
	v_mfma_f32_16x16x32_bf16 v[120:123], v[136:139], v[144:147], 0
	v_mfma_f32_16x16x32_bf16 v[112:115], v[128:131], v[152:155], 0
	v_mfma_f32_16x16x32_bf16 v[104:107], v[136:139], v[152:155], 0
	v_mfma_f32_16x16x32_bf16 v[92:95], v[128:131], v[176:179], 0
	v_mfma_f32_16x16x32_bf16 v[88:91], v[136:139], v[176:179], 0
	v_mfma_f32_16x16x32_bf16 v[76:79], v[128:131], v[196:199], 0
	v_mfma_f32_16x16x32_bf16 v[72:75], v[136:139], v[196:199], 0
	v_mfma_f32_16x16x32_bf16 v[124:127], v[132:135], v[148:151], v[124:127]
	v_mfma_f32_16x16x32_bf16 v[120:123], v[140:143], v[148:151], v[120:123]
	v_mfma_f32_16x16x32_bf16 v[112:115], v[132:135], v[156:159], v[112:115]
	v_mfma_f32_16x16x32_bf16 v[104:107], v[140:143], v[156:159], v[104:107]
	v_mfma_f32_16x16x32_bf16 v[92:95], v[132:135], v[180:183], v[92:95]
	v_mfma_f32_16x16x32_bf16 v[88:91], v[140:143], v[180:183], v[88:91]
	v_mfma_f32_16x16x32_bf16 v[76:79], v[132:135], v[200:203], v[76:79]
	v_mfma_f32_16x16x32_bf16 v[72:75], v[140:143], v[200:203], v[72:75]
	s_barrier
	s_add_i32 s47, s42, s34
	s_add_u32 s90, s22, 0x80
	s_addc_u32 s91, s23, 0
	s_mov_b32 m0, s47
	ds_read_b128 v[204:207], v195
	ds_read_b128 v[208:211], v195 offset:1024
	ds_read_b128 v[212:215], v195 offset:2048
	ds_read_b128 v[216:219], v195 offset:3072
	global_load_lds_dwordx4 v162, s[22:23]
	s_add_i32 m0, s47, 0x2000
	s_nop 0
	global_load_lds_dwordx4 v166, s[22:23]
	s_barrier
	s_waitcnt lgkmcnt(0)
	v_mfma_f32_16x16x32_bf16 v[116:119], v[204:207], v[144:147], 0
	v_mfma_f32_16x16x32_bf16 v[108:111], v[212:215], v[144:147], 0
	v_mfma_f32_16x16x32_bf16 v[100:103], v[204:207], v[152:155], 0
	v_mfma_f32_16x16x32_bf16 v[96:99], v[212:215], v[152:155], 0
	v_mfma_f32_16x16x32_bf16 v[84:87], v[204:207], v[176:179], 0
	v_mfma_f32_16x16x32_bf16 v[80:83], v[212:215], v[176:179], 0
	v_mfma_f32_16x16x32_bf16 v[68:71], v[204:207], v[196:199], 0
	v_mfma_f32_16x16x32_bf16 v[64:67], v[212:215], v[196:199], 0
	v_mfma_f32_16x16x32_bf16 v[116:119], v[208:211], v[148:151], v[116:119]
	v_mfma_f32_16x16x32_bf16 v[108:111], v[216:219], v[148:151], v[108:111]
	v_mfma_f32_16x16x32_bf16 v[100:103], v[208:211], v[156:159], v[100:103]
	v_mfma_f32_16x16x32_bf16 v[96:99], v[216:219], v[156:159], v[96:99]
	v_mfma_f32_16x16x32_bf16 v[84:87], v[208:211], v[180:183], v[84:87]
	v_mfma_f32_16x16x32_bf16 v[80:83], v[216:219], v[180:183], v[80:83]
	v_mfma_f32_16x16x32_bf16 v[68:71], v[208:211], v[200:203], v[68:71]
	v_mfma_f32_16x16x32_bf16 v[64:67], v[216:219], v[200:203], v[64:67]
	s_barrier
	s_mov_b32 m0, s17
	s_add_u32 s92, s24, 0x80
	s_addc_u32 s93, s25, 0
	ds_read_b128 v[144:147], v194 offset:16384
	ds_read_b128 v[148:151], v194 offset:17408
	ds_read_b128 v[152:155], v194 offset:18432
	ds_read_b128 v[156:159], v194 offset:19456
	ds_read_b128 v[176:179], v194 offset:20480
	ds_read_b128 v[180:183], v194 offset:21504
	ds_read_b128 v[196:199], v194 offset:22528
	ds_read_b128 v[200:203], v194 offset:23552
	global_load_lds_dwordx4 v160, s[24:25]
	s_mov_b32 m0, s19
	s_nop 0
	global_load_lds_dwordx4 v164, s[24:25]
	s_barrier
	s_waitcnt lgkmcnt(0)
	v_mfma_f32_16x16x32_bf16 v[60:63], v[128:131], v[144:147], 0
	v_mfma_f32_16x16x32_bf16 v[56:59], v[136:139], v[144:147], 0
	v_mfma_f32_16x16x32_bf16 v[48:51], v[128:131], v[152:155], 0
	v_mfma_f32_16x16x32_bf16 v[40:43], v[136:139], v[152:155], 0
	v_mfma_f32_16x16x32_bf16 v[32:35], v[128:131], v[176:179], 0
	v_mfma_f32_16x16x32_bf16 v[24:27], v[136:139], v[176:179], 0
	v_mfma_f32_16x16x32_bf16 v[16:19], v[128:131], v[196:199], 0
	v_mfma_f32_16x16x32_bf16 v[8:11], v[136:139], v[196:199], 0
	v_mfma_f32_16x16x32_bf16 v[60:63], v[132:135], v[148:151], v[60:63]
	v_mfma_f32_16x16x32_bf16 v[56:59], v[140:143], v[148:151], v[56:59]
	v_mfma_f32_16x16x32_bf16 v[48:51], v[132:135], v[156:159], v[48:51]
	v_mfma_f32_16x16x32_bf16 v[40:43], v[140:143], v[156:159], v[40:43]
	v_mfma_f32_16x16x32_bf16 v[32:35], v[132:135], v[180:183], v[32:35]
	v_mfma_f32_16x16x32_bf16 v[24:27], v[140:143], v[180:183], v[24:27]
	v_mfma_f32_16x16x32_bf16 v[16:19], v[132:135], v[200:203], v[16:19]
	v_mfma_f32_16x16x32_bf16 v[8:11], v[140:143], v[200:203], v[8:11]
	s_barrier
	s_add_u32 s48, s22, 0x100000
	s_addc_u32 s49, s23, 0
	s_add_i32 s47, s43, s34
	s_mov_b32 m0, s47
	s_nop 0
	global_load_lds_dwordx4 v162, s[48:49]
	s_add_i32 m0, s47, 0x2000
	s_nop 0
	global_load_lds_dwordx4 v166, s[48:49]
	s_waitcnt vmcnt(6)
	s_barrier
; #define PG8_STAGE(bufoff, gbase, voff) do { _Pragma("unroll") for (int _i = 0; _i < 2; ++_i) \
;         __builtin_amdgcn_global_load_lds((const unsigned*)((const char*)(gbase) + (voff)[_i]), (LAS unsigned*)(lds + (bufoff) + ldsw + _i * 8192), 16, 0, 0); } while (0)
; #define PG8_LDA(dst, b, h) do { _Pragma("unroll") for (int m = 0; m < 4; ++m) _Pragma("unroll") for (int k = 0; k < 2; ++k) dst[m][k] = *(const LAS bf16x8*)(lds + PG8_SA(b, h) + aoff + m * 2048 + k * 1024); } while (0)
; #define PG8_LDB(dst, b, h) do { _Pragma("unroll") for (int n = 0; n < 2; ++n) _Pragma("unroll") for (int k = 0; k < 2; ++k) dst[n][k] = *(const LAS bf16x8*)(lds + PG8_SB(b, h) + boff + n * 2048 + k * 1024); } while (0)
; #define PG8_WAIT_V(n) asm volatile("s_waitcnt vmcnt(" #n ")" ::: "memory")
; #define PG8_WAIT_L(n) asm volatile("s_waitcnt lgkmcnt(" #n ")" ::: "memory")
; #define PG8_BAR __builtin_amdgcn_s_barrier()
; #define PG8_SCHED __builtin_amdgcn_sched_barrier(0)
; template <class Epi, class Ptrs>
; __device__ __forceinline__ void gemm_phase(LAS unsigned char* lds, const int K, const StaticOrder& S, const Ptrs& P, const Epi& E) {
;     ...
;             PG8_LDB(B0, 0, 0); PG8_SCHED; PG8_LDA(At, 0, 0); PG8_STAGE(PG8_SA(1, 1), a1 + hstep, voffA);
;             PG8_WAIT_L(8); PG8_BAR; PG8_WAIT_L(0); PG8_MMA(0, 0, At, B0); PG8_BAR; PG8_SCHED;
;             PG8_LDB(B1, 0, 1); PG8_STAGE(PG8_SB(0, 0), b2, voffB);
;             PG8_BAR; PG8_WAIT_L(0); PG8_MMA(0, 1, At, B1); PG8_BAR;
;             PG8_LDA(At, 0, 1); PG8_STAGE(PG8_SA(0, 0), a2, voffA);
;             PG8_BAR; PG8_WAIT_L(0); PG8_MMA(1, 0, At, B0); PG8_BAR; PG8_SCHED;
;             PG8_STAGE(PG8_SB(0, 1), b2 + hstep, voffB);
;             PG8_WAIT_V(6); PG8_BAR; PG8_MMA(1, 1, At, B1); PG8_BAR;
;             PG8_LDB(B0, 1, 0); PG8_SCHED; PG8_LDA(At, 1, 0); PG8_STAGE(PG8_SA(0, 1), a2 + hstep, voffA);
;             PG8_WAIT_L(8); PG8_BAR; PG8_WAIT_L(0); PG8_MMA(0, 0, At, B0); PG8_BAR; PG8_SCHED;
;             PG8_LDB(B1, 1, 1); PG8_STAGE(PG8_SB(1, 0), b3, voffB);
;             PG8_BAR; PG8_WAIT_L(0); PG8_MMA(0, 1, At, B1); PG8_BAR;
;             PG8_LDA(At, 1, 1); PG8_STAGE(PG8_SA(1, 0), a3, voffA);
;             PG8_BAR; PG8_WAIT_L(0); PG8_MMA(1, 0, At, B0); PG8_BAR; PG8_SCHED;
;             PG8_STAGE(PG8_SB(1, 1), b3 + hstep, voffB);
;             PG8_WAIT_V(6); PG8_BAR; PG8_MMA(1, 1, At, B1); PG8_BAR;
	v_mfma_f32_16x16x32_bf16 v[52:55], v[204:207], v[144:147], 0
	v_mfma_f32_16x16x32_bf16 v[44:47], v[212:215], v[144:147], 0
	v_mfma_f32_16x16x32_bf16 v[36:39], v[204:207], v[152:155], 0
	v_mfma_f32_16x16x32_bf16 v[28:31], v[212:215], v[152:155], 0
	v_mfma_f32_16x16x32_bf16 v[20:23], v[204:207], v[176:179], 0
	v_mfma_f32_16x16x32_bf16 v[12:15], v[212:215], v[176:179], 0
	v_mfma_f32_16x16x32_bf16 v[4:7], v[204:207], v[196:199], 0
	v_mfma_f32_16x16x32_bf16 v[0:3], v[212:215], v[196:199], 0
	v_mfma_f32_16x16x32_bf16 v[52:55], v[208:211], v[148:151], v[52:55]
	v_mfma_f32_16x16x32_bf16 v[44:47], v[216:219], v[148:151], v[44:47]
	v_mfma_f32_16x16x32_bf16 v[36:39], v[208:211], v[156:159], v[36:39]
	v_mfma_f32_16x16x32_bf16 v[28:31], v[216:219], v[156:159], v[28:31]
	v_mfma_f32_16x16x32_bf16 v[20:23], v[208:211], v[180:183], v[20:23]
	v_mfma_f32_16x16x32_bf16 v[12:15], v[216:219], v[180:183], v[12:15]
	v_mfma_f32_16x16x32_bf16 v[4:7], v[208:211], v[200:203], v[4:7]
	v_mfma_f32_16x16x32_bf16 v[0:3], v[216:219], v[200:203], v[0:3]
	s_barrier
	s_add_i32 s47, 0, 0x18000
	ds_read_b128 v[128:131], v252
	ds_read_b128 v[132:135], v252 offset:1024
	ds_read_b128 v[136:139], v252 offset:2048
	ds_read_b128 v[140:143], v252 offset:3072
	s_add_u32 s24, s24, 0x100000
	s_addc_u32 s25, s25, 0
	s_mov_b32 m0, s40
	ds_read_b128 v[144:147], v194 offset:32768
	ds_read_b128 v[148:151], v194 offset:33792
	ds_read_b128 v[152:155], v194 offset:34816
	ds_read_b128 v[156:159], v194 offset:35840
	ds_read_b128 v[176:179], v194 offset:36864
	ds_read_b128 v[180:183], v194 offset:37888
	ds_read_b128 v[196:199], v194 offset:38912
	ds_read_b128 v[200:203], v194 offset:39936
	global_load_lds_dwordx4 v160, s[24:25]
	s_mov_b32 m0, s41
	s_nop 0
	global_load_lds_dwordx4 v164, s[24:25]
	s_waitcnt lgkmcnt(8)
	s_barrier
	s_waitcnt lgkmcnt(0)
	v_mfma_f32_16x16x32_bf16 v[124:127], v[128:131], v[144:147], v[124:127]
	v_mfma_f32_16x16x32_bf16 v[120:123], v[136:139], v[144:147], v[120:123]
	v_mfma_f32_16x16x32_bf16 v[112:115], v[128:131], v[152:155], v[112:115]
	v_mfma_f32_16x16x32_bf16 v[104:107], v[136:139], v[152:155], v[104:107]
	v_mfma_f32_16x16x32_bf16 v[92:95], v[128:131], v[176:179], v[92:95]
	v_mfma_f32_16x16x32_bf16 v[88:91], v[136:139], v[176:179], v[88:91]
	v_mfma_f32_16x16x32_bf16 v[76:79], v[128:131], v[196:199], v[76:79]
	v_mfma_f32_16x16x32_bf16 v[72:75], v[136:139], v[196:199], v[72:75]
	v_mfma_f32_16x16x32_bf16 v[124:127], v[132:135], v[148:151], v[124:127]
	v_mfma_f32_16x16x32_bf16 v[120:123], v[140:143], v[148:151], v[120:123]
	v_mfma_f32_16x16x32_bf16 v[112:115], v[132:135], v[156:159], v[112:115]
	v_mfma_f32_16x16x32_bf16 v[104:107], v[140:143], v[156:159], v[104:107]
	v_mfma_f32_16x16x32_bf16 v[92:95], v[132:135], v[180:183], v[92:95]
	v_mfma_f32_16x16x32_bf16 v[88:91], v[140:143], v[180:183], v[88:91]
	v_mfma_f32_16x16x32_bf16 v[76:79], v[132:135], v[200:203], v[76:79]
	v_mfma_f32_16x16x32_bf16 v[72:75], v[140:143], v[200:203], v[72:75]
	s_barrier
	s_add_i32 s24, 0, 0x1c000
	s_add_i32 s25, s47, s34
	s_mov_b32 m0, s25
	ds_read_b128 v[204:207], v253
	ds_read_b128 v[208:211], v253 offset:1024
	ds_read_b128 v[212:215], v253 offset:2048
	ds_read_b128 v[216:219], v253 offset:3072
	global_load_lds_dwordx4 v162, s[90:91]
	s_add_i32 m0, s25, 0x2000
	s_nop 0
	global_load_lds_dwordx4 v166, s[90:91]
	s_barrier
	s_waitcnt lgkmcnt(0)
	v_mfma_f32_16x16x32_bf16 v[116:119], v[204:207], v[144:147], v[116:119]
	v_mfma_f32_16x16x32_bf16 v[108:111], v[212:215], v[144:147], v[108:111]
	v_mfma_f32_16x16x32_bf16 v[100:103], v[204:207], v[152:155], v[100:103]
	v_mfma_f32_16x16x32_bf16 v[96:99], v[212:215], v[152:155], v[96:99]
	v_mfma_f32_16x16x32_bf16 v[84:87], v[204:207], v[176:179], v[84:87]
	v_mfma_f32_16x16x32_bf16 v[80:83], v[212:215], v[176:179], v[80:83]
	v_mfma_f32_16x16x32_bf16 v[68:71], v[204:207], v[196:199], v[68:71]
	v_mfma_f32_16x16x32_bf16 v[64:67], v[212:215], v[196:199], v[64:67]
	v_mfma_f32_16x16x32_bf16 v[116:119], v[208:211], v[148:151], v[116:119]
	v_mfma_f32_16x16x32_bf16 v[108:111], v[216:219], v[148:151], v[108:111]
	v_mfma_f32_16x16x32_bf16 v[100:103], v[208:211], v[156:159], v[100:103]
	v_mfma_f32_16x16x32_bf16 v[96:99], v[216:219], v[156:159], v[96:99]
	v_mfma_f32_16x16x32_bf16 v[84:87], v[208:211], v[180:183], v[84:87]
	v_mfma_f32_16x16x32_bf16 v[80:83], v[216:219], v[180:183], v[80:83]
	v_mfma_f32_16x16x32_bf16 v[68:71], v[208:211], v[200:203], v[68:71]
	v_mfma_f32_16x16x32_bf16 v[64:67], v[216:219], v[200:203], v[64:67]
	s_barrier
	s_mov_b32 m0, s28
	ds_read_b128 v[144:147], v194 offset:49152
	ds_read_b128 v[148:151], v194 offset:50176
	ds_read_b128 v[152:155], v194 offset:51200
	ds_read_b128 v[156:159], v194 offset:52224
	ds_read_b128 v[176:179], v194 offset:53248
	ds_read_b128 v[180:183], v194 offset:54272
	ds_read_b128 v[196:199], v194 offset:55296
	ds_read_b128 v[200:203], v194 offset:56320
	global_load_lds_dwordx4 v160, s[92:93]
	s_mov_b32 m0, s29
	s_nop 0
	global_load_lds_dwordx4 v164, s[92:93]
	s_barrier
	s_waitcnt lgkmcnt(0)
	v_mfma_f32_16x16x32_bf16 v[60:63], v[128:131], v[144:147], v[60:63]
	v_mfma_f32_16x16x32_bf16 v[56:59], v[136:139], v[144:147], v[56:59]
	v_mfma_f32_16x16x32_bf16 v[48:51], v[128:131], v[152:155], v[48:51]
	v_mfma_f32_16x16x32_bf16 v[40:43], v[136:139], v[152:155], v[40:43]
	v_mfma_f32_16x16x32_bf16 v[32:35], v[128:131], v[176:179], v[32:35]
	v_mfma_f32_16x16x32_bf16 v[24:27], v[136:139], v[176:179], v[24:27]
	v_mfma_f32_16x16x32_bf16 v[16:19], v[128:131], v[196:199], v[16:19]
	v_mfma_f32_16x16x32_bf16 v[8:11], v[136:139], v[196:199], v[8:11]
	v_mfma_f32_16x16x32_bf16 v[60:63], v[132:135], v[148:151], v[60:63]
	v_mfma_f32_16x16x32_bf16 v[56:59], v[140:143], v[148:151], v[56:59]
	v_mfma_f32_16x16x32_bf16 v[48:51], v[132:135], v[156:159], v[48:51]
	v_mfma_f32_16x16x32_bf16 v[40:43], v[140:143], v[156:159], v[40:43]
	v_mfma_f32_16x16x32_bf16 v[32:35], v[132:135], v[180:183], v[32:35]
	v_mfma_f32_16x16x32_bf16 v[24:27], v[140:143], v[180:183], v[24:27]
	v_mfma_f32_16x16x32_bf16 v[16:19], v[132:135], v[200:203], v[16:19]
	v_mfma_f32_16x16x32_bf16 v[8:11], v[140:143], v[200:203], v[8:11]
	s_barrier
; #define PG8_STAGE(bufoff, gbase, voff) do { _Pragma("unroll") for (int _i = 0; _i < 2; ++_i) \
;         __builtin_amdgcn_global_load_lds((const unsigned*)((const char*)(gbase) + (voff)[_i]), (LAS unsigned*)(lds + (bufoff) + ldsw + _i * 8192), 16, 0, 0); } while (0)
; #define PG8_LDA(dst, b, h) do { _Pragma("unroll") for (int m = 0; m < 4; ++m) _Pragma("unroll") for (int k = 0; k < 2; ++k) dst[m][k] = *(const LAS bf16x8*)(lds + PG8_SA(b, h) + aoff + m * 2048 + k * 1024); } while (0)
; #define PG8_LDB(dst, b, h) do { _Pragma("unroll") for (int n = 0; n < 2; ++n) _Pragma("unroll") for (int k = 0; k < 2; ++k) dst[n][k] = *(const LAS bf16x8*)(lds + PG8_SB(b, h) + boff + n * 2048 + k * 1024); } while (0)
; #define PG8_WAIT_V(n) asm volatile("s_waitcnt vmcnt(" #n ")" ::: "memory")
; #define PG8_WAIT_L(n) asm volatile("s_waitcnt lgkmcnt(" #n ")" ::: "memory")
; #define PG8_BAR __builtin_amdgcn_s_barrier()
; #define PG8_SCHED __builtin_amdgcn_sched_barrier(0)
; template <class Epi, class Ptrs>
; __device__ __forceinline__ void gemm_phase(LAS unsigned char* lds, const int K, const StaticOrder& S, const Ptrs& P, const Epi& E) {
;     ...
;             PG8_LDB(B0, 0, 0); PG8_SCHED; PG8_LDA(At, 0, 0); PG8_STAGE(PG8_SA(1, 1), a1 + hstep, voffA);
;             PG8_WAIT_L(8); PG8_BAR; PG8_WAIT_L(0); PG8_MMA(0, 0, At, B0); PG8_BAR; PG8_SCHED;
;             PG8_LDB(B1, 0, 1); PG8_STAGE(PG8_SB(0, 0), b2, voffB);
;             PG8_BAR; PG8_WAIT_L(0); PG8_MMA(0, 1, At, B1); PG8_BAR;
;             PG8_LDA(At, 0, 1); PG8_STAGE(PG8_SA(0, 0), a2, voffA);
;             PG8_BAR; PG8_WAIT_L(0); PG8_MMA(1, 0, At, B0); PG8_BAR; PG8_SCHED;
;             PG8_STAGE(PG8_SB(0, 1), b2 + hstep, voffB);
;             PG8_WAIT_V(6); PG8_BAR; PG8_MMA(1, 1, At, B1); PG8_BAR;
;             PG8_LDB(B0, 1, 0); PG8_SCHED; PG8_LDA(At, 1, 0); PG8_STAGE(PG8_SA(0, 1), a2 + hstep, voffA);
;             PG8_WAIT_L(8); PG8_BAR; PG8_WAIT_L(0); PG8_MMA(0, 0, At, B0); PG8_BAR; PG8_SCHED;
;             PG8_LDB(B1, 1, 1); PG8_STAGE(PG8_SB(1, 0), b3, voffB);
;             PG8_BAR; PG8_WAIT_L(0); PG8_MMA(0, 1, At, B1); PG8_BAR;
;             PG8_LDA(At, 1, 1); PG8_STAGE(PG8_SA(1, 0), a3, voffA);
;             PG8_BAR; PG8_WAIT_L(0); PG8_MMA(1, 0, At, B0); PG8_BAR; PG8_SCHED;
;             PG8_STAGE(PG8_SB(1, 1), b3 + hstep, voffB);
;             PG8_WAIT_V(6); PG8_BAR; PG8_MMA(1, 1, At, B1); PG8_BAR;
	s_add_u32 s22, s22, 0x100080
	s_addc_u32 s23, s23, 0
	s_add_i32 s24, s24, s34
	s_mov_b32 m0, s24
	s_nop 0
	global_load_lds_dwordx4 v162, s[22:23]
	s_add_i32 m0, s24, 0x2000
	s_nop 0
	global_load_lds_dwordx4 v166, s[22:23]
	s_waitcnt vmcnt(6)
	s_barrier
	v_mfma_f32_16x16x32_bf16 v[52:55], v[204:207], v[144:147], v[52:55]
	v_mfma_f32_16x16x32_bf16 v[44:47], v[212:215], v[144:147], v[44:47]
	v_mfma_f32_16x16x32_bf16 v[36:39], v[204:207], v[152:155], v[36:39]
	v_mfma_f32_16x16x32_bf16 v[28:31], v[212:215], v[152:155], v[28:31]
	v_mfma_f32_16x16x32_bf16 v[20:23], v[204:207], v[176:179], v[20:23]
	v_mfma_f32_16x16x32_bf16 v[12:15], v[212:215], v[176:179], v[12:15]
	v_mfma_f32_16x16x32_bf16 v[4:7], v[204:207], v[196:199], v[4:7]
	v_mfma_f32_16x16x32_bf16 v[0:3], v[212:215], v[196:199], v[0:3]
	v_mfma_f32_16x16x32_bf16 v[52:55], v[208:211], v[148:151], v[52:55]
	v_mfma_f32_16x16x32_bf16 v[44:47], v[216:219], v[148:151], v[44:47]
	v_mfma_f32_16x16x32_bf16 v[36:39], v[208:211], v[156:159], v[36:39]
	v_mfma_f32_16x16x32_bf16 v[28:31], v[216:219], v[156:159], v[28:31]
	v_mfma_f32_16x16x32_bf16 v[20:23], v[208:211], v[180:183], v[20:23]
	v_mfma_f32_16x16x32_bf16 v[12:15], v[216:219], v[180:183], v[12:15]
	v_mfma_f32_16x16x32_bf16 v[4:7], v[208:211], v[200:203], v[4:7]
	v_mfma_f32_16x16x32_bf16 v[0:3], v[216:219], v[200:203], v[0:3]
	s_barrier
	s_add_i32 s46, s46, 2
	s_add_u32 s20, s20, 0x100
	s_addc_u32 s21, s21, 0
	s_add_u32 s11, s11, 0x100
	s_addc_u32 s13, s13, 0
	s_cmp_gt_u32 s46, 61
.LBB0_522:
	ds_read_b128 v[128:131], v193
	ds_read_b128 v[132:135], v193 offset:1024
	ds_read_b128 v[136:139], v193 offset:2048
	ds_read_b128 v[140:143], v193 offset:3072
	s_add_u32 s22, s20, 0xfff00080
	s_addc_u32 s23, s21, -1
	s_cmp_eq_u32 s46, 60
	s_cselect_b32 s25, s5, s23
	s_cselect_b32 s24, s4, s22
	s_cselect_b32 s23, s15, s13
	s_cselect_b32 s22, s14, s11
	s_add_i32 m0, s17, 0xc000
	ds_read_b128 v[144:147], v194
	ds_read_b128 v[148:151], v194 offset:1024
	ds_read_b128 v[152:155], v194 offset:2048
	ds_read_b128 v[156:159], v194 offset:3072
	ds_read_b128 v[176:179], v194 offset:4096
	ds_read_b128 v[180:183], v194 offset:5120
	ds_read_b128 v[196:199], v194 offset:6144
	ds_read_b128 v[200:203], v194 offset:7168
	global_load_lds_dwordx4 v168, s[20:21]
	s_add_i32 m0, s17, 0xe000
	s_nop 0
	global_load_lds_dwordx4 v170, s[20:21]
	s_waitcnt lgkmcnt(8)
	s_barrier
	s_waitcnt lgkmcnt(0)
	v_mfma_f32_16x16x32_bf16 v[124:127], v[128:131], v[144:147], v[124:127]
	v_mfma_f32_16x16x32_bf16 v[120:123], v[136:139], v[144:147], v[120:123]
	v_mfma_f32_16x16x32_bf16 v[112:115], v[128:131], v[152:155], v[112:115]
	v_mfma_f32_16x16x32_bf16 v[104:107], v[136:139], v[152:155], v[104:107]
	v_mfma_f32_16x16x32_bf16 v[92:95], v[128:131], v[176:179], v[92:95]
	v_mfma_f32_16x16x32_bf16 v[88:91], v[136:139], v[176:179], v[88:91]
	v_mfma_f32_16x16x32_bf16 v[76:79], v[128:131], v[196:199], v[76:79]
	v_mfma_f32_16x16x32_bf16 v[72:75], v[136:139], v[196:199], v[72:75]
	v_mfma_f32_16x16x32_bf16 v[124:127], v[132:135], v[148:151], v[124:127]
	v_mfma_f32_16x16x32_bf16 v[120:123], v[140:143], v[148:151], v[120:123]
	v_mfma_f32_16x16x32_bf16 v[112:115], v[132:135], v[156:159], v[112:115]
	v_mfma_f32_16x16x32_bf16 v[104:107], v[140:143], v[156:159], v[104:107]
	v_mfma_f32_16x16x32_bf16 v[92:95], v[132:135], v[180:183], v[92:95]
	v_mfma_f32_16x16x32_bf16 v[88:91], v[140:143], v[180:183], v[88:91]
	v_mfma_f32_16x16x32_bf16 v[76:79], v[132:135], v[200:203], v[76:79]
	v_mfma_f32_16x16x32_bf16 v[72:75], v[140:143], v[200:203], v[72:75]
	s_barrier
	s_add_i32 s47, s42, s34
	s_add_u32 s90, s22, 0x80
	s_addc_u32 s91, s23, 0
	s_mov_b32 m0, s47
	ds_read_b128 v[204:207], v195
	ds_read_b128 v[208:211], v195 offset:1024
	ds_read_b128 v[212:215], v195 offset:2048
	ds_read_b128 v[216:219], v195 offset:3072
	global_load_lds_dwordx4 v162, s[22:23]
	s_add_i32 m0, s47, 0x2000
	s_nop 0
	global_load_lds_dwordx4 v166, s[22:23]
	s_barrier
	s_waitcnt lgkmcnt(0)
	v_mfma_f32_16x16x32_bf16 v[116:119], v[204:207], v[144:147], v[116:119]
	v_mfma_f32_16x16x32_bf16 v[108:111], v[212:215], v[144:147], v[108:111]
	v_mfma_f32_16x16x32_bf16 v[100:103], v[204:207], v[152:155], v[100:103]
	v_mfma_f32_16x16x32_bf16 v[96:99], v[212:215], v[152:155], v[96:99]
	v_mfma_f32_16x16x32_bf16 v[84:87], v[204:207], v[176:179], v[84:87]
	v_mfma_f32_16x16x32_bf16 v[80:83], v[212:215], v[176:179], v[80:83]
	v_mfma_f32_16x16x32_bf16 v[68:71], v[204:207], v[196:199], v[68:71]
	v_mfma_f32_16x16x32_bf16 v[64:67], v[212:215], v[196:199], v[64:67]
	v_mfma_f32_16x16x32_bf16 v[116:119], v[208:211], v[148:151], v[116:119]
	v_mfma_f32_16x16x32_bf16 v[108:111], v[216:219], v[148:151], v[108:111]
	v_mfma_f32_16x16x32_bf16 v[100:103], v[208:211], v[156:159], v[100:103]
	v_mfma_f32_16x16x32_bf16 v[96:99], v[216:219], v[156:159], v[96:99]
	v_mfma_f32_16x16x32_bf16 v[84:87], v[208:211], v[180:183], v[84:87]
	v_mfma_f32_16x16x32_bf16 v[80:83], v[216:219], v[180:183], v[80:83]
	v_mfma_f32_16x16x32_bf16 v[68:71], v[208:211], v[200:203], v[68:71]
	v_mfma_f32_16x16x32_bf16 v[64:67], v[216:219], v[200:203], v[64:67]
	s_barrier
	s_mov_b32 m0, s17
	s_add_u32 s92, s24, 0x80
	s_addc_u32 s93, s25, 0
	ds_read_b128 v[144:147], v194 offset:16384
	ds_read_b128 v[148:151], v194 offset:17408
	ds_read_b128 v[152:155], v194 offset:18432
	ds_read_b128 v[156:159], v194 offset:19456
	ds_read_b128 v[176:179], v194 offset:20480
	ds_read_b128 v[180:183], v194 offset:21504
	ds_read_b128 v[196:199], v194 offset:22528
	ds_read_b128 v[200:203], v194 offset:23552
	global_load_lds_dwordx4 v160, s[24:25]
	s_mov_b32 m0, s19
	s_nop 0
	global_load_lds_dwordx4 v164, s[24:25]
	s_barrier
; #define PG8_STAGE(bufoff, gbase, voff) do { _Pragma("unroll") for (int _i = 0; _i < 2; ++_i) \
;         __builtin_amdgcn_global_load_lds((const unsigned*)((const char*)(gbase) + (voff)[_i]), (LAS unsigned*)(lds + (bufoff) + ldsw + _i * 8192), 16, 0, 0); } while (0)
; #define PG8_LDA(dst, b, h) do { _Pragma("unroll") for (int m = 0; m < 4; ++m) _Pragma("unroll") for (int k = 0; k < 2; ++k) dst[m][k] = *(const LAS bf16x8*)(lds + PG8_SA(b, h) + aoff + m * 2048 + k * 1024); } while (0)
; #define PG8_LDB(dst, b, h) do { _Pragma("unroll") for (int n = 0; n < 2; ++n) _Pragma("unroll") for (int k = 0; k < 2; ++k) dst[n][k] = *(const LAS bf16x8*)(lds + PG8_SB(b, h) + boff + n * 2048 + k * 1024); } while (0)
; #define PG8_WAIT_V(n) asm volatile("s_waitcnt vmcnt(" #n ")" ::: "memory")
; #define PG8_WAIT_L(n) asm volatile("s_waitcnt lgkmcnt(" #n ")" ::: "memory")
; #define PG8_BAR __builtin_amdgcn_s_barrier()
; #define PG8_SCHED __builtin_amdgcn_sched_barrier(0)
; template <class Epi, class Ptrs>
; __device__ __forceinline__ void gemm_phase(LAS unsigned char* lds, const int K, const StaticOrder& S, const Ptrs& P, const Epi& E) {
;     ...
;             PG8_LDB(B0, 0, 0); PG8_SCHED; PG8_LDA(At, 0, 0); PG8_STAGE(PG8_SA(1, 1), a1 + hstep, voffA);
;             PG8_WAIT_L(8); PG8_BAR; PG8_WAIT_L(0); PG8_MMA(0, 0, At, B0); PG8_BAR; PG8_SCHED;
;             PG8_LDB(B1, 0, 1); PG8_STAGE(PG8_SB(0, 0), b2, voffB);
;             PG8_BAR; PG8_WAIT_L(0); PG8_MMA(0, 1, At, B1); PG8_BAR;
;             PG8_LDA(At, 0, 1); PG8_STAGE(PG8_SA(0, 0), a2, voffA);
;             PG8_BAR; PG8_WAIT_L(0); PG8_MMA(1, 0, At, B0); PG8_BAR; PG8_SCHED;
;             PG8_STAGE(PG8_SB(0, 1), b2 + hstep, voffB);
;             PG8_WAIT_V(6); PG8_BAR; PG8_MMA(1, 1, At, B1); PG8_BAR;
;             PG8_LDB(B0, 1, 0); PG8_SCHED; PG8_LDA(At, 1, 0); PG8_STAGE(PG8_SA(0, 1), a2 + hstep, voffA);
;             PG8_WAIT_L(8); PG8_BAR; PG8_WAIT_L(0); PG8_MMA(0, 0, At, B0); PG8_BAR; PG8_SCHED;
;             PG8_LDB(B1, 1, 1); PG8_STAGE(PG8_SB(1, 0), b3, voffB);
;             PG8_BAR; PG8_WAIT_L(0); PG8_MMA(0, 1, At, B1); PG8_BAR;
;             PG8_LDA(At, 1, 1); PG8_STAGE(PG8_SA(1, 0), a3, voffA);
;             PG8_BAR; PG8_WAIT_L(0); PG8_MMA(1, 0, At, B0); PG8_BAR; PG8_SCHED;
;             PG8_STAGE(PG8_SB(1, 1), b3 + hstep, voffB);
;             PG8_WAIT_V(6); PG8_BAR; PG8_MMA(1, 1, At, B1); PG8_BAR;
	s_waitcnt lgkmcnt(0)
	v_mfma_f32_16x16x32_bf16 v[60:63], v[128:131], v[144:147], v[60:63]
	v_mfma_f32_16x16x32_bf16 v[56:59], v[136:139], v[144:147], v[56:59]
	v_mfma_f32_16x16x32_bf16 v[48:51], v[128:131], v[152:155], v[48:51]
	v_mfma_f32_16x16x32_bf16 v[40:43], v[136:139], v[152:155], v[40:43]
	v_mfma_f32_16x16x32_bf16 v[32:35], v[128:131], v[176:179], v[32:35]
	v_mfma_f32_16x16x32_bf16 v[24:27], v[136:139], v[176:179], v[24:27]
	v_mfma_f32_16x16x32_bf16 v[16:19], v[128:131], v[196:199], v[16:19]
	v_mfma_f32_16x16x32_bf16 v[8:11], v[136:139], v[196:199], v[8:11]
	v_mfma_f32_16x16x32_bf16 v[60:63], v[132:135], v[148:151], v[60:63]
	v_mfma_f32_16x16x32_bf16 v[56:59], v[140:143], v[148:151], v[56:59]
	v_mfma_f32_16x16x32_bf16 v[48:51], v[132:135], v[156:159], v[48:51]
	v_mfma_f32_16x16x32_bf16 v[40:43], v[140:143], v[156:159], v[40:43]
	v_mfma_f32_16x16x32_bf16 v[32:35], v[132:135], v[180:183], v[32:35]
	v_mfma_f32_16x16x32_bf16 v[24:27], v[140:143], v[180:183], v[24:27]
	v_mfma_f32_16x16x32_bf16 v[16:19], v[132:135], v[200:203], v[16:19]
	v_mfma_f32_16x16x32_bf16 v[8:11], v[140:143], v[200:203], v[8:11]
	s_barrier
	s_add_u32 s48, s22, 0x100000
	s_addc_u32 s49, s23, 0
	s_add_i32 s47, s43, s34
	s_mov_b32 m0, s47
	s_nop 0
	global_load_lds_dwordx4 v162, s[48:49]
	s_add_i32 m0, s47, 0x2000
	s_nop 0
	global_load_lds_dwordx4 v166, s[48:49]
	s_waitcnt vmcnt(6)
	s_barrier
	v_mfma_f32_16x16x32_bf16 v[52:55], v[204:207], v[144:147], v[52:55]
	v_mfma_f32_16x16x32_bf16 v[44:47], v[212:215], v[144:147], v[44:47]
	v_mfma_f32_16x16x32_bf16 v[36:39], v[204:207], v[152:155], v[36:39]
	v_mfma_f32_16x16x32_bf16 v[28:31], v[212:215], v[152:155], v[28:31]
	v_mfma_f32_16x16x32_bf16 v[20:23], v[204:207], v[176:179], v[20:23]
	v_mfma_f32_16x16x32_bf16 v[12:15], v[212:215], v[176:179], v[12:15]
	v_mfma_f32_16x16x32_bf16 v[4:7], v[204:207], v[196:199], v[4:7]
	v_mfma_f32_16x16x32_bf16 v[0:3], v[212:215], v[196:199], v[0:3]
	v_mfma_f32_16x16x32_bf16 v[52:55], v[208:211], v[148:151], v[52:55]
	v_mfma_f32_16x16x32_bf16 v[44:47], v[216:219], v[148:151], v[44:47]
	v_mfma_f32_16x16x32_bf16 v[36:39], v[208:211], v[156:159], v[36:39]
	v_mfma_f32_16x16x32_bf16 v[28:31], v[216:219], v[156:159], v[28:31]
	v_mfma_f32_16x16x32_bf16 v[20:23], v[208:211], v[180:183], v[20:23]
	v_mfma_f32_16x16x32_bf16 v[12:15], v[216:219], v[180:183], v[12:15]
	v_mfma_f32_16x16x32_bf16 v[4:7], v[208:211], v[200:203], v[4:7]
	v_mfma_f32_16x16x32_bf16 v[0:3], v[216:219], v[200:203], v[0:3]
	s_barrier
	s_add_i32 s47, 0, 0x18000
	ds_read_b128 v[128:131], v252
	ds_read_b128 v[132:135], v252 offset:1024
	ds_read_b128 v[136:139], v252 offset:2048
	ds_read_b128 v[140:143], v252 offset:3072
	s_add_u32 s24, s24, 0x100000
	s_addc_u32 s25, s25, 0
	s_mov_b32 m0, s40
	ds_read_b128 v[144:147], v194 offset:32768
	ds_read_b128 v[148:151], v194 offset:33792
	ds_read_b128 v[152:155], v194 offset:34816
	ds_read_b128 v[156:159], v194 offset:35840
	ds_read_b128 v[176:179], v194 offset:36864
	ds_read_b128 v[180:183], v194 offset:37888
	ds_read_b128 v[196:199], v194 offset:38912
	ds_read_b128 v[200:203], v194 offset:39936
	global_load_lds_dwordx4 v160, s[24:25]
	s_mov_b32 m0, s41
	s_nop 0
	global_load_lds_dwordx4 v164, s[24:25]
	s_waitcnt lgkmcnt(8)
	s_barrier
	s_waitcnt lgkmcnt(0)
	v_mfma_f32_16x16x32_bf16 v[124:127], v[128:131], v[144:147], v[124:127]
	v_mfma_f32_16x16x32_bf16 v[120:123], v[136:139], v[144:147], v[120:123]
	v_mfma_f32_16x16x32_bf16 v[112:115], v[128:131], v[152:155], v[112:115]
	v_mfma_f32_16x16x32_bf16 v[104:107], v[136:139], v[152:155], v[104:107]
	v_mfma_f32_16x16x32_bf16 v[92:95], v[128:131], v[176:179], v[92:95]
	v_mfma_f32_16x16x32_bf16 v[88:91], v[136:139], v[176:179], v[88:91]
	v_mfma_f32_16x16x32_bf16 v[76:79], v[128:131], v[196:199], v[76:79]
	v_mfma_f32_16x16x32_bf16 v[72:75], v[136:139], v[196:199], v[72:75]
	v_mfma_f32_16x16x32_bf16 v[124:127], v[132:135], v[148:151], v[124:127]
	v_mfma_f32_16x16x32_bf16 v[120:123], v[140:143], v[148:151], v[120:123]
	v_mfma_f32_16x16x32_bf16 v[112:115], v[132:135], v[156:159], v[112:115]
	v_mfma_f32_16x16x32_bf16 v[104:107], v[140:143], v[156:159], v[104:107]
	v_mfma_f32_16x16x32_bf16 v[92:95], v[132:135], v[180:183], v[92:95]
	v_mfma_f32_16x16x32_bf16 v[88:91], v[140:143], v[180:183], v[88:91]
	v_mfma_f32_16x16x32_bf16 v[76:79], v[132:135], v[200:203], v[76:79]
	v_mfma_f32_16x16x32_bf16 v[72:75], v[140:143], v[200:203], v[72:75]
	s_barrier
	s_add_i32 s24, 0, 0x1c000
	s_add_i32 s25, s47, s34
	s_mov_b32 m0, s25
	ds_read_b128 v[204:207], v253
	ds_read_b128 v[208:211], v253 offset:1024
	ds_read_b128 v[212:215], v253 offset:2048
	ds_read_b128 v[216:219], v253 offset:3072
	global_load_lds_dwordx4 v162, s[90:91]
	s_add_i32 m0, s25, 0x2000
	s_nop 0
	global_load_lds_dwordx4 v166, s[90:91]
	s_barrier
	s_waitcnt lgkmcnt(0)
	v_mfma_f32_16x16x32_bf16 v[116:119], v[204:207], v[144:147], v[116:119]
	v_mfma_f32_16x16x32_bf16 v[108:111], v[212:215], v[144:147], v[108:111]
	v_mfma_f32_16x16x32_bf16 v[100:103], v[204:207], v[152:155], v[100:103]
	v_mfma_f32_16x16x32_bf16 v[96:99], v[212:215], v[152:155], v[96:99]
	v_mfma_f32_16x16x32_bf16 v[84:87], v[204:207], v[176:179], v[84:87]
	v_mfma_f32_16x16x32_bf16 v[80:83], v[212:215], v[176:179], v[80:83]
	v_mfma_f32_16x16x32_bf16 v[68:71], v[204:207], v[196:199], v[68:71]
	v_mfma_f32_16x16x32_bf16 v[64:67], v[212:215], v[196:199], v[64:67]
	v_mfma_f32_16x16x32_bf16 v[116:119], v[208:211], v[148:151], v[116:119]
	v_mfma_f32_16x16x32_bf16 v[108:111], v[216:219], v[148:151], v[108:111]
	v_mfma_f32_16x16x32_bf16 v[100:103], v[208:211], v[156:159], v[100:103]
	v_mfma_f32_16x16x32_bf16 v[96:99], v[216:219], v[156:159], v[96:99]
	v_mfma_f32_16x16x32_bf16 v[84:87], v[208:211], v[180:183], v[84:87]
	v_mfma_f32_16x16x32_bf16 v[80:83], v[216:219], v[180:183], v[80:83]
	v_mfma_f32_16x16x32_bf16 v[68:71], v[208:211], v[200:203], v[68:71]
	v_mfma_f32_16x16x32_bf16 v[64:67], v[216:219], v[200:203], v[64:67]
	s_barrier
; #define PG8_STAGE(bufoff, gbase, voff) do { _Pragma("unroll") for (int _i = 0; _i < 2; ++_i) \
;         __builtin_amdgcn_global_load_lds((const unsigned*)((const char*)(gbase) + (voff)[_i]), (LAS unsigned*)(lds + (bufoff) + ldsw + _i * 8192), 16, 0, 0); } while (0)
; #define PG8_LDA(dst, b, h) do { _Pragma("unroll") for (int m = 0; m < 4; ++m) _Pragma("unroll") for (int k = 0; k < 2; ++k) dst[m][k] = *(const LAS bf16x8*)(lds + PG8_SA(b, h) + aoff + m * 2048 + k * 1024); } while (0)
; #define PG8_MMA(ai, bj, At, Bt) do { __builtin_amdgcn_s_setprio(1); _Pragma("unroll") for (int m = 0; m < 4; ++m) _Pragma("unroll") for (int n = 0; n < 2; ++n) _Pragma("unroll") for (int k = 0; k < 2; ++k) \
;         acc[ai][bj][m][n] = __builtin_amdgcn_mfma_f32_16x16x32_bf16(Bt[n][k], At[m][k], acc[ai][bj][m][n], 0, 0, 0); __builtin_amdgcn_s_setprio(0); } while (0)
; #define PG8_WAIT_V(n) asm volatile("s_waitcnt vmcnt(" #n ")" ::: "memory")
; #define PG8_WAIT_L(n) asm volatile("s_waitcnt lgkmcnt(" #n ")" ::: "memory")
; #define PG8_BAR __builtin_amdgcn_s_barrier()
; #define PG8_SCHED __builtin_amdgcn_sched_barrier(0)
; template <class Epi, class Ptrs>
; __device__ __forceinline__ void gemm_phase(LAS unsigned char* lds, const int K, const StaticOrder& S, const Ptrs& P, const Epi& E) {
;     ...
;             PG8_LDA(At, 1, 1); PG8_STAGE(PG8_SA(1, 0), a3, voffA);
;             PG8_BAR; PG8_WAIT_L(0); PG8_MMA(1, 0, At, B0); PG8_BAR; PG8_SCHED;
;             PG8_STAGE(PG8_SB(1, 1), b3 + hstep, voffB);
;             PG8_WAIT_V(6); PG8_BAR; PG8_MMA(1, 1, At, B1); PG8_BAR;
;         }
;     __device__ __forceinline__ void operator()(const f32x4 (&acc)[2][2][4][2], const Unit& u, int ui, int wr, int wc, int fr, int fq) const {
;         const int rl0 = wr * 64 + fr, col0 = u.pn * 256 + wc * 32 + 8 * fq;
;         u32x4 xv[2][4][2];
; #pragma unroll
;         for (int ai = 0; ai < 2; ++ai)
; #pragma unroll
;             for (int m = 0; m < 4; ++m)
; #pragma unroll
;                 for (int bj = 0; bj < 2; ++bj) xv[ai][m][bj] = *(const u32x4*)(xb + (size_t)(u.pm * 256 + rl0 + ai * 128 + m * 16) * DM + col0 + bj * 128);
	s_mov_b32 m0, s28
	ds_read_b128 v[144:147], v194 offset:49152
	ds_read_b128 v[148:151], v194 offset:50176
	ds_read_b128 v[152:155], v194 offset:51200
	ds_read_b128 v[156:159], v194 offset:52224
	ds_read_b128 v[176:179], v194 offset:53248
	ds_read_b128 v[180:183], v194 offset:54272
	ds_read_b128 v[196:199], v194 offset:55296
	ds_read_b128 v[200:203], v194 offset:56320
	global_load_lds_dwordx4 v160, s[92:93]
	s_mov_b32 m0, s29
	s_nop 0
	global_load_lds_dwordx4 v164, s[92:93]
	s_barrier
	s_waitcnt lgkmcnt(0)
	v_mfma_f32_16x16x32_bf16 v[60:63], v[128:131], v[144:147], v[60:63]
	v_mfma_f32_16x16x32_bf16 v[56:59], v[136:139], v[144:147], v[56:59]
	v_mfma_f32_16x16x32_bf16 v[48:51], v[128:131], v[152:155], v[48:51]
	v_mfma_f32_16x16x32_bf16 v[40:43], v[136:139], v[152:155], v[40:43]
	v_mfma_f32_16x16x32_bf16 v[32:35], v[128:131], v[176:179], v[32:35]
	v_mfma_f32_16x16x32_bf16 v[24:27], v[136:139], v[176:179], v[24:27]
	v_mfma_f32_16x16x32_bf16 v[16:19], v[128:131], v[196:199], v[16:19]
	v_mfma_f32_16x16x32_bf16 v[8:11], v[136:139], v[196:199], v[8:11]
	v_mfma_f32_16x16x32_bf16 v[60:63], v[132:135], v[148:151], v[60:63]
	v_mfma_f32_16x16x32_bf16 v[56:59], v[140:143], v[148:151], v[56:59]
	v_mfma_f32_16x16x32_bf16 v[48:51], v[132:135], v[156:159], v[48:51]
	v_mfma_f32_16x16x32_bf16 v[40:43], v[140:143], v[156:159], v[40:43]
	v_mfma_f32_16x16x32_bf16 v[32:35], v[132:135], v[180:183], v[32:35]
	v_mfma_f32_16x16x32_bf16 v[24:27], v[140:143], v[180:183], v[24:27]
	v_mfma_f32_16x16x32_bf16 v[16:19], v[132:135], v[200:203], v[16:19]
	v_mfma_f32_16x16x32_bf16 v[8:11], v[140:143], v[200:203], v[8:11]
	s_barrier
	s_add_u32 s22, s22, 0x100080
	s_addc_u32 s23, s23, 0
	s_add_i32 s24, s24, s34
	s_mov_b32 m0, s24
	s_nop 0
	global_load_lds_dwordx4 v162, s[22:23]
	s_add_i32 m0, s24, 0x2000
	s_nop 0
	global_load_lds_dwordx4 v166, s[22:23]
	s_waitcnt vmcnt(6)
	s_barrier
	v_mfma_f32_16x16x32_bf16 v[52:55], v[204:207], v[144:147], v[52:55]
	v_mfma_f32_16x16x32_bf16 v[44:47], v[212:215], v[144:147], v[44:47]
	v_mfma_f32_16x16x32_bf16 v[36:39], v[204:207], v[152:155], v[36:39]
	v_mfma_f32_16x16x32_bf16 v[28:31], v[212:215], v[152:155], v[28:31]
	v_mfma_f32_16x16x32_bf16 v[20:23], v[204:207], v[176:179], v[20:23]
	v_mfma_f32_16x16x32_bf16 v[12:15], v[212:215], v[176:179], v[12:15]
	v_mfma_f32_16x16x32_bf16 v[4:7], v[204:207], v[196:199], v[4:7]
	v_mfma_f32_16x16x32_bf16 v[0:3], v[212:215], v[196:199], v[0:3]
	v_mfma_f32_16x16x32_bf16 v[52:55], v[208:211], v[148:151], v[52:55]
	v_mfma_f32_16x16x32_bf16 v[44:47], v[216:219], v[148:151], v[44:47]
	v_mfma_f32_16x16x32_bf16 v[36:39], v[208:211], v[156:159], v[36:39]
	v_mfma_f32_16x16x32_bf16 v[28:31], v[216:219], v[156:159], v[28:31]
	v_mfma_f32_16x16x32_bf16 v[20:23], v[208:211], v[180:183], v[20:23]
	v_mfma_f32_16x16x32_bf16 v[12:15], v[216:219], v[180:183], v[12:15]
	v_mfma_f32_16x16x32_bf16 v[4:7], v[208:211], v[200:203], v[4:7]
	v_mfma_f32_16x16x32_bf16 v[0:3], v[216:219], v[200:203], v[0:3]
	s_barrier
	s_add_i32 s46, s46, 2
	s_add_u32 s20, s20, 0x100
	s_addc_u32 s21, s21, 0
	s_add_u32 s11, s11, 0x100
	s_addc_u32 s13, s13, 0
	s_cmp_gt_u32 s46, 61
	s_cbranch_scc0 .LBB0_522
	s_lshl_b32 s11, s18, 8
	v_lshl_or_b32 v128, s16, 8, v191
	v_add_u32_e32 v130, s11, v186
	v_ashrrev_i32_e32 v129, 31, v128
	v_ashrrev_i32_e32 v131, 31, v130
	v_lshl_add_u64 v[132:133], v[128:129], 1, s[6:7]
	v_lshlrev_b64 v[134:135], 11, v[130:131]
	v_lshl_add_u64 v[134:135], v[132:133], 0, v[134:135]
	global_load_dwordx4 v[198:201], v[134:135], off
	global_load_dwordx4 v[202:205], v[134:135], off offset:256
	v_or_b32_e32 v134, 16, v130
	v_ashrrev_i32_e32 v135, 31, v134
	v_lshlrev_b64 v[134:135], 11, v[134:135]
	v_lshl_add_u64 v[134:135], v[132:133], 0, v[134:135]
	global_load_dwordx4 v[206:209], v[134:135], off
	global_load_dwordx4 v[210:213], v[134:135], off offset:256
	v_or_b32_e32 v136, 32, v130
	v_ashrrev_i32_e32 v137, 31, v136
	v_or_b32_e32 v138, 48, v130
	v_add_u32_e32 v184, 0x80, v130
	v_add_u32_e32 v182, 0x90, v130
	v_add_u32_e32 v180, 0xa0, v130
	v_add_u32_e32 v178, 0xb0, v130
	v_lshlrev_b64 v[176:177], 2, v[128:129]
	v_lshlrev_b64 v[128:129], 12, v[130:131]
	v_lshlrev_b64 v[130:131], 11, v[136:137]
	v_lshl_add_u64 v[130:131], v[132:133], 0, v[130:131]
	global_load_dwordx4 v[214:217], v[130:131], off
	v_ashrrev_i32_e32 v139, 31, v138
	v_ashrrev_i32_e32 v185, 31, v184
	v_ashrrev_i32_e32 v183, 31, v182
	v_ashrrev_i32_e32 v181, 31, v180
	v_ashrrev_i32_e32 v179, 31, v178
	v_lshlrev_b64 v[134:135], 11, v[138:139]
	v_lshlrev_b64 v[136:137], 11, v[184:185]
	v_lshlrev_b64 v[138:139], 11, v[182:183]
	v_lshl_add_u32 v196, s45, 10, v192
	v_lshlrev_b64 v[140:141], 11, v[180:181]
	v_lshlrev_b64 v[142:143], 11, v[178:179]
	v_lshl_add_u64 v[128:129], s[26:27], 0, v[128:129]
	v_lshl_add_u64 v[134:135], v[132:133], 0, v[134:135]
	v_lshl_add_u64 v[136:137], v[132:133], 0, v[136:137]
	v_lshl_add_u64 v[138:139], v[132:133], 0, v[138:139]
	ds_read2_b32 v[230:231], v196 offset1:16
	v_lshl_add_u64 v[234:235], v[132:133], 0, v[140:141]
	v_lshl_add_u64 v[236:237], v[132:133], 0, v[142:143]
	v_lshl_add_u64 v[238:239], v[128:129], 0, v[176:177]
	global_load_dwordx4 v[218:221], v[130:131], off offset:256
	global_load_dwordx4 v[222:225], v[134:135], off
	global_load_dwordx4 v[226:229], v[134:135], off offset:256
	global_load_dwordx4 v[156:159], v[136:137], off
	global_load_dwordx4 v[152:155], v[136:137], off offset:256
	global_load_dwordx4 v[148:151], v[138:139], off
	global_load_dwordx4 v[144:147], v[138:139], off offset:256
	global_load_dwordx4 v[140:143], v[234:235], off
	s_nop 0
	global_load_dwordx4 v[136:139], v[234:235], off offset:256
	global_load_dwordx4 v[132:135], v[236:237], off
	global_load_dwordx4 v[128:131], v[236:237], off offset:256
	v_add_u32_e32 v232, s11, v188
	v_ashrrev_i32_e32 v233, 31, v232
	s_and_b64 vcc, exec, s[0:1]
	s_mov_b32 s16, s10
	s_mov_b32 s18, s12
	s_mov_b64 s[20:21], s[4:5]
	s_mov_b64 s[22:23], s[14:15]
	s_mov_b32 s45, s44
	s_waitcnt vmcnt(0)
; __device__ __forceinline__ float bf_lo(unsigned w) { return __uint_as_float(w << 16); }
; __device__ __forceinline__ float bf_hi(unsigned w) { return __uint_as_float(w & 0xffff0000u); }
;     __device__ __forceinline__ void operator()(const f32x4 (&acc)[2][2][4][2], const Unit& u, int ui, int wr, int wc, int fr, int fq) const {
;     ...
;         for (int ai = 0; ai < 2; ++ai)
; #pragma unroll
;             for (int m = 0; m < 4; ++m) { const int rl = rl0 + ai * 128 + m * 16; float* rowp = out + (size_t)(u.pm * 256 + rl) * DM + col0;
;                 const float r2 = tab[ui * 256 + rl];
; #pragma unroll
;                 for (int bj = 0; bj < 2; ++bj) { const u32x4 x = xv[ai][m][bj];
;                     const f32x4 x0 = {bf_lo(x.x), bf_hi(x.x), bf_lo(x.y), bf_hi(x.y)}, x1 = {bf_lo(x.z), bf_hi(x.z), bf_lo(x.w), bf_hi(x.w)};
;                     *(f32x4*)(rowp + bj * 128) = acc[ai][bj][m][0] * r2 + x0; *(f32x4*)(rowp + bj * 128 + 4) = acc[ai][bj][m][1] * r2 + x1; } }
	v_lshlrev_b32_e32 v234, 16, v198
	v_and_b32_e32 v235, 0xffff0000, v198
	v_lshlrev_b32_e32 v198, 16, v199
	v_and_b32_e32 v199, 0xffff0000, v199
	v_lshlrev_b32_e32 v242, 16, v204
	v_and_b32_e32 v243, 0xffff0000, v204
	v_lshlrev_b32_e32 v236, 16, v200
	v_and_b32_e32 v237, 0xffff0000, v200
	v_lshlrev_b32_e32 v200, 16, v201
	v_and_b32_e32 v201, 0xffff0000, v201
	v_lshlrev_b32_e32 v240, 16, v202
	v_and_b32_e32 v241, 0xffff0000, v202
	v_lshlrev_b32_e32 v202, 16, v203
	v_and_b32_e32 v203, 0xffff0000, v203
	v_lshlrev_b32_e32 v204, 16, v205
	v_and_b32_e32 v205, 0xffff0000, v205
	s_waitcnt lgkmcnt(0)
	v_pk_fma_f32 v[126:127], v[126:127], v[230:231], v[198:199] op_sel_hi:[1,0,1]
	v_pk_fma_f32 v[124:125], v[124:125], v[230:231], v[234:235] op_sel_hi:[1,0,1]
	v_pk_fma_f32 v[108:109], v[108:109], v[230:231], v[242:243] op_sel_hi:[1,0,1]
	v_pk_fma_f32 v[122:123], v[122:123], v[230:231], v[200:201] op_sel_hi:[1,0,1]
	v_pk_fma_f32 v[120:121], v[120:121], v[230:231], v[236:237] op_sel_hi:[1,0,1]
	v_pk_fma_f32 v[118:119], v[118:119], v[230:231], v[202:203] op_sel_hi:[1,0,1]
	v_pk_fma_f32 v[116:117], v[116:117], v[230:231], v[240:241] op_sel_hi:[1,0,1]
	v_pk_fma_f32 v[110:111], v[110:111], v[230:231], v[204:205] op_sel_hi:[1,0,1]
	global_store_dwordx4 v[238:239], v[124:127], off
	global_store_dwordx4 v[238:239], v[120:123], off offset:16
	global_store_dwordx4 v[238:239], v[116:119], off offset:512
	global_store_dwordx4 v[238:239], v[108:111], off offset:528
	v_mov_b32_e32 v122, v231
	v_lshlrev_b32_e32 v118, 16, v208
	v_lshlrev_b64 v[108:109], 12, v[232:233]
	v_lshl_add_u64 v[108:109], s[26:27], 0, v[108:109]
	v_lshl_add_u64 v[116:117], v[108:109], 0, v[176:177]
	v_lshlrev_b32_e32 v108, 16, v206
	v_and_b32_e32 v109, 0xffff0000, v206
	v_lshlrev_b32_e32 v110, 16, v207
	v_and_b32_e32 v111, 0xffff0000, v207
	v_pk_fma_f32 v[110:111], v[114:115], v[122:123], v[110:111] op_sel_hi:[1,0,1]
	v_pk_fma_f32 v[108:109], v[112:113], v[122:123], v[108:109] op_sel_hi:[1,0,1]
	global_store_dwordx4 v[116:117], v[108:111], off
	v_and_b32_e32 v119, 0xffff0000, v208
	v_lshlrev_b32_e32 v120, 16, v209
	v_lshlrev_b32_e32 v108, 16, v212
	v_and_b32_e32 v109, 0xffff0000, v212
	v_lshlrev_b32_e32 v110, 16, v213
	v_and_b32_e32 v111, 0xffff0000, v213
	v_pk_fma_f32 v[98:99], v[98:99], v[122:123], v[110:111] op_sel_hi:[1,0,1]
	v_pk_fma_f32 v[96:97], v[96:97], v[122:123], v[108:109] op_sel_hi:[1,0,1]
	v_and_b32_e32 v121, 0xffff0000, v209
	global_store_dwordx4 v[116:117], v[96:99], off offset:528
	ds_read2_b32 v[98:99], v196 offset0:32 offset1:48
	v_pk_fma_f32 v[106:107], v[106:107], v[122:123], v[120:121] op_sel_hi:[1,0,1]
	v_pk_fma_f32 v[104:105], v[104:105], v[122:123], v[118:119] op_sel_hi:[1,0,1]
	v_add_u32_e32 v96, s11, v189
	global_store_dwordx4 v[116:117], v[104:107], off offset:16
	v_ashrrev_i32_e32 v97, 31, v96
	v_lshlrev_b64 v[96:97], 12, v[96:97]
	v_lshlrev_b32_e32 v104, 16, v210
	v_and_b32_e32 v105, 0xffff0000, v210
	v_lshlrev_b32_e32 v106, 16, v211
	v_and_b32_e32 v107, 0xffff0000, v211
	v_pk_fma_f32 v[102:103], v[102:103], v[122:123], v[106:107] op_sel_hi:[1,0,1]
	v_pk_fma_f32 v[100:101], v[100:101], v[122:123], v[104:105] op_sel_hi:[1,0,1]
	global_store_dwordx4 v[116:117], v[100:103], off offset:512
	v_lshl_add_u64 v[96:97], s[26:27], 0, v[96:97]
	v_lshl_add_u64 v[96:97], v[96:97], 0, v[176:177]
	v_lshlrev_b32_e32 v100, 16, v214
	v_and_b32_e32 v101, 0xffff0000, v214
	v_lshlrev_b32_e32 v102, 16, v215
	v_and_b32_e32 v103, 0xffff0000, v215
	s_waitcnt lgkmcnt(0)
	v_pk_fma_f32 v[94:95], v[94:95], v[98:99], v[102:103] op_sel_hi:[1,0,1]
	v_pk_fma_f32 v[92:93], v[92:93], v[98:99], v[100:101] op_sel_hi:[1,0,1]
	global_store_dwordx4 v[96:97], v[92:95], off
	v_lshlrev_b32_e32 v104, 16, v216
	v_and_b32_e32 v105, 0xffff0000, v216
	v_lshlrev_b32_e32 v92, 16, v220
	v_and_b32_e32 v93, 0xffff0000, v220
	v_lshlrev_b32_e32 v94, 16, v221
	v_and_b32_e32 v95, 0xffff0000, v221
	v_lshlrev_b32_e32 v106, 16, v217
	v_and_b32_e32 v107, 0xffff0000, v217
	v_pk_fma_f32 v[82:83], v[82:83], v[98:99], v[94:95] op_sel_hi:[1,0,1]
	v_pk_fma_f32 v[80:81], v[80:81], v[98:99], v[92:93] op_sel_hi:[1,0,1]
	v_pk_fma_f32 v[90:91], v[90:91], v[98:99], v[106:107] op_sel_hi:[1,0,1]
	v_pk_fma_f32 v[88:89], v[88:89], v[98:99], v[104:105] op_sel_hi:[1,0,1]
	global_store_dwordx4 v[96:97], v[80:83], off offset:528
	global_store_dwordx4 v[96:97], v[88:91], off offset:16
	s_nop 0
	v_add_u32_e32 v80, s11, v190
	v_lshlrev_b32_e32 v88, 16, v218
	v_and_b32_e32 v89, 0xffff0000, v218
	v_lshlrev_b32_e32 v90, 16, v219
	v_and_b32_e32 v91, 0xffff0000, v219
	v_ashrrev_i32_e32 v81, 31, v80
	v_pk_fma_f32 v[86:87], v[86:87], v[98:99], v[90:91] op_sel_hi:[1,0,1]
	v_pk_fma_f32 v[84:85], v[84:85], v[98:99], v[88:89] op_sel_hi:[1,0,1]
	v_lshlrev_b64 v[80:81], 12, v[80:81]
	global_store_dwordx4 v[96:97], v[84:87], off offset:512
	v_lshl_add_u64 v[80:81], s[26:27], 0, v[80:81]
	v_lshlrev_b32_e32 v82, 16, v222
	v_and_b32_e32 v83, 0xffff0000, v222
	v_lshlrev_b32_e32 v84, 16, v223
	v_and_b32_e32 v85, 0xffff0000, v223
	v_mov_b32_e32 v90, v99
	v_lshl_add_u64 v[80:81], v[80:81], 0, v[176:177]
	v_pk_fma_f32 v[78:79], v[78:79], v[90:91], v[84:85] op_sel_hi:[1,0,1]
	v_pk_fma_f32 v[76:77], v[76:77], v[90:91], v[82:83] op_sel_hi:[1,0,1]
	global_store_dwordx4 v[80:81], v[76:79], off
	v_lshlrev_b32_e32 v86, 16, v224
	v_and_b32_e32 v87, 0xffff0000, v224
	v_lshlrev_b32_e32 v76, 16, v228
	v_and_b32_e32 v77, 0xffff0000, v228
	v_lshlrev_b32_e32 v78, 16, v229
	v_and_b32_e32 v79, 0xffff0000, v229
	v_pk_fma_f32 v[66:67], v[66:67], v[90:91], v[78:79] op_sel_hi:[1,0,1]
	v_pk_fma_f32 v[64:65], v[64:65], v[90:91], v[76:77] op_sel_hi:[1,0,1]
	v_lshlrev_b32_e32 v88, 16, v225
	v_and_b32_e32 v89, 0xffff0000, v225
	global_store_dwordx4 v[80:81], v[64:67], off offset:528
	ds_read2_b32 v[66:67], v196 offset0:128 offset1:144
	v_pk_fma_f32 v[74:75], v[74:75], v[90:91], v[88:89] op_sel_hi:[1,0,1]
	v_pk_fma_f32 v[72:73], v[72:73], v[90:91], v[86:87] op_sel_hi:[1,0,1]
	global_store_dwordx4 v[80:81], v[72:75], off offset:16
	v_lshlrev_b64 v[64:65], 12, v[184:185]
	v_lshl_add_u64 v[64:65], s[26:27], 0, v[64:65]
	v_lshlrev_b32_e32 v72, 16, v226
	v_and_b32_e32 v73, 0xffff0000, v226
	v_lshlrev_b32_e32 v74, 16, v227
	v_and_b32_e32 v75, 0xffff0000, v227
	v_pk_fma_f32 v[70:71], v[70:71], v[90:91], v[74:75] op_sel_hi:[1,0,1]
	v_pk_fma_f32 v[68:69], v[68:69], v[90:91], v[72:73] op_sel_hi:[1,0,1]
	global_store_dwordx4 v[80:81], v[68:71], off offset:512
	v_lshl_add_u64 v[64:65], v[64:65], 0, v[176:177]
	v_lshlrev_b32_e32 v72, 16, v158
	v_lshlrev_b32_e32 v68, 16, v156
	v_and_b32_e32 v69, 0xffff0000, v156
	v_lshlrev_b32_e32 v70, 16, v157
	v_and_b32_e32 v71, 0xffff0000, v157
	v_and_b32_e32 v73, 0xffff0000, v158
	v_lshlrev_b32_e32 v74, 16, v159
	v_and_b32_e32 v75, 0xffff0000, v159
	s_waitcnt lgkmcnt(0)
; __device__ __forceinline__ float bf_lo(unsigned w) { return __uint_as_float(w << 16); }
; __device__ __forceinline__ float bf_hi(unsigned w) { return __uint_as_float(w & 0xffff0000u); }
; #define PG8_WAIT_V(n) asm volatile("s_waitcnt vmcnt(" #n ")" ::: "memory")
; #define PG8_BAR __builtin_amdgcn_s_barrier()
; template <class Epi, class Ptrs>
; __device__ __forceinline__ void gemm_phase(LAS unsigned char* lds, const int K, const StaticOrder& S, const Ptrs& P, const Epi& E) {
;     ...
;     PG8_WAIT_V(0);
;     if (wr == 0) PG8_BAR;
;     PG8_BAR;
;     __device__ __forceinline__ void operator()(const f32x4 (&acc)[2][2][4][2], const Unit& u, int ui, int wr, int wc, int fr, int fq) const {
;     ...
;             for (int m = 0; m < 4; ++m) { const int rl = rl0 + ai * 128 + m * 16; float* rowp = out + (size_t)(u.pm * 256 + rl) * DM + col0;
;                 const float r2 = tab[ui * 256 + rl];
; #pragma unroll
;                 for (int bj = 0; bj < 2; ++bj) { const u32x4 x = xv[ai][m][bj];
;                     const f32x4 x0 = {bf_lo(x.x), bf_hi(x.x), bf_lo(x.y), bf_hi(x.y)}, x1 = {bf_lo(x.z), bf_hi(x.z), bf_lo(x.w), bf_hi(x.w)};
;                     *(f32x4*)(rowp + bj * 128) = acc[ai][bj][m][0] * r2 + x0; *(f32x4*)(rowp + bj * 128 + 4) = acc[ai][bj][m][1] * r2 + x1; } }
	v_pk_fma_f32 v[62:63], v[62:63], v[66:67], v[70:71] op_sel_hi:[1,0,1]
	v_pk_fma_f32 v[60:61], v[60:61], v[66:67], v[68:69] op_sel_hi:[1,0,1]
	global_store_dwordx4 v[64:65], v[60:63], off
	v_pk_fma_f32 v[58:59], v[58:59], v[66:67], v[74:75] op_sel_hi:[1,0,1]
	v_pk_fma_f32 v[56:57], v[56:57], v[66:67], v[72:73] op_sel_hi:[1,0,1]
	v_lshlrev_b32_e32 v60, 16, v154
	v_and_b32_e32 v61, 0xffff0000, v154
	v_lshlrev_b32_e32 v62, 16, v155
	v_and_b32_e32 v63, 0xffff0000, v155
	global_store_dwordx4 v[64:65], v[56:59], off offset:16
	v_pk_fma_f32 v[46:47], v[46:47], v[66:67], v[62:63] op_sel_hi:[1,0,1]
	v_pk_fma_f32 v[44:45], v[44:45], v[66:67], v[60:61] op_sel_hi:[1,0,1]
	v_lshlrev_b32_e32 v56, 16, v152
	v_and_b32_e32 v57, 0xffff0000, v152
	v_lshlrev_b32_e32 v58, 16, v153
	v_and_b32_e32 v59, 0xffff0000, v153
	v_pk_fma_f32 v[54:55], v[54:55], v[66:67], v[58:59] op_sel_hi:[1,0,1]
	v_pk_fma_f32 v[52:53], v[52:53], v[66:67], v[56:57] op_sel_hi:[1,0,1]
	global_store_dwordx4 v[64:65], v[44:47], off offset:528
	global_store_dwordx4 v[64:65], v[52:55], off offset:512
	v_lshlrev_b32_e32 v56, 16, v151
	v_lshlrev_b64 v[44:45], 12, v[182:183]
	v_lshl_add_u64 v[44:45], s[26:27], 0, v[44:45]
	v_lshlrev_b32_e32 v54, 16, v150
	v_and_b32_e32 v55, 0xffff0000, v150
	v_and_b32_e32 v57, 0xffff0000, v151
	v_mov_b32_e32 v58, v67
	v_lshl_add_u64 v[52:53], v[44:45], 0, v[176:177]
	v_pk_fma_f32 v[42:43], v[42:43], v[58:59], v[56:57] op_sel_hi:[1,0,1]
	v_pk_fma_f32 v[40:41], v[40:41], v[58:59], v[54:55] op_sel_hi:[1,0,1]
	v_lshlrev_b32_e32 v44, 16, v148
	v_and_b32_e32 v45, 0xffff0000, v148
	v_lshlrev_b32_e32 v46, 16, v149
	v_and_b32_e32 v47, 0xffff0000, v149
	global_store_dwordx4 v[52:53], v[40:43], off offset:16
	v_pk_fma_f32 v[46:47], v[50:51], v[58:59], v[46:47] op_sel_hi:[1,0,1]
	v_pk_fma_f32 v[44:45], v[48:49], v[58:59], v[44:45] op_sel_hi:[1,0,1]
	v_lshlrev_b32_e32 v40, 16, v144
	v_and_b32_e32 v41, 0xffff0000, v144
	v_lshlrev_b32_e32 v42, 16, v145
	v_and_b32_e32 v43, 0xffff0000, v145
	v_pk_fma_f32 v[38:39], v[38:39], v[58:59], v[42:43] op_sel_hi:[1,0,1]
	v_pk_fma_f32 v[36:37], v[36:37], v[58:59], v[40:41] op_sel_hi:[1,0,1]
	global_store_dwordx4 v[52:53], v[44:47], off
	global_store_dwordx4 v[52:53], v[36:39], off offset:512
	ds_read2_b32 v[38:39], v196 offset0:160 offset1:176
	v_lshlrev_b32_e32 v44, 16, v146
	v_and_b32_e32 v45, 0xffff0000, v146
	v_lshlrev_b32_e32 v46, 16, v147
	v_and_b32_e32 v47, 0xffff0000, v147
	v_pk_fma_f32 v[30:31], v[30:31], v[58:59], v[46:47] op_sel_hi:[1,0,1]
	v_pk_fma_f32 v[28:29], v[28:29], v[58:59], v[44:45] op_sel_hi:[1,0,1]
	global_store_dwordx4 v[52:53], v[28:31], off offset:528
	v_lshlrev_b32_e32 v40, 16, v142
	v_and_b32_e32 v41, 0xffff0000, v142
	v_lshlrev_b64 v[28:29], 12, v[180:181]
	v_lshl_add_u64 v[28:29], s[26:27], 0, v[28:29]
	v_lshl_add_u64 v[36:37], v[28:29], 0, v[176:177]
	v_lshlrev_b32_e32 v28, 16, v140
	v_and_b32_e32 v29, 0xffff0000, v140
	v_lshlrev_b32_e32 v30, 16, v141
	v_and_b32_e32 v31, 0xffff0000, v141
	s_waitcnt lgkmcnt(0)
	v_pk_fma_f32 v[30:31], v[34:35], v[38:39], v[30:31] op_sel_hi:[1,0,1]
	v_pk_fma_f32 v[28:29], v[32:33], v[38:39], v[28:29] op_sel_hi:[1,0,1]
	v_lshlrev_b32_e32 v42, 16, v143
	v_and_b32_e32 v43, 0xffff0000, v143
	global_store_dwordx4 v[36:37], v[28:31], off
	v_pk_fma_f32 v[26:27], v[26:27], v[38:39], v[42:43] op_sel_hi:[1,0,1]
	v_pk_fma_f32 v[24:25], v[24:25], v[38:39], v[40:41] op_sel_hi:[1,0,1]
	v_lshlrev_b32_e32 v28, 16, v138
	v_and_b32_e32 v29, 0xffff0000, v138
	v_lshlrev_b32_e32 v30, 16, v139
	v_and_b32_e32 v31, 0xffff0000, v139
	v_pk_fma_f32 v[14:15], v[14:15], v[38:39], v[30:31] op_sel_hi:[1,0,1]
	v_pk_fma_f32 v[12:13], v[12:13], v[38:39], v[28:29] op_sel_hi:[1,0,1]
	global_store_dwordx4 v[36:37], v[24:27], off offset:16
	global_store_dwordx4 v[36:37], v[12:15], off offset:528
	s_nop 0
	v_lshlrev_b32_e32 v24, 16, v136
	v_and_b32_e32 v25, 0xffff0000, v136
	v_lshlrev_b32_e32 v26, 16, v137
	v_and_b32_e32 v27, 0xffff0000, v137
	v_lshlrev_b64 v[12:13], 12, v[178:179]
	v_pk_fma_f32 v[22:23], v[22:23], v[38:39], v[26:27] op_sel_hi:[1,0,1]
	v_pk_fma_f32 v[20:21], v[20:21], v[38:39], v[24:25] op_sel_hi:[1,0,1]
	v_lshl_add_u64 v[12:13], s[26:27], 0, v[12:13]
	global_store_dwordx4 v[36:37], v[20:23], off offset:512
	v_lshlrev_b32_e32 v14, 16, v133
	v_and_b32_e32 v15, 0xffff0000, v133
	v_lshl_add_u64 v[20:21], v[12:13], 0, v[176:177]
	v_lshlrev_b32_e32 v12, 16, v132
	v_and_b32_e32 v13, 0xffff0000, v132
	v_lshlrev_b32_e32 v22, 16, v134
	v_and_b32_e32 v23, 0xffff0000, v134
	v_lshlrev_b32_e32 v24, 16, v135
	v_and_b32_e32 v25, 0xffff0000, v135
	v_mov_b32_e32 v26, v39
	v_pk_fma_f32 v[14:15], v[18:19], v[26:27], v[14:15] op_sel_hi:[1,0,1]
	v_pk_fma_f32 v[12:13], v[16:17], v[26:27], v[12:13] op_sel_hi:[1,0,1]
	v_pk_fma_f32 v[10:11], v[10:11], v[26:27], v[24:25] op_sel_hi:[1,0,1]
	v_pk_fma_f32 v[8:9], v[8:9], v[26:27], v[22:23] op_sel_hi:[1,0,1]
	global_store_dwordx4 v[20:21], v[12:15], off
	global_store_dwordx4 v[20:21], v[8:11], off offset:16
	s_nop 0
	v_lshlrev_b32_e32 v12, 16, v130
	v_lshlrev_b32_e32 v8, 16, v128
	v_and_b32_e32 v9, 0xffff0000, v128
	v_lshlrev_b32_e32 v10, 16, v129
	v_and_b32_e32 v11, 0xffff0000, v129
	v_and_b32_e32 v13, 0xffff0000, v130
	v_lshlrev_b32_e32 v14, 16, v131
	v_and_b32_e32 v15, 0xffff0000, v131
	v_pk_fma_f32 v[6:7], v[6:7], v[26:27], v[10:11] op_sel_hi:[1,0,1]
	v_pk_fma_f32 v[4:5], v[4:5], v[26:27], v[8:9] op_sel_hi:[1,0,1]
	v_pk_fma_f32 v[2:3], v[2:3], v[26:27], v[14:15] op_sel_hi:[1,0,1]
	v_pk_fma_f32 v[0:1], v[0:1], v[26:27], v[12:13] op_sel_hi:[1,0,1]
	global_store_dwordx4 v[20:21], v[4:7], off offset:512
	global_store_dwordx4 v[20:21], v[0:3], off offset:528
	s_cbranch_vccz .LBB0_517
	s_waitcnt vmcnt(0)
	s_setprio 0
	s_cmpk_gt_u32 s33, 0xff
	s_cbranch_scc1 .LBB0_526
	s_barrier
